# K-loop: setprio raised before pre-MFMA barrier, redundant lgkmcnt wait after barrier removed, setprio 0 moved after post-MFMA barrier
# speedup vs baseline: 1.0027x; 1.0027x over previous
; #define PG8_STAGE(bufoff, gbase, voff) do { _Pragma("unroll") for (int _i = 0; _i < 2; ++_i) \
;         __builtin_amdgcn_global_load_lds((const unsigned*)((const char*)(gbase) + (voff)[_i]), (PG8_LAS unsigned*)(lds + (bufoff) + ldsw + _i * 8192), 16, 0, 0); } while (0)
; #define PG8_LDA(dst, b, h) do { _Pragma("unroll") for (int m = 0; m < 4; ++m) _Pragma("unroll") for (int k = 0; k < 2; ++k) dst[m][k] = *(const PG8_LAS bf16x8*)(lds + PG8_SA(b, h) + aoff + m * 2048 + k * 1024); } while (0)
; #define PG8_LDB(dst, b, h) do { _Pragma("unroll") for (int n = 0; n < 2; ++n) _Pragma("unroll") for (int k = 0; k < 2; ++k) dst[n][k] = *(const PG8_LAS bf16x8*)(lds + PG8_SB(b, h) + boff + n * 2048 + k * 1024); } while (0)
; #define PG8_MMA(ai, bj, At, Bt) do { __builtin_amdgcn_s_setprio(1); _Pragma("unroll") for (int m = 0; m < 4; ++m) _Pragma("unroll") for (int n = 0; n < 2; ++n) _Pragma("unroll") for (int k = 0; k < 2; ++k) \
;         acc[ai][bj][m][n] = __builtin_amdgcn_mfma_f32_16x16x32_bf16(Bt[n][k], At[m][k], acc[ai][bj][m][n], 0, 0, 0); __builtin_amdgcn_s_setprio(0); } while (0)
; #define PG8_BAR __builtin_amdgcn_s_barrier()
; template <class Epi, class Sched, bool ALIGN_EPI = false, bool SP2 = false>
; __device__ __forceinline__ void gemm_phase(PG8_LAS unsigned char* lds, const Gemm g, const Sched& S, const Epi& E) {
;     ...
;         const bool has_next = S.next(ui + 1, nxt);
;         const char* nA = has_next ? (const char*)g.A + (size_t)nxt.pm * tstep : cA; const char* nB = has_next ? (const char*)g.Bt + (size_t)nxt.pn * tstep : cB;
;         for (int t = 0; t < nt; t += 2) {
;             const bool last = (t == nt - 2);
;             const char* a1 = cA + (size_t)(t + 1) * kstep;
;             const char* a2 = last ? nA : cA + (size_t)(t + 2) * kstep; const char* b2 = last ? nB : cB + (size_t)(t + 2) * kstep;
;             const char* a3 = a2 + kstep; const char* b3 = b2 + kstep;
;             if (last && has_next) S.a_ready(nxt);
;             if constexpr (SP2) {
;             PG8_LDB(B0, 0, 0); PG8_LDB(B1, 0, 1); PG8_SCHED; PG8_LDA(At, 0, 0); PG8_STAGE(PG8_SA(1, 1), a1 + hstep, voffA);
;             PG8_WAIT_V(8); PG8_WAIT_L(0); PG8_BAR; PG8_MMA(0, 0, At, B0); PG8_MMA(0, 1, At, B1); PG8_BAR; PG8_SCHED;
;             PG8_LDA(At, 0, 1); PG8_STAGE(PG8_SB(0, 0), b2, voffB); PG8_STAGE(PG8_SB(0, 1), b2 + hstep, voffB); PG8_STAGE(PG8_SA(0, 0), a2, voffA);
.LBB0_197:
	s_ashr_i32 s39, s38, 31
	s_lshl_b64 s[22:23], s[38:39], 19
	s_add_u32 s40, s13, s22
	s_addc_u32 s41, s36, s23
	s_and_b64 s[22:23], s[4:5], exec
	s_cselect_b32 s22, s41, s7
	s_cselect_b32 s23, s40, s6
	s_ashr_i32 s19, s18, 31
	s_lshl_b64 s[42:43], s[18:19], 19
	s_add_u32 s42, s37, s42
	s_addc_u32 s43, s46, s43
	s_and_b64 s[50:51], s[4:5], exec
	s_cselect_b32 s19, s43, s45
	s_cselect_b32 s39, s42, s44
	s_add_u32 s6, s6, 0x40080
	s_addc_u32 s7, s7, 0
	s_add_u32 s60, s44, 0x100
	s_addc_u32 s61, s45, 0
	s_mov_b32 s62, -2
	s_add_u32 s44, s6, 0xfffc0080
	s_addc_u32 s45, s7, -1
	s_add_i32 s63, 0, 0x10000
	s_cmp_eq_u32 s62, 12
	s_cselect_b32 s51, s22, s45
	s_cselect_b32 s50, s23, s44
	s_cselect_b32 s45, s19, s61
	s_cselect_b32 s44, s39, s60
	s_add_i32 s73, 0, 0x14000
	v_add_u32_e32 v140, s63, v191
	v_add_u32_e32 v168, s73, v191
	ds_read_b128 v[128:131], v140
	ds_read_b128 v[132:135], v140 offset:1024
	ds_read_b128 v[136:139], v140 offset:2048
	ds_read_b128 v[140:143], v140 offset:3072
	ds_read_b128 v[144:147], v168
	ds_read_b128 v[148:151], v168 offset:1024
	ds_read_b128 v[164:167], v168 offset:2048
	ds_read_b128 v[168:171], v168 offset:3072
	v_lshl_add_u64 v[202:203], s[6:7], 0, v[160:161]
	s_add_i32 m0, s52, 0xc000
	ds_read_b128 v[172:175], v193
	ds_read_b128 v[176:179], v193 offset:1024
	ds_read_b128 v[186:189], v193 offset:2048
	ds_read_b128 v[194:197], v193 offset:3072
	ds_read_b128 v[198:201], v193 offset:4096
	ds_read_b128 v[216:219], v193 offset:5120
	ds_read_b128 v[224:227], v193 offset:6144
	ds_read_b128 v[230:233], v193 offset:7168
	global_load_lds_dwordx4 v[202:203], off
	v_lshl_add_u64 v[202:203], s[6:7], 0, v[162:163]
	s_add_i32 m0, s52, 0xe000
	s_nop 0
	global_load_lds_dwordx4 v[202:203], off
	s_waitcnt vmcnt(8)
	s_waitcnt lgkmcnt(0)
	s_setprio 1
	s_barrier
	v_mfma_f32_16x16x32_bf16 v[124:127], v[128:131], v[172:175], 0
	v_mfma_f32_16x16x32_bf16 v[112:115], v[136:139], v[172:175], 0
	v_mfma_f32_16x16x32_bf16 v[108:111], v[128:131], v[186:189], 0
	v_mfma_f32_16x16x32_bf16 v[96:99], v[136:139], v[186:189], 0
	v_mfma_f32_16x16x32_bf16 v[92:95], v[128:131], v[198:201], 0
	v_mfma_f32_16x16x32_bf16 v[80:83], v[136:139], v[198:201], 0
	v_mfma_f32_16x16x32_bf16 v[76:79], v[128:131], v[224:227], 0
	v_mfma_f32_16x16x32_bf16 v[64:67], v[136:139], v[224:227], 0
	v_mfma_f32_16x16x32_bf16 v[124:127], v[132:135], v[176:179], v[124:127]
	v_mfma_f32_16x16x32_bf16 v[112:115], v[140:143], v[176:179], v[112:115]
	v_mfma_f32_16x16x32_bf16 v[108:111], v[132:135], v[194:197], v[108:111]
	v_mfma_f32_16x16x32_bf16 v[96:99], v[140:143], v[194:197], v[96:99]
	v_mfma_f32_16x16x32_bf16 v[92:95], v[132:135], v[216:219], v[92:95]
	v_mfma_f32_16x16x32_bf16 v[80:83], v[140:143], v[216:219], v[80:83]
	v_mfma_f32_16x16x32_bf16 v[76:79], v[132:135], v[230:233], v[76:79]
	v_mfma_f32_16x16x32_bf16 v[64:67], v[140:143], v[230:233], v[64:67]
	s_setprio 0
	s_setprio 1
	v_mfma_f32_16x16x32_bf16 v[120:123], v[144:147], v[172:175], 0
	v_mfma_f32_16x16x32_bf16 v[116:119], v[164:167], v[172:175], 0
	v_mfma_f32_16x16x32_bf16 v[104:107], v[144:147], v[186:189], 0
	v_mfma_f32_16x16x32_bf16 v[100:103], v[164:167], v[186:189], 0
	v_mfma_f32_16x16x32_bf16 v[88:91], v[144:147], v[198:201], 0
	v_mfma_f32_16x16x32_bf16 v[84:87], v[164:167], v[198:201], 0
	v_mfma_f32_16x16x32_bf16 v[72:75], v[144:147], v[224:227], 0
	v_mfma_f32_16x16x32_bf16 v[68:71], v[164:167], v[224:227], 0
	v_mfma_f32_16x16x32_bf16 v[120:123], v[148:151], v[176:179], v[120:123]
	v_mfma_f32_16x16x32_bf16 v[116:119], v[168:171], v[176:179], v[116:119]
	v_mfma_f32_16x16x32_bf16 v[104:107], v[148:151], v[194:197], v[104:107]
	v_mfma_f32_16x16x32_bf16 v[100:103], v[168:171], v[194:197], v[100:103]
	v_mfma_f32_16x16x32_bf16 v[88:91], v[148:151], v[216:219], v[88:91]
	v_mfma_f32_16x16x32_bf16 v[84:87], v[168:171], v[216:219], v[84:87]
	v_mfma_f32_16x16x32_bf16 v[72:75], v[148:151], v[230:233], v[72:75]
	v_mfma_f32_16x16x32_bf16 v[68:71], v[168:171], v[230:233], v[68:71]
	s_barrier
	s_setprio 0
	s_add_i32 s63, s63, s47
	v_lshl_add_u64 v[202:203], s[44:45], 0, v[180:181]
	s_mov_b32 m0, s63
	ds_read_b128 v[172:175], v193 offset:16384
	ds_read_b128 v[176:179], v193 offset:17408
	ds_read_b128 v[186:189], v193 offset:18432
	ds_read_b128 v[194:197], v193 offset:19456
	ds_read_b128 v[198:201], v193 offset:20480
	ds_read_b128 v[216:219], v193 offset:21504
	ds_read_b128 v[224:227], v193 offset:22528
	ds_read_b128 v[230:233], v193 offset:23552
	global_load_lds_dwordx4 v[202:203], off
	s_add_i32 m0, s63, 0x2000
	s_add_u32 s76, s44, 0x40000
	v_lshl_add_u64 v[208:209], s[44:45], 0, v[152:153]
	s_addc_u32 s77, s45, 0
	s_add_i32 s63, s73, s47
	global_load_lds_dwordx4 v[208:209], off
	v_lshl_add_u64 v[220:221], s[76:77], 0, v[180:181]
	s_mov_b32 m0, s63
	v_lshl_add_u64 v[234:235], s[50:51], 0, v[154:155]
	global_load_lds_dwordx4 v[220:221], off
	v_lshl_add_u64 v[220:221], s[76:77], 0, v[152:153]
	s_add_i32 m0, s63, 0x2000
	s_nop 0
	global_load_lds_dwordx4 v[220:221], off
	v_lshl_add_u64 v[220:221], s[50:51], 0, v[156:157]
	s_mov_b32 m0, s52
	s_nop 0
	global_load_lds_dwordx4 v[220:221], off
	s_mov_b32 m0, s53
	s_nop 0
	global_load_lds_dwordx4 v[234:235], off
	s_waitcnt vmcnt(8)
	s_waitcnt lgkmcnt(0)
	s_setprio 1
	s_barrier
; #define PG8_STAGE(bufoff, gbase, voff) do { _Pragma("unroll") for (int _i = 0; _i < 2; ++_i) \
;         __builtin_amdgcn_global_load_lds((const unsigned*)((const char*)(gbase) + (voff)[_i]), (PG8_LAS unsigned*)(lds + (bufoff) + ldsw + _i * 8192), 16, 0, 0); } while (0)
; #define PG8_LDA(dst, b, h) do { _Pragma("unroll") for (int m = 0; m < 4; ++m) _Pragma("unroll") for (int k = 0; k < 2; ++k) dst[m][k] = *(const PG8_LAS bf16x8*)(lds + PG8_SA(b, h) + aoff + m * 2048 + k * 1024); } while (0)
; #define PG8_LDB(dst, b, h) do { _Pragma("unroll") for (int n = 0; n < 2; ++n) _Pragma("unroll") for (int k = 0; k < 2; ++k) dst[n][k] = *(const PG8_LAS bf16x8*)(lds + PG8_SB(b, h) + boff + n * 2048 + k * 1024); } while (0)
; #define PG8_MMA(ai, bj, At, Bt) do { __builtin_amdgcn_s_setprio(1); _Pragma("unroll") for (int m = 0; m < 4; ++m) _Pragma("unroll") for (int n = 0; n < 2; ++n) _Pragma("unroll") for (int k = 0; k < 2; ++k) \
;         acc[ai][bj][m][n] = __builtin_amdgcn_mfma_f32_16x16x32_bf16(Bt[n][k], At[m][k], acc[ai][bj][m][n], 0, 0, 0); __builtin_amdgcn_s_setprio(0); } while (0)
; #define PG8_WAIT_V(n) asm volatile("s_waitcnt vmcnt(" #n ")" ::: "memory")
; #define PG8_WAIT_L(n) asm volatile("s_waitcnt lgkmcnt(" #n ")" ::: "memory")
; #define PG8_BAR __builtin_amdgcn_s_barrier()
; #define PG8_SCHED __builtin_amdgcn_sched_barrier(0)
; template <class Epi, class Sched, bool ALIGN_EPI = false, bool SP2 = false>
; __device__ __forceinline__ void gemm_phase(PG8_LAS unsigned char* lds, const Gemm g, const Sched& S, const Epi& E) {
;     ...
;             PG8_WAIT_V(8); PG8_WAIT_L(0); PG8_BAR; PG8_MMA(1, 0, At, B0); PG8_MMA(1, 1, At, B1); PG8_BAR; PG8_SCHED;
;             PG8_LDB(B0, 1, 0); PG8_LDB(B1, 1, 1); PG8_SCHED; PG8_LDA(At, 1, 0); PG8_STAGE(PG8_SA(0, 1), a2 + hstep, voffA);
;             PG8_WAIT_V(8); PG8_WAIT_L(0); PG8_BAR; PG8_MMA(0, 0, At, B0); PG8_MMA(0, 1, At, B1); PG8_BAR; PG8_SCHED;
	v_mfma_f32_16x16x32_bf16 v[60:63], v[128:131], v[172:175], 0
	v_mfma_f32_16x16x32_bf16 v[48:51], v[136:139], v[172:175], 0
	v_mfma_f32_16x16x32_bf16 v[44:47], v[128:131], v[186:189], 0
	v_mfma_f32_16x16x32_bf16 v[32:35], v[136:139], v[186:189], 0
	v_mfma_f32_16x16x32_bf16 v[28:31], v[128:131], v[198:201], 0
	v_mfma_f32_16x16x32_bf16 v[16:19], v[136:139], v[198:201], 0
	v_mfma_f32_16x16x32_bf16 v[12:15], v[128:131], v[224:227], 0
	v_mfma_f32_16x16x32_bf16 v[4:7], v[136:139], v[224:227], 0
	v_mfma_f32_16x16x32_bf16 v[60:63], v[132:135], v[176:179], v[60:63]
	v_mfma_f32_16x16x32_bf16 v[48:51], v[140:143], v[176:179], v[48:51]
	v_mfma_f32_16x16x32_bf16 v[44:47], v[132:135], v[194:197], v[44:47]
	v_mfma_f32_16x16x32_bf16 v[32:35], v[140:143], v[194:197], v[32:35]
	v_mfma_f32_16x16x32_bf16 v[28:31], v[132:135], v[216:219], v[28:31]
	v_mfma_f32_16x16x32_bf16 v[16:19], v[140:143], v[216:219], v[16:19]
	v_mfma_f32_16x16x32_bf16 v[12:15], v[132:135], v[230:233], v[12:15]
	v_mfma_f32_16x16x32_bf16 v[4:7], v[140:143], v[230:233], v[4:7]
	s_setprio 0
	s_setprio 1
	v_mfma_f32_16x16x32_bf16 v[56:59], v[144:147], v[172:175], 0
	v_mfma_f32_16x16x32_bf16 v[52:55], v[164:167], v[172:175], 0
	v_mfma_f32_16x16x32_bf16 v[40:43], v[144:147], v[186:189], 0
	v_mfma_f32_16x16x32_bf16 v[36:39], v[164:167], v[186:189], 0
	v_mfma_f32_16x16x32_bf16 v[24:27], v[144:147], v[198:201], 0
	v_mfma_f32_16x16x32_bf16 v[20:23], v[164:167], v[198:201], 0
	v_mfma_f32_16x16x32_bf16 v[8:11], v[144:147], v[224:227], 0
	v_mfma_f32_16x16x32_bf16 v[0:3], v[164:167], v[224:227], 0
	v_mfma_f32_16x16x32_bf16 v[56:59], v[148:151], v[176:179], v[56:59]
	v_mfma_f32_16x16x32_bf16 v[52:55], v[168:171], v[176:179], v[52:55]
	v_mfma_f32_16x16x32_bf16 v[40:43], v[148:151], v[194:197], v[40:43]
	v_mfma_f32_16x16x32_bf16 v[36:39], v[168:171], v[194:197], v[36:39]
	v_mfma_f32_16x16x32_bf16 v[24:27], v[148:151], v[216:219], v[24:27]
	v_mfma_f32_16x16x32_bf16 v[20:23], v[168:171], v[216:219], v[20:23]
	v_mfma_f32_16x16x32_bf16 v[8:11], v[148:151], v[230:233], v[8:11]
	v_mfma_f32_16x16x32_bf16 v[0:3], v[168:171], v[230:233], v[0:3]
	s_barrier
	s_setprio 0
	s_add_i32 s63, 0, 0x18000
	s_add_i32 s73, 0, 0x1c000
	v_add_u32_e32 v140, s63, v191
	v_add_u32_e32 v168, s73, v191
	ds_read_b128 v[128:131], v140
	ds_read_b128 v[132:135], v140 offset:1024
	ds_read_b128 v[136:139], v140 offset:2048
	ds_read_b128 v[140:143], v140 offset:3072
	ds_read_b128 v[144:147], v168
	ds_read_b128 v[148:151], v168 offset:1024
	ds_read_b128 v[164:167], v168 offset:2048
	ds_read_b128 v[168:171], v168 offset:3072
	s_add_u32 s50, s50, 0x40000
	s_addc_u32 s51, s51, 0
	s_mov_b32 m0, s54
	v_lshl_add_u64 v[236:237], s[50:51], 0, v[156:157]
	ds_read_b128 v[172:175], v193 offset:32768
	ds_read_b128 v[176:179], v193 offset:33792
	ds_read_b128 v[186:189], v193 offset:34816
	ds_read_b128 v[194:197], v193 offset:35840
	ds_read_b128 v[198:201], v193 offset:36864
	ds_read_b128 v[216:219], v193 offset:37888
	ds_read_b128 v[224:227], v193 offset:38912
	ds_read_b128 v[230:233], v193 offset:39936
	global_load_lds_dwordx4 v[236:237], off
	v_lshl_add_u64 v[236:237], s[50:51], 0, v[154:155]
	s_mov_b32 m0, s55
	s_nop 0
	global_load_lds_dwordx4 v[236:237], off
	s_waitcnt vmcnt(8)
	s_waitcnt lgkmcnt(0)
	s_setprio 1
	s_barrier
	v_mfma_f32_16x16x32_bf16 v[124:127], v[128:131], v[172:175], v[124:127]
	v_mfma_f32_16x16x32_bf16 v[112:115], v[136:139], v[172:175], v[112:115]
	v_mfma_f32_16x16x32_bf16 v[108:111], v[128:131], v[186:189], v[108:111]
	v_mfma_f32_16x16x32_bf16 v[96:99], v[136:139], v[186:189], v[96:99]
	v_mfma_f32_16x16x32_bf16 v[92:95], v[128:131], v[198:201], v[92:95]
	v_mfma_f32_16x16x32_bf16 v[80:83], v[136:139], v[198:201], v[80:83]
	v_mfma_f32_16x16x32_bf16 v[76:79], v[128:131], v[224:227], v[76:79]
	v_mfma_f32_16x16x32_bf16 v[64:67], v[136:139], v[224:227], v[64:67]
	v_mfma_f32_16x16x32_bf16 v[124:127], v[132:135], v[176:179], v[124:127]
	v_mfma_f32_16x16x32_bf16 v[112:115], v[140:143], v[176:179], v[112:115]
	v_mfma_f32_16x16x32_bf16 v[108:111], v[132:135], v[194:197], v[108:111]
	v_mfma_f32_16x16x32_bf16 v[96:99], v[140:143], v[194:197], v[96:99]
	v_mfma_f32_16x16x32_bf16 v[92:95], v[132:135], v[216:219], v[92:95]
	v_mfma_f32_16x16x32_bf16 v[80:83], v[140:143], v[216:219], v[80:83]
	v_mfma_f32_16x16x32_bf16 v[76:79], v[132:135], v[230:233], v[76:79]
	v_mfma_f32_16x16x32_bf16 v[64:67], v[140:143], v[230:233], v[64:67]
	s_setprio 0
	s_setprio 1
	v_mfma_f32_16x16x32_bf16 v[120:123], v[144:147], v[172:175], v[120:123]
	v_mfma_f32_16x16x32_bf16 v[116:119], v[164:167], v[172:175], v[116:119]
	v_mfma_f32_16x16x32_bf16 v[104:107], v[144:147], v[186:189], v[104:107]
	v_mfma_f32_16x16x32_bf16 v[100:103], v[164:167], v[186:189], v[100:103]
	v_mfma_f32_16x16x32_bf16 v[88:91], v[144:147], v[198:201], v[88:91]
	v_mfma_f32_16x16x32_bf16 v[84:87], v[164:167], v[198:201], v[84:87]
	v_mfma_f32_16x16x32_bf16 v[72:75], v[144:147], v[224:227], v[72:75]
	v_mfma_f32_16x16x32_bf16 v[68:71], v[164:167], v[224:227], v[68:71]
	v_mfma_f32_16x16x32_bf16 v[120:123], v[148:151], v[176:179], v[120:123]
	v_mfma_f32_16x16x32_bf16 v[116:119], v[168:171], v[176:179], v[116:119]
	v_mfma_f32_16x16x32_bf16 v[104:107], v[148:151], v[194:197], v[104:107]
	v_mfma_f32_16x16x32_bf16 v[100:103], v[168:171], v[194:197], v[100:103]
	v_mfma_f32_16x16x32_bf16 v[88:91], v[148:151], v[216:219], v[88:91]
	v_mfma_f32_16x16x32_bf16 v[84:87], v[168:171], v[216:219], v[84:87]
	v_mfma_f32_16x16x32_bf16 v[72:75], v[148:151], v[230:233], v[72:75]
	v_mfma_f32_16x16x32_bf16 v[68:71], v[168:171], v[230:233], v[68:71]
	s_barrier
; #define PG8_STAGE(bufoff, gbase, voff) do { _Pragma("unroll") for (int _i = 0; _i < 2; ++_i) \
;         __builtin_amdgcn_global_load_lds((const unsigned*)((const char*)(gbase) + (voff)[_i]), (PG8_LAS unsigned*)(lds + (bufoff) + ldsw + _i * 8192), 16, 0, 0); } while (0)
; #define PG8_LDA(dst, b, h) do { _Pragma("unroll") for (int m = 0; m < 4; ++m) _Pragma("unroll") for (int k = 0; k < 2; ++k) dst[m][k] = *(const PG8_LAS bf16x8*)(lds + PG8_SA(b, h) + aoff + m * 2048 + k * 1024); } while (0)
; #define PG8_LDB(dst, b, h) do { _Pragma("unroll") for (int n = 0; n < 2; ++n) _Pragma("unroll") for (int k = 0; k < 2; ++k) dst[n][k] = *(const PG8_LAS bf16x8*)(lds + PG8_SB(b, h) + boff + n * 2048 + k * 1024); } while (0)
; #define PG8_MMA(ai, bj, At, Bt) do { __builtin_amdgcn_s_setprio(1); _Pragma("unroll") for (int m = 0; m < 4; ++m) _Pragma("unroll") for (int n = 0; n < 2; ++n) _Pragma("unroll") for (int k = 0; k < 2; ++k) \
;         acc[ai][bj][m][n] = __builtin_amdgcn_mfma_f32_16x16x32_bf16(Bt[n][k], At[m][k], acc[ai][bj][m][n], 0, 0, 0); __builtin_amdgcn_s_setprio(0); } while (0)
; #define PG8_WAIT_V(n) asm volatile("s_waitcnt vmcnt(" #n ")" ::: "memory")
; #define PG8_WAIT_L(n) asm volatile("s_waitcnt lgkmcnt(" #n ")" ::: "memory")
; #define PG8_BAR __builtin_amdgcn_s_barrier()
; #define PG8_SCHED __builtin_amdgcn_sched_barrier(0)
; template <class Epi, class Sched, bool ALIGN_EPI = false, bool SP2 = false>
; __device__ __forceinline__ void gemm_phase(PG8_LAS unsigned char* lds, const Gemm g, const Sched& S, const Epi& E) {
;     ...
;         for (int t = 0; t < nt; t += 2) {
;             const bool last = (t == nt - 2);
;             const char* a1 = cA + (size_t)(t + 1) * kstep;
;             const char* a2 = last ? nA : cA + (size_t)(t + 2) * kstep; const char* b2 = last ? nB : cB + (size_t)(t + 2) * kstep;
;             const char* a3 = a2 + kstep; const char* b3 = b2 + kstep;
;             if (last && has_next) S.a_ready(nxt);
;             if constexpr (SP2) {
;             PG8_LDB(B0, 0, 0); PG8_LDB(B1, 0, 1); PG8_SCHED; PG8_LDA(At, 0, 0); PG8_STAGE(PG8_SA(1, 1), a1 + hstep, voffA);
;     ...
;             PG8_LDA(At, 1, 1); PG8_STAGE(PG8_SB(1, 0), b3, voffB); PG8_STAGE(PG8_SB(1, 1), b3 + hstep, voffB); PG8_STAGE(PG8_SA(1, 0), a3, voffA);
;             PG8_WAIT_V(8); PG8_WAIT_L(0); PG8_BAR; PG8_MMA(1, 0, At, B0); PG8_MMA(1, 1, At, B1); PG8_BAR; PG8_SCHED;
	s_setprio 0
	s_add_i32 s50, s63, s47
	v_lshl_add_u64 v[202:203], v[202:203], 0, s[70:71]
	s_mov_b32 m0, s50
	ds_read_b128 v[172:175], v193 offset:49152
	ds_read_b128 v[176:179], v193 offset:50176
	ds_read_b128 v[186:189], v193 offset:51200
	ds_read_b128 v[194:197], v193 offset:52224
	ds_read_b128 v[198:201], v193 offset:53248
	ds_read_b128 v[216:219], v193 offset:54272
	ds_read_b128 v[224:227], v193 offset:55296
	ds_read_b128 v[230:233], v193 offset:56320
	global_load_lds_dwordx4 v[202:203], off
	s_add_i32 m0, s50, 0x2000
	s_add_u32 s44, s44, 0x40080
	v_lshl_add_u64 v[202:203], v[208:209], 0, s[70:71]
	s_addc_u32 s45, s45, 0
	s_add_i32 s50, s73, s47
	global_load_lds_dwordx4 v[202:203], off
	v_lshl_add_u64 v[202:203], s[44:45], 0, v[180:181]
	s_mov_b32 m0, s50
	s_nop 0
	global_load_lds_dwordx4 v[202:203], off
	v_lshl_add_u64 v[202:203], s[44:45], 0, v[152:153]
	s_add_i32 m0, s50, 0x2000
	s_nop 0
	global_load_lds_dwordx4 v[202:203], off
	v_lshl_add_u64 v[202:203], v[220:221], 0, s[70:71]
	s_mov_b32 m0, s56
	s_nop 0
	global_load_lds_dwordx4 v[202:203], off
	v_lshl_add_u64 v[202:203], v[234:235], 0, s[70:71]
	s_mov_b32 m0, s57
	s_nop 0
	global_load_lds_dwordx4 v[202:203], off
	s_waitcnt vmcnt(8)
	s_waitcnt lgkmcnt(0)
	s_setprio 1
	s_barrier
	v_mfma_f32_16x16x32_bf16 v[60:63], v[128:131], v[172:175], v[60:63]
	v_mfma_f32_16x16x32_bf16 v[48:51], v[136:139], v[172:175], v[48:51]
	v_mfma_f32_16x16x32_bf16 v[44:47], v[128:131], v[186:189], v[44:47]
	v_mfma_f32_16x16x32_bf16 v[32:35], v[136:139], v[186:189], v[32:35]
	v_mfma_f32_16x16x32_bf16 v[28:31], v[128:131], v[198:201], v[28:31]
	v_mfma_f32_16x16x32_bf16 v[16:19], v[136:139], v[198:201], v[16:19]
	v_mfma_f32_16x16x32_bf16 v[12:15], v[128:131], v[224:227], v[12:15]
	v_mfma_f32_16x16x32_bf16 v[4:7], v[136:139], v[224:227], v[4:7]
	v_mfma_f32_16x16x32_bf16 v[60:63], v[132:135], v[176:179], v[60:63]
	v_mfma_f32_16x16x32_bf16 v[48:51], v[140:143], v[176:179], v[48:51]
	v_mfma_f32_16x16x32_bf16 v[44:47], v[132:135], v[194:197], v[44:47]
	v_mfma_f32_16x16x32_bf16 v[32:35], v[140:143], v[194:197], v[32:35]
	v_mfma_f32_16x16x32_bf16 v[28:31], v[132:135], v[216:219], v[28:31]
	v_mfma_f32_16x16x32_bf16 v[16:19], v[140:143], v[216:219], v[16:19]
	v_mfma_f32_16x16x32_bf16 v[12:15], v[132:135], v[230:233], v[12:15]
	v_mfma_f32_16x16x32_bf16 v[4:7], v[140:143], v[230:233], v[4:7]
	s_setprio 0
	s_setprio 1
	v_mfma_f32_16x16x32_bf16 v[56:59], v[144:147], v[172:175], v[56:59]
	v_mfma_f32_16x16x32_bf16 v[52:55], v[164:167], v[172:175], v[52:55]
	v_mfma_f32_16x16x32_bf16 v[40:43], v[144:147], v[186:189], v[40:43]
	v_mfma_f32_16x16x32_bf16 v[36:39], v[164:167], v[186:189], v[36:39]
	v_mfma_f32_16x16x32_bf16 v[24:27], v[144:147], v[198:201], v[24:27]
	v_mfma_f32_16x16x32_bf16 v[20:23], v[164:167], v[198:201], v[20:23]
	v_mfma_f32_16x16x32_bf16 v[8:11], v[144:147], v[224:227], v[8:11]
	v_mfma_f32_16x16x32_bf16 v[0:3], v[164:167], v[224:227], v[0:3]
	v_mfma_f32_16x16x32_bf16 v[56:59], v[148:151], v[176:179], v[56:59]
	v_mfma_f32_16x16x32_bf16 v[52:55], v[168:171], v[176:179], v[52:55]
	v_mfma_f32_16x16x32_bf16 v[40:43], v[148:151], v[194:197], v[40:43]
	v_mfma_f32_16x16x32_bf16 v[36:39], v[168:171], v[194:197], v[36:39]
	v_mfma_f32_16x16x32_bf16 v[24:27], v[148:151], v[216:219], v[24:27]
	v_mfma_f32_16x16x32_bf16 v[20:23], v[168:171], v[216:219], v[20:23]
	v_mfma_f32_16x16x32_bf16 v[8:11], v[148:151], v[230:233], v[8:11]
	v_mfma_f32_16x16x32_bf16 v[0:3], v[168:171], v[230:233], v[0:3]
	s_barrier
	s_setprio 0
	s_add_i32 s62, s62, 2
	s_add_u32 s6, s6, 0x100
	s_addc_u32 s7, s7, 0
	s_add_u32 s60, s60, 0x100
	s_addc_u32 s61, s61, 0
	s_cmp_gt_u32 s62, 13
.LBB0_198:
	s_add_u32 s44, s6, 0xfffc0080
	s_addc_u32 s45, s7, -1
	s_add_i32 s63, 0, 0x10000
	s_cmp_eq_u32 s62, 12
	s_cselect_b32 s51, s22, s45
	s_cselect_b32 s50, s23, s44
	s_cselect_b32 s45, s19, s61
	s_cselect_b32 s44, s39, s60
	s_add_i32 s73, 0, 0x14000
	v_add_u32_e32 v140, s63, v191
	v_add_u32_e32 v168, s73, v191
	ds_read_b128 v[128:131], v140
	ds_read_b128 v[132:135], v140 offset:1024
	ds_read_b128 v[136:139], v140 offset:2048
	ds_read_b128 v[140:143], v140 offset:3072
	ds_read_b128 v[144:147], v168
	ds_read_b128 v[148:151], v168 offset:1024
	ds_read_b128 v[164:167], v168 offset:2048
	ds_read_b128 v[168:171], v168 offset:3072
	v_lshl_add_u64 v[202:203], s[6:7], 0, v[160:161]
	s_add_i32 m0, s52, 0xc000
	ds_read_b128 v[172:175], v193
	ds_read_b128 v[176:179], v193 offset:1024
	ds_read_b128 v[186:189], v193 offset:2048
	ds_read_b128 v[194:197], v193 offset:3072
	ds_read_b128 v[198:201], v193 offset:4096
	ds_read_b128 v[216:219], v193 offset:5120
	ds_read_b128 v[224:227], v193 offset:6144
	ds_read_b128 v[230:233], v193 offset:7168
	global_load_lds_dwordx4 v[202:203], off
	v_lshl_add_u64 v[202:203], s[6:7], 0, v[162:163]
	s_add_i32 m0, s52, 0xe000
	s_nop 0
	global_load_lds_dwordx4 v[202:203], off
	s_waitcnt vmcnt(8)
	s_waitcnt lgkmcnt(0)
	s_setprio 1
	s_barrier
; #define PG8_STAGE(bufoff, gbase, voff) do { _Pragma("unroll") for (int _i = 0; _i < 2; ++_i) \
;         __builtin_amdgcn_global_load_lds((const unsigned*)((const char*)(gbase) + (voff)[_i]), (PG8_LAS unsigned*)(lds + (bufoff) + ldsw + _i * 8192), 16, 0, 0); } while (0)
; #define PG8_LDA(dst, b, h) do { _Pragma("unroll") for (int m = 0; m < 4; ++m) _Pragma("unroll") for (int k = 0; k < 2; ++k) dst[m][k] = *(const PG8_LAS bf16x8*)(lds + PG8_SA(b, h) + aoff + m * 2048 + k * 1024); } while (0)
; #define PG8_MMA(ai, bj, At, Bt) do { __builtin_amdgcn_s_setprio(1); _Pragma("unroll") for (int m = 0; m < 4; ++m) _Pragma("unroll") for (int n = 0; n < 2; ++n) _Pragma("unroll") for (int k = 0; k < 2; ++k) \
;         acc[ai][bj][m][n] = __builtin_amdgcn_mfma_f32_16x16x32_bf16(Bt[n][k], At[m][k], acc[ai][bj][m][n], 0, 0, 0); __builtin_amdgcn_s_setprio(0); } while (0)
; #define PG8_WAIT_V(n) asm volatile("s_waitcnt vmcnt(" #n ")" ::: "memory")
; #define PG8_WAIT_L(n) asm volatile("s_waitcnt lgkmcnt(" #n ")" ::: "memory")
; #define PG8_BAR __builtin_amdgcn_s_barrier()
; #define PG8_SCHED __builtin_amdgcn_sched_barrier(0)
; template <class Epi, class Sched, bool ALIGN_EPI = false, bool SP2 = false>
; __device__ __forceinline__ void gemm_phase(PG8_LAS unsigned char* lds, const Gemm g, const Sched& S, const Epi& E) {
;     ...
;             PG8_WAIT_V(8); PG8_WAIT_L(0); PG8_BAR; PG8_MMA(0, 0, At, B0); PG8_MMA(0, 1, At, B1); PG8_BAR; PG8_SCHED;
;             PG8_LDA(At, 0, 1); PG8_STAGE(PG8_SB(0, 0), b2, voffB); PG8_STAGE(PG8_SB(0, 1), b2 + hstep, voffB); PG8_STAGE(PG8_SA(0, 0), a2, voffA);
;             PG8_WAIT_V(8); PG8_WAIT_L(0); PG8_BAR; PG8_MMA(1, 0, At, B0); PG8_MMA(1, 1, At, B1); PG8_BAR; PG8_SCHED;
	v_mfma_f32_16x16x32_bf16 v[124:127], v[128:131], v[172:175], v[124:127]
	v_mfma_f32_16x16x32_bf16 v[112:115], v[136:139], v[172:175], v[112:115]
	v_mfma_f32_16x16x32_bf16 v[108:111], v[128:131], v[186:189], v[108:111]
	v_mfma_f32_16x16x32_bf16 v[96:99], v[136:139], v[186:189], v[96:99]
	v_mfma_f32_16x16x32_bf16 v[92:95], v[128:131], v[198:201], v[92:95]
	v_mfma_f32_16x16x32_bf16 v[80:83], v[136:139], v[198:201], v[80:83]
	v_mfma_f32_16x16x32_bf16 v[76:79], v[128:131], v[224:227], v[76:79]
	v_mfma_f32_16x16x32_bf16 v[64:67], v[136:139], v[224:227], v[64:67]
	v_mfma_f32_16x16x32_bf16 v[124:127], v[132:135], v[176:179], v[124:127]
	v_mfma_f32_16x16x32_bf16 v[112:115], v[140:143], v[176:179], v[112:115]
	v_mfma_f32_16x16x32_bf16 v[108:111], v[132:135], v[194:197], v[108:111]
	v_mfma_f32_16x16x32_bf16 v[96:99], v[140:143], v[194:197], v[96:99]
	v_mfma_f32_16x16x32_bf16 v[92:95], v[132:135], v[216:219], v[92:95]
	v_mfma_f32_16x16x32_bf16 v[80:83], v[140:143], v[216:219], v[80:83]
	v_mfma_f32_16x16x32_bf16 v[76:79], v[132:135], v[230:233], v[76:79]
	v_mfma_f32_16x16x32_bf16 v[64:67], v[140:143], v[230:233], v[64:67]
	s_setprio 0
	s_setprio 1
	v_mfma_f32_16x16x32_bf16 v[120:123], v[144:147], v[172:175], v[120:123]
	v_mfma_f32_16x16x32_bf16 v[116:119], v[164:167], v[172:175], v[116:119]
	v_mfma_f32_16x16x32_bf16 v[104:107], v[144:147], v[186:189], v[104:107]
	v_mfma_f32_16x16x32_bf16 v[100:103], v[164:167], v[186:189], v[100:103]
	v_mfma_f32_16x16x32_bf16 v[88:91], v[144:147], v[198:201], v[88:91]
	v_mfma_f32_16x16x32_bf16 v[84:87], v[164:167], v[198:201], v[84:87]
	v_mfma_f32_16x16x32_bf16 v[72:75], v[144:147], v[224:227], v[72:75]
	v_mfma_f32_16x16x32_bf16 v[68:71], v[164:167], v[224:227], v[68:71]
	v_mfma_f32_16x16x32_bf16 v[120:123], v[148:151], v[176:179], v[120:123]
	v_mfma_f32_16x16x32_bf16 v[116:119], v[168:171], v[176:179], v[116:119]
	v_mfma_f32_16x16x32_bf16 v[104:107], v[148:151], v[194:197], v[104:107]
	v_mfma_f32_16x16x32_bf16 v[100:103], v[168:171], v[194:197], v[100:103]
	v_mfma_f32_16x16x32_bf16 v[88:91], v[148:151], v[216:219], v[88:91]
	v_mfma_f32_16x16x32_bf16 v[84:87], v[168:171], v[216:219], v[84:87]
	v_mfma_f32_16x16x32_bf16 v[72:75], v[148:151], v[230:233], v[72:75]
	v_mfma_f32_16x16x32_bf16 v[68:71], v[168:171], v[230:233], v[68:71]
	s_barrier
	s_setprio 0
	s_add_i32 s63, s63, s47
	v_lshl_add_u64 v[202:203], s[44:45], 0, v[180:181]
	s_mov_b32 m0, s63
	ds_read_b128 v[172:175], v193 offset:16384
	ds_read_b128 v[176:179], v193 offset:17408
	ds_read_b128 v[186:189], v193 offset:18432
	ds_read_b128 v[194:197], v193 offset:19456
	ds_read_b128 v[198:201], v193 offset:20480
	ds_read_b128 v[216:219], v193 offset:21504
	ds_read_b128 v[224:227], v193 offset:22528
	ds_read_b128 v[230:233], v193 offset:23552
	global_load_lds_dwordx4 v[202:203], off
	s_add_i32 m0, s63, 0x2000
	s_add_u32 s76, s44, 0x40000
	v_lshl_add_u64 v[208:209], s[44:45], 0, v[152:153]
	s_addc_u32 s77, s45, 0
	s_add_i32 s63, s73, s47
	global_load_lds_dwordx4 v[208:209], off
	v_lshl_add_u64 v[220:221], s[76:77], 0, v[180:181]
	s_mov_b32 m0, s63
	v_lshl_add_u64 v[234:235], s[50:51], 0, v[154:155]
	global_load_lds_dwordx4 v[220:221], off
	v_lshl_add_u64 v[220:221], s[76:77], 0, v[152:153]
	s_add_i32 m0, s63, 0x2000
	s_nop 0
	global_load_lds_dwordx4 v[220:221], off
	v_lshl_add_u64 v[220:221], s[50:51], 0, v[156:157]
	s_mov_b32 m0, s52
	s_nop 0
	global_load_lds_dwordx4 v[220:221], off
	s_mov_b32 m0, s53
	s_nop 0
	global_load_lds_dwordx4 v[234:235], off
	s_waitcnt vmcnt(8)
	s_waitcnt lgkmcnt(0)
	s_setprio 1
	s_barrier
	v_mfma_f32_16x16x32_bf16 v[60:63], v[128:131], v[172:175], v[60:63]
	v_mfma_f32_16x16x32_bf16 v[48:51], v[136:139], v[172:175], v[48:51]
	v_mfma_f32_16x16x32_bf16 v[44:47], v[128:131], v[186:189], v[44:47]
	v_mfma_f32_16x16x32_bf16 v[32:35], v[136:139], v[186:189], v[32:35]
	v_mfma_f32_16x16x32_bf16 v[28:31], v[128:131], v[198:201], v[28:31]
	v_mfma_f32_16x16x32_bf16 v[16:19], v[136:139], v[198:201], v[16:19]
	v_mfma_f32_16x16x32_bf16 v[12:15], v[128:131], v[224:227], v[12:15]
	v_mfma_f32_16x16x32_bf16 v[4:7], v[136:139], v[224:227], v[4:7]
	v_mfma_f32_16x16x32_bf16 v[60:63], v[132:135], v[176:179], v[60:63]
	v_mfma_f32_16x16x32_bf16 v[48:51], v[140:143], v[176:179], v[48:51]
	v_mfma_f32_16x16x32_bf16 v[44:47], v[132:135], v[194:197], v[44:47]
	v_mfma_f32_16x16x32_bf16 v[32:35], v[140:143], v[194:197], v[32:35]
	v_mfma_f32_16x16x32_bf16 v[28:31], v[132:135], v[216:219], v[28:31]
	v_mfma_f32_16x16x32_bf16 v[16:19], v[140:143], v[216:219], v[16:19]
	v_mfma_f32_16x16x32_bf16 v[12:15], v[132:135], v[230:233], v[12:15]
	v_mfma_f32_16x16x32_bf16 v[4:7], v[140:143], v[230:233], v[4:7]
	s_setprio 0
	s_setprio 1
	v_mfma_f32_16x16x32_bf16 v[56:59], v[144:147], v[172:175], v[56:59]
	v_mfma_f32_16x16x32_bf16 v[52:55], v[164:167], v[172:175], v[52:55]
	v_mfma_f32_16x16x32_bf16 v[40:43], v[144:147], v[186:189], v[40:43]
	v_mfma_f32_16x16x32_bf16 v[36:39], v[164:167], v[186:189], v[36:39]
	v_mfma_f32_16x16x32_bf16 v[24:27], v[144:147], v[198:201], v[24:27]
	v_mfma_f32_16x16x32_bf16 v[20:23], v[164:167], v[198:201], v[20:23]
	v_mfma_f32_16x16x32_bf16 v[8:11], v[144:147], v[224:227], v[8:11]
	v_mfma_f32_16x16x32_bf16 v[0:3], v[164:167], v[224:227], v[0:3]
	v_mfma_f32_16x16x32_bf16 v[56:59], v[148:151], v[176:179], v[56:59]
	v_mfma_f32_16x16x32_bf16 v[52:55], v[168:171], v[176:179], v[52:55]
	v_mfma_f32_16x16x32_bf16 v[40:43], v[148:151], v[194:197], v[40:43]
	v_mfma_f32_16x16x32_bf16 v[36:39], v[168:171], v[194:197], v[36:39]
	v_mfma_f32_16x16x32_bf16 v[24:27], v[148:151], v[216:219], v[24:27]
	v_mfma_f32_16x16x32_bf16 v[20:23], v[168:171], v[216:219], v[20:23]
	v_mfma_f32_16x16x32_bf16 v[8:11], v[148:151], v[230:233], v[8:11]
	v_mfma_f32_16x16x32_bf16 v[0:3], v[168:171], v[230:233], v[0:3]
	s_barrier
; #define PG8_STAGE(bufoff, gbase, voff) do { _Pragma("unroll") for (int _i = 0; _i < 2; ++_i) \
;         __builtin_amdgcn_global_load_lds((const unsigned*)((const char*)(gbase) + (voff)[_i]), (PG8_LAS unsigned*)(lds + (bufoff) + ldsw + _i * 8192), 16, 0, 0); } while (0)
; #define PG8_LDA(dst, b, h) do { _Pragma("unroll") for (int m = 0; m < 4; ++m) _Pragma("unroll") for (int k = 0; k < 2; ++k) dst[m][k] = *(const PG8_LAS bf16x8*)(lds + PG8_SA(b, h) + aoff + m * 2048 + k * 1024); } while (0)
; #define PG8_LDB(dst, b, h) do { _Pragma("unroll") for (int n = 0; n < 2; ++n) _Pragma("unroll") for (int k = 0; k < 2; ++k) dst[n][k] = *(const PG8_LAS bf16x8*)(lds + PG8_SB(b, h) + boff + n * 2048 + k * 1024); } while (0)
; #define PG8_MMA(ai, bj, At, Bt) do { __builtin_amdgcn_s_setprio(1); _Pragma("unroll") for (int m = 0; m < 4; ++m) _Pragma("unroll") for (int n = 0; n < 2; ++n) _Pragma("unroll") for (int k = 0; k < 2; ++k) \
;         acc[ai][bj][m][n] = __builtin_amdgcn_mfma_f32_16x16x32_bf16(Bt[n][k], At[m][k], acc[ai][bj][m][n], 0, 0, 0); __builtin_amdgcn_s_setprio(0); } while (0)
; #define PG8_WAIT_V(n) asm volatile("s_waitcnt vmcnt(" #n ")" ::: "memory")
; #define PG8_WAIT_L(n) asm volatile("s_waitcnt lgkmcnt(" #n ")" ::: "memory")
; #define PG8_BAR __builtin_amdgcn_s_barrier()
; #define PG8_SCHED __builtin_amdgcn_sched_barrier(0)
; template <class Epi, class Sched, bool ALIGN_EPI = false, bool SP2 = false>
; __device__ __forceinline__ void gemm_phase(PG8_LAS unsigned char* lds, const Gemm g, const Sched& S, const Epi& E) {
;     ...
;             PG8_LDB(B0, 1, 0); PG8_LDB(B1, 1, 1); PG8_SCHED; PG8_LDA(At, 1, 0); PG8_STAGE(PG8_SA(0, 1), a2 + hstep, voffA);
;             PG8_WAIT_V(8); PG8_WAIT_L(0); PG8_BAR; PG8_MMA(0, 0, At, B0); PG8_MMA(0, 1, At, B1); PG8_BAR; PG8_SCHED;
;             PG8_LDA(At, 1, 1); PG8_STAGE(PG8_SB(1, 0), b3, voffB); PG8_STAGE(PG8_SB(1, 1), b3 + hstep, voffB); PG8_STAGE(PG8_SA(1, 0), a3, voffA);
	s_setprio 0
	s_add_i32 s63, 0, 0x18000
	s_add_i32 s73, 0, 0x1c000
	v_add_u32_e32 v140, s63, v191
	v_add_u32_e32 v168, s73, v191
	ds_read_b128 v[128:131], v140
	ds_read_b128 v[132:135], v140 offset:1024
	ds_read_b128 v[136:139], v140 offset:2048
	ds_read_b128 v[140:143], v140 offset:3072
	ds_read_b128 v[144:147], v168
	ds_read_b128 v[148:151], v168 offset:1024
	ds_read_b128 v[164:167], v168 offset:2048
	ds_read_b128 v[168:171], v168 offset:3072
	s_add_u32 s50, s50, 0x40000
	s_addc_u32 s51, s51, 0
	s_mov_b32 m0, s54
	v_lshl_add_u64 v[236:237], s[50:51], 0, v[156:157]
	ds_read_b128 v[172:175], v193 offset:32768
	ds_read_b128 v[176:179], v193 offset:33792
	ds_read_b128 v[186:189], v193 offset:34816
	ds_read_b128 v[194:197], v193 offset:35840
	ds_read_b128 v[198:201], v193 offset:36864
	ds_read_b128 v[216:219], v193 offset:37888
	ds_read_b128 v[224:227], v193 offset:38912
	ds_read_b128 v[230:233], v193 offset:39936
	global_load_lds_dwordx4 v[236:237], off
	v_lshl_add_u64 v[236:237], s[50:51], 0, v[154:155]
	s_mov_b32 m0, s55
	s_nop 0
	global_load_lds_dwordx4 v[236:237], off
	s_waitcnt vmcnt(8)
	s_waitcnt lgkmcnt(0)
	s_setprio 1
	s_barrier
	v_mfma_f32_16x16x32_bf16 v[124:127], v[128:131], v[172:175], v[124:127]
	v_mfma_f32_16x16x32_bf16 v[112:115], v[136:139], v[172:175], v[112:115]
	v_mfma_f32_16x16x32_bf16 v[108:111], v[128:131], v[186:189], v[108:111]
	v_mfma_f32_16x16x32_bf16 v[96:99], v[136:139], v[186:189], v[96:99]
	v_mfma_f32_16x16x32_bf16 v[92:95], v[128:131], v[198:201], v[92:95]
	v_mfma_f32_16x16x32_bf16 v[80:83], v[136:139], v[198:201], v[80:83]
	v_mfma_f32_16x16x32_bf16 v[76:79], v[128:131], v[224:227], v[76:79]
	v_mfma_f32_16x16x32_bf16 v[64:67], v[136:139], v[224:227], v[64:67]
	v_mfma_f32_16x16x32_bf16 v[124:127], v[132:135], v[176:179], v[124:127]
	v_mfma_f32_16x16x32_bf16 v[112:115], v[140:143], v[176:179], v[112:115]
	v_mfma_f32_16x16x32_bf16 v[108:111], v[132:135], v[194:197], v[108:111]
	v_mfma_f32_16x16x32_bf16 v[96:99], v[140:143], v[194:197], v[96:99]
	v_mfma_f32_16x16x32_bf16 v[92:95], v[132:135], v[216:219], v[92:95]
	v_mfma_f32_16x16x32_bf16 v[80:83], v[140:143], v[216:219], v[80:83]
	v_mfma_f32_16x16x32_bf16 v[76:79], v[132:135], v[230:233], v[76:79]
	v_mfma_f32_16x16x32_bf16 v[64:67], v[140:143], v[230:233], v[64:67]
	s_setprio 0
	s_setprio 1
	v_mfma_f32_16x16x32_bf16 v[120:123], v[144:147], v[172:175], v[120:123]
	v_mfma_f32_16x16x32_bf16 v[116:119], v[164:167], v[172:175], v[116:119]
	v_mfma_f32_16x16x32_bf16 v[104:107], v[144:147], v[186:189], v[104:107]
	v_mfma_f32_16x16x32_bf16 v[100:103], v[164:167], v[186:189], v[100:103]
	v_mfma_f32_16x16x32_bf16 v[88:91], v[144:147], v[198:201], v[88:91]
	v_mfma_f32_16x16x32_bf16 v[84:87], v[164:167], v[198:201], v[84:87]
	v_mfma_f32_16x16x32_bf16 v[72:75], v[144:147], v[224:227], v[72:75]
	v_mfma_f32_16x16x32_bf16 v[68:71], v[164:167], v[224:227], v[68:71]
	v_mfma_f32_16x16x32_bf16 v[120:123], v[148:151], v[176:179], v[120:123]
	v_mfma_f32_16x16x32_bf16 v[116:119], v[168:171], v[176:179], v[116:119]
	v_mfma_f32_16x16x32_bf16 v[104:107], v[148:151], v[194:197], v[104:107]
	v_mfma_f32_16x16x32_bf16 v[100:103], v[168:171], v[194:197], v[100:103]
	v_mfma_f32_16x16x32_bf16 v[88:91], v[148:151], v[216:219], v[88:91]
	v_mfma_f32_16x16x32_bf16 v[84:87], v[168:171], v[216:219], v[84:87]
	v_mfma_f32_16x16x32_bf16 v[72:75], v[148:151], v[230:233], v[72:75]
	v_mfma_f32_16x16x32_bf16 v[68:71], v[168:171], v[230:233], v[68:71]
	s_barrier
	s_setprio 0
	s_add_i32 s50, s63, s47
	v_lshl_add_u64 v[202:203], v[202:203], 0, s[70:71]
	s_mov_b32 m0, s50
	ds_read_b128 v[172:175], v193 offset:49152
	ds_read_b128 v[176:179], v193 offset:50176
	ds_read_b128 v[186:189], v193 offset:51200
	ds_read_b128 v[194:197], v193 offset:52224
	ds_read_b128 v[198:201], v193 offset:53248
	ds_read_b128 v[216:219], v193 offset:54272
	ds_read_b128 v[224:227], v193 offset:55296
	ds_read_b128 v[230:233], v193 offset:56320
	global_load_lds_dwordx4 v[202:203], off
	s_add_i32 m0, s50, 0x2000
	s_add_u32 s44, s44, 0x40080
	v_lshl_add_u64 v[202:203], v[208:209], 0, s[70:71]
	s_addc_u32 s45, s45, 0
	s_add_i32 s50, s73, s47
	global_load_lds_dwordx4 v[202:203], off
	v_lshl_add_u64 v[202:203], s[44:45], 0, v[180:181]
	s_mov_b32 m0, s50
	s_nop 0
	global_load_lds_dwordx4 v[202:203], off
	v_lshl_add_u64 v[202:203], s[44:45], 0, v[152:153]
	s_add_i32 m0, s50, 0x2000
	s_nop 0
	global_load_lds_dwordx4 v[202:203], off
	v_lshl_add_u64 v[202:203], v[220:221], 0, s[70:71]
	s_mov_b32 m0, s56
	s_nop 0
	global_load_lds_dwordx4 v[202:203], off
	v_lshl_add_u64 v[202:203], v[234:235], 0, s[70:71]
	s_mov_b32 m0, s57
	s_nop 0
	global_load_lds_dwordx4 v[202:203], off
	s_waitcnt vmcnt(8)
	s_waitcnt lgkmcnt(0)
	s_setprio 1
	s_barrier
; #define PG8_MMA(ai, bj, At, Bt) do { __builtin_amdgcn_s_setprio(1); _Pragma("unroll") for (int m = 0; m < 4; ++m) _Pragma("unroll") for (int n = 0; n < 2; ++n) _Pragma("unroll") for (int k = 0; k < 2; ++k) \
;         acc[ai][bj][m][n] = __builtin_amdgcn_mfma_f32_16x16x32_bf16(Bt[n][k], At[m][k], acc[ai][bj][m][n], 0, 0, 0); __builtin_amdgcn_s_setprio(0); } while (0)
; #define PG8_WAIT_V(n) asm volatile("s_waitcnt vmcnt(" #n ")" ::: "memory")
; #define PG8_WAIT_L(n) asm volatile("s_waitcnt lgkmcnt(" #n ")" ::: "memory")
; #define PG8_BAR __builtin_amdgcn_s_barrier()
; #define PG8_SCHED __builtin_amdgcn_sched_barrier(0)
; __device__ __forceinline__ float row_rs(const float* part, int row, int fq) {
;     const f32x4 v = *(const f32x4*)(part + (size_t)row * 16 + 4 * fq);
;     float s = (v[0] + v[1]) + (v[2] + v[3]); s += __shfl_xor(s, 16); s += __shfl_xor(s, 32);
;     return rsqrtf(s * (1.0f / 1024.0f) + 1e-6f);
; }
; template <class Epi, class Sched, bool ALIGN_EPI = false, bool SP2 = false>
; __device__ __forceinline__ void gemm_phase(PG8_LAS unsigned char* lds, const Gemm g, const Sched& S, const Epi& E) {
;     ...
;             PG8_WAIT_V(8); PG8_WAIT_L(0); PG8_BAR; PG8_MMA(1, 0, At, B0); PG8_MMA(1, 1, At, B1); PG8_BAR; PG8_SCHED;
	v_mfma_f32_16x16x32_bf16 v[60:63], v[128:131], v[172:175], v[60:63]
	v_mfma_f32_16x16x32_bf16 v[48:51], v[136:139], v[172:175], v[48:51]
	v_mfma_f32_16x16x32_bf16 v[44:47], v[128:131], v[186:189], v[44:47]
	v_mfma_f32_16x16x32_bf16 v[32:35], v[136:139], v[186:189], v[32:35]
	v_mfma_f32_16x16x32_bf16 v[28:31], v[128:131], v[198:201], v[28:31]
	v_mfma_f32_16x16x32_bf16 v[16:19], v[136:139], v[198:201], v[16:19]
	v_mfma_f32_16x16x32_bf16 v[12:15], v[128:131], v[224:227], v[12:15]
	v_mfma_f32_16x16x32_bf16 v[4:7], v[136:139], v[224:227], v[4:7]
	v_mfma_f32_16x16x32_bf16 v[60:63], v[132:135], v[176:179], v[60:63]
	v_mfma_f32_16x16x32_bf16 v[48:51], v[140:143], v[176:179], v[48:51]
	v_mfma_f32_16x16x32_bf16 v[44:47], v[132:135], v[194:197], v[44:47]
	v_mfma_f32_16x16x32_bf16 v[32:35], v[140:143], v[194:197], v[32:35]
	v_mfma_f32_16x16x32_bf16 v[28:31], v[132:135], v[216:219], v[28:31]
	v_mfma_f32_16x16x32_bf16 v[16:19], v[140:143], v[216:219], v[16:19]
	v_mfma_f32_16x16x32_bf16 v[12:15], v[132:135], v[230:233], v[12:15]
	v_mfma_f32_16x16x32_bf16 v[4:7], v[140:143], v[230:233], v[4:7]
	s_setprio 0
	s_setprio 1
	v_mfma_f32_16x16x32_bf16 v[56:59], v[144:147], v[172:175], v[56:59]
	v_mfma_f32_16x16x32_bf16 v[52:55], v[164:167], v[172:175], v[52:55]
	v_mfma_f32_16x16x32_bf16 v[40:43], v[144:147], v[186:189], v[40:43]
	v_mfma_f32_16x16x32_bf16 v[36:39], v[164:167], v[186:189], v[36:39]
	v_mfma_f32_16x16x32_bf16 v[24:27], v[144:147], v[198:201], v[24:27]
	v_mfma_f32_16x16x32_bf16 v[20:23], v[164:167], v[198:201], v[20:23]
	v_mfma_f32_16x16x32_bf16 v[8:11], v[144:147], v[224:227], v[8:11]
	v_mfma_f32_16x16x32_bf16 v[0:3], v[164:167], v[224:227], v[0:3]
	v_mfma_f32_16x16x32_bf16 v[56:59], v[148:151], v[176:179], v[56:59]
	v_mfma_f32_16x16x32_bf16 v[52:55], v[168:171], v[176:179], v[52:55]
	v_mfma_f32_16x16x32_bf16 v[40:43], v[148:151], v[194:197], v[40:43]
	v_mfma_f32_16x16x32_bf16 v[36:39], v[168:171], v[194:197], v[36:39]
	v_mfma_f32_16x16x32_bf16 v[24:27], v[148:151], v[216:219], v[24:27]
	v_mfma_f32_16x16x32_bf16 v[20:23], v[168:171], v[216:219], v[20:23]
	v_mfma_f32_16x16x32_bf16 v[8:11], v[148:151], v[230:233], v[8:11]
	v_mfma_f32_16x16x32_bf16 v[0:3], v[168:171], v[230:233], v[0:3]
	s_barrier
	s_setprio 0
	s_add_i32 s62, s62, 2
	s_add_u32 s6, s6, 0x100
	s_addc_u32 s7, s7, 0
	s_add_u32 s60, s60, 0x100
	s_addc_u32 s61, s61, 0
	s_cmp_gt_u32 s62, 13
	s_cbranch_scc0 .LBB0_198
	s_and_b64 vcc, exec, s[16:17]
	s_cbranch_vccz .LBB0_201
	v_lshl_add_u32 v194, s59, 8, v228
	v_lshlrev_b32_e32 v194, 6, v194
	v_and_b32_e32 v196, 48, v228
	v_sub_u32_e32 v194, v194, v196
	v_mov_b32_e32 v195, 0
	v_lshl_add_u64 v[194:195], v[158:159], 0, v[194:195]
	global_load_dwordx4 v[128:131], v[194:195], off
	global_load_dwordx4 v[132:135], v[194:195], off offset:16
	global_load_dwordx4 v[136:139], v[194:195], off offset:32
	global_load_dwordx4 v[140:143], v[194:195], off offset:48
	v_lshlrev_b32_e32 v196, 2, v228
	v_add_u32_e32 v196, 0x20000, v196
	v_mov_b32_e32 v197, s74
	s_waitcnt vmcnt(0)
	v_add_f32_e32 v128, v128, v129
	v_add_f32_e32 v130, v130, v131
	v_add_f32_e32 v128, v128, v130
	v_add_f32_e32 v132, v132, v133
	v_add_f32_e32 v134, v134, v135
	v_add_f32_e32 v132, v132, v134
	v_add_f32_e32 v136, v136, v137
	v_add_f32_e32 v138, v138, v139
	v_add_f32_e32 v136, v136, v138
	v_add_f32_e32 v140, v140, v141
	v_add_f32_e32 v142, v142, v143
	v_add_f32_e32 v140, v140, v142
	v_add_f32_e32 v128, v128, v132
	v_add_f32_e32 v136, v136, v140
	v_add_f32_e32 v128, v128, v136
	v_fma_f32 v128, v128, s72, v197
	v_mul_f32_e32 v129, 0x4b800000, v128
	v_cmp_gt_f32_e32 vcc, s91, v128
	s_nop 1
	v_cndmask_b32_e32 v128, v128, v129, vcc
	v_rsq_f32_e32 v128, v128
	s_nop 0
	v_mul_f32_e32 v129, 0x45800000, v128
	v_cndmask_b32_e32 v128, v128, v129, vcc
	ds_write_b32 v196, v128
	s_waitcnt lgkmcnt(0)
	s_barrier

; #define PG8_STAGE(bufoff, gbase, voff) do { _Pragma("unroll") for (int _i = 0; _i < 2; ++_i) \
;         __builtin_amdgcn_global_load_lds((const unsigned*)((const char*)(gbase) + (voff)[_i]), (PG8_LAS unsigned*)(lds + (bufoff) + ldsw + _i * 8192), 16, 0, 0); } while (0)
; #define PG8_LDA(dst, b, h) do { _Pragma("unroll") for (int m = 0; m < 4; ++m) _Pragma("unroll") for (int k = 0; k < 2; ++k) dst[m][k] = *(const PG8_LAS bf16x8*)(lds + PG8_SA(b, h) + aoff + m * 2048 + k * 1024); } while (0)
; #define PG8_LDB(dst, b, h) do { _Pragma("unroll") for (int n = 0; n < 2; ++n) _Pragma("unroll") for (int k = 0; k < 2; ++k) dst[n][k] = *(const PG8_LAS bf16x8*)(lds + PG8_SB(b, h) + boff + n * 2048 + k * 1024); } while (0)
; #define PG8_MMA(ai, bj, At, Bt) do { __builtin_amdgcn_s_setprio(1); _Pragma("unroll") for (int m = 0; m < 4; ++m) _Pragma("unroll") for (int n = 0; n < 2; ++n) _Pragma("unroll") for (int k = 0; k < 2; ++k) \
;         acc[ai][bj][m][n] = __builtin_amdgcn_mfma_f32_16x16x32_bf16(Bt[n][k], At[m][k], acc[ai][bj][m][n], 0, 0, 0); __builtin_amdgcn_s_setprio(0); } while (0)
; #define PG8_BAR __builtin_amdgcn_s_barrier()
; template <class Epi, class Sched, bool ALIGN_EPI = false, bool SP2 = false>
; __device__ __forceinline__ void gemm_phase(PG8_LAS unsigned char* lds, const Gemm g, const Sched& S, const Epi& E) {
;     ...
;         const bool has_next = S.next(ui + 1, nxt);
;         const char* nA = has_next ? (const char*)g.A + (size_t)nxt.pm * tstep : cA; const char* nB = has_next ? (const char*)g.Bt + (size_t)nxt.pn * tstep : cB;
;         for (int t = 0; t < nt; t += 2) {
;             const bool last = (t == nt - 2);
;             const char* a1 = cA + (size_t)(t + 1) * kstep;
;             const char* a2 = last ? nA : cA + (size_t)(t + 2) * kstep; const char* b2 = last ? nB : cB + (size_t)(t + 2) * kstep;
;             const char* a3 = a2 + kstep; const char* b3 = b2 + kstep;
;             if (last && has_next) S.a_ready(nxt);
;             if constexpr (SP2) {
;             PG8_LDB(B0, 0, 0); PG8_LDB(B1, 0, 1); PG8_SCHED; PG8_LDA(At, 0, 0); PG8_STAGE(PG8_SA(1, 1), a1 + hstep, voffA);
;             PG8_WAIT_V(8); PG8_WAIT_L(0); PG8_BAR; PG8_MMA(0, 0, At, B0); PG8_MMA(0, 1, At, B1); PG8_BAR; PG8_SCHED;
;             PG8_LDA(At, 0, 1); PG8_STAGE(PG8_SB(0, 0), b2, voffB); PG8_STAGE(PG8_SB(0, 1), b2 + hstep, voffB); PG8_STAGE(PG8_SA(0, 0), a2, voffA);
.LBB0_273:
	s_add_u32 s23, s52, 0x100
	s_addc_u32 s62, s53, 0
	s_mov_b32 s63, -2
	s_waitcnt lgkmcnt(0)
	s_add_u32 s52, s50, 0x100
	s_addc_u32 s53, s51, 0
	s_add_i32 s68, 0, 0x10000
	s_cmp_eq_u32 s63, 40
	s_cselect_b32 s61, s11, s53
	s_cselect_b32 s60, s10, s52
	s_cselect_b32 s55, s45, s62
	s_cselect_b32 s54, s44, s23
	s_add_i32 s73, 0, 0x14000
	v_add_u32_e32 v150, s68, v157
	v_add_u32_e32 v154, s73, v157
	ds_read_b128 v[128:131], v150
	ds_read_b128 v[132:135], v150 offset:1024
	ds_read_b128 v[146:149], v150 offset:2048
	ds_read_b128 v[150:153], v150 offset:3072
	ds_read_b128 v[160:163], v154
	ds_read_b128 v[164:167], v154 offset:1024
	ds_read_b128 v[168:171], v154 offset:2048
	ds_read_b128 v[172:175], v154 offset:3072
	v_lshl_add_u64 v[154:155], s[50:51], 0, v[142:143]
	s_add_i32 m0, s39, 0xc000
	ds_read_b128 v[176:179], v159
	ds_read_b128 v[186:189], v159 offset:1024
	ds_read_b128 v[190:193], v159 offset:2048
	ds_read_b128 v[194:197], v159 offset:3072
	ds_read_b128 v[198:201], v159 offset:4096
	ds_read_b128 v[216:219], v159 offset:5120
	ds_read_b128 v[224:227], v159 offset:6144
	ds_read_b128 v[230:233], v159 offset:7168
	global_load_lds_dwordx4 v[154:155], off
	v_lshl_add_u64 v[154:155], s[50:51], 0, v[144:145]
	s_add_i32 m0, s39, 0xe000
	s_nop 0
	global_load_lds_dwordx4 v[154:155], off
	s_waitcnt vmcnt(8)
	s_waitcnt lgkmcnt(0)
	s_setprio 1
	s_barrier
	v_mfma_f32_16x16x32_bf16 v[124:127], v[128:131], v[176:179], 0
	v_mfma_f32_16x16x32_bf16 v[120:123], v[146:149], v[176:179], 0
	v_mfma_f32_16x16x32_bf16 v[108:111], v[128:131], v[190:193], 0
	v_mfma_f32_16x16x32_bf16 v[104:107], v[146:149], v[190:193], 0
	v_mfma_f32_16x16x32_bf16 v[92:95], v[128:131], v[198:201], 0
	v_mfma_f32_16x16x32_bf16 v[88:91], v[146:149], v[198:201], 0
	v_mfma_f32_16x16x32_bf16 v[76:79], v[128:131], v[224:227], 0
	v_mfma_f32_16x16x32_bf16 v[72:75], v[146:149], v[224:227], 0
	v_mfma_f32_16x16x32_bf16 v[124:127], v[132:135], v[186:189], v[124:127]
	v_mfma_f32_16x16x32_bf16 v[120:123], v[150:153], v[186:189], v[120:123]
	v_mfma_f32_16x16x32_bf16 v[108:111], v[132:135], v[194:197], v[108:111]
	v_mfma_f32_16x16x32_bf16 v[104:107], v[150:153], v[194:197], v[104:107]
	v_mfma_f32_16x16x32_bf16 v[92:95], v[132:135], v[216:219], v[92:95]
	v_mfma_f32_16x16x32_bf16 v[88:91], v[150:153], v[216:219], v[88:91]
	v_mfma_f32_16x16x32_bf16 v[76:79], v[132:135], v[230:233], v[76:79]
	v_mfma_f32_16x16x32_bf16 v[72:75], v[150:153], v[230:233], v[72:75]
	s_setprio 0
	s_setprio 1
	v_mfma_f32_16x16x32_bf16 v[116:119], v[160:163], v[176:179], 0
	v_mfma_f32_16x16x32_bf16 v[112:115], v[168:171], v[176:179], 0
	v_mfma_f32_16x16x32_bf16 v[100:103], v[160:163], v[190:193], 0
	v_mfma_f32_16x16x32_bf16 v[96:99], v[168:171], v[190:193], 0
	v_mfma_f32_16x16x32_bf16 v[84:87], v[160:163], v[198:201], 0
	v_mfma_f32_16x16x32_bf16 v[80:83], v[168:171], v[198:201], 0
	v_mfma_f32_16x16x32_bf16 v[68:71], v[160:163], v[224:227], 0
	v_mfma_f32_16x16x32_bf16 v[64:67], v[168:171], v[224:227], 0
	v_mfma_f32_16x16x32_bf16 v[116:119], v[164:167], v[186:189], v[116:119]
	v_mfma_f32_16x16x32_bf16 v[112:115], v[172:175], v[186:189], v[112:115]
	v_mfma_f32_16x16x32_bf16 v[100:103], v[164:167], v[194:197], v[100:103]
	v_mfma_f32_16x16x32_bf16 v[96:99], v[172:175], v[194:197], v[96:99]
	v_mfma_f32_16x16x32_bf16 v[84:87], v[164:167], v[216:219], v[84:87]
	v_mfma_f32_16x16x32_bf16 v[80:83], v[172:175], v[216:219], v[80:83]
	v_mfma_f32_16x16x32_bf16 v[68:71], v[164:167], v[230:233], v[68:71]
	v_mfma_f32_16x16x32_bf16 v[64:67], v[172:175], v[230:233], v[64:67]
	s_barrier
	s_setprio 0
	s_add_i32 s50, s68, s38
	v_lshl_add_u64 v[154:155], s[54:55], 0, v[180:181]
	s_mov_b32 m0, s50
	ds_read_b128 v[176:179], v159 offset:16384
	ds_read_b128 v[186:189], v159 offset:17408
	ds_read_b128 v[190:193], v159 offset:18432
	ds_read_b128 v[194:197], v159 offset:19456
	ds_read_b128 v[198:201], v159 offset:20480
	ds_read_b128 v[216:219], v159 offset:21504
	ds_read_b128 v[224:227], v159 offset:22528
	ds_read_b128 v[230:233], v159 offset:23552
	global_load_lds_dwordx4 v[154:155], off
	s_add_i32 m0, s50, 0x2000
	s_add_u32 s50, s54, 0xb0000
	v_lshl_add_u64 v[202:203], s[54:55], 0, v[136:137]
	s_addc_u32 s51, s55, 0
	s_add_i32 s68, s73, s38
	global_load_lds_dwordx4 v[202:203], off
	v_lshl_add_u64 v[208:209], s[50:51], 0, v[180:181]
	s_mov_b32 m0, s68
	v_lshl_add_u64 v[220:221], s[60:61], 0, v[138:139]
	global_load_lds_dwordx4 v[208:209], off
	v_lshl_add_u64 v[208:209], s[50:51], 0, v[136:137]
	s_add_i32 m0, s68, 0x2000
	s_nop 0
	global_load_lds_dwordx4 v[208:209], off
	v_lshl_add_u64 v[208:209], s[60:61], 0, v[140:141]
	s_mov_b32 m0, s39
	s_nop 0
	global_load_lds_dwordx4 v[208:209], off
	s_mov_b32 m0, s46
	s_nop 0
	global_load_lds_dwordx4 v[220:221], off
	s_waitcnt vmcnt(8)
	s_waitcnt lgkmcnt(0)
	s_setprio 1
	s_barrier
; #define PG8_STAGE(bufoff, gbase, voff) do { _Pragma("unroll") for (int _i = 0; _i < 2; ++_i) \
;         __builtin_amdgcn_global_load_lds((const unsigned*)((const char*)(gbase) + (voff)[_i]), (PG8_LAS unsigned*)(lds + (bufoff) + ldsw + _i * 8192), 16, 0, 0); } while (0)
; #define PG8_LDA(dst, b, h) do { _Pragma("unroll") for (int m = 0; m < 4; ++m) _Pragma("unroll") for (int k = 0; k < 2; ++k) dst[m][k] = *(const PG8_LAS bf16x8*)(lds + PG8_SA(b, h) + aoff + m * 2048 + k * 1024); } while (0)
; #define PG8_LDB(dst, b, h) do { _Pragma("unroll") for (int n = 0; n < 2; ++n) _Pragma("unroll") for (int k = 0; k < 2; ++k) dst[n][k] = *(const PG8_LAS bf16x8*)(lds + PG8_SB(b, h) + boff + n * 2048 + k * 1024); } while (0)
; #define PG8_MMA(ai, bj, At, Bt) do { __builtin_amdgcn_s_setprio(1); _Pragma("unroll") for (int m = 0; m < 4; ++m) _Pragma("unroll") for (int n = 0; n < 2; ++n) _Pragma("unroll") for (int k = 0; k < 2; ++k) \
;         acc[ai][bj][m][n] = __builtin_amdgcn_mfma_f32_16x16x32_bf16(Bt[n][k], At[m][k], acc[ai][bj][m][n], 0, 0, 0); __builtin_amdgcn_s_setprio(0); } while (0)
; #define PG8_WAIT_V(n) asm volatile("s_waitcnt vmcnt(" #n ")" ::: "memory")
; #define PG8_WAIT_L(n) asm volatile("s_waitcnt lgkmcnt(" #n ")" ::: "memory")
; #define PG8_BAR __builtin_amdgcn_s_barrier()
; #define PG8_SCHED __builtin_amdgcn_sched_barrier(0)
; template <class Epi, class Sched, bool ALIGN_EPI = false, bool SP2 = false>
; __device__ __forceinline__ void gemm_phase(PG8_LAS unsigned char* lds, const Gemm g, const Sched& S, const Epi& E) {
;     ...
;             PG8_WAIT_V(8); PG8_WAIT_L(0); PG8_BAR; PG8_MMA(1, 0, At, B0); PG8_MMA(1, 1, At, B1); PG8_BAR; PG8_SCHED;
;             PG8_LDB(B0, 1, 0); PG8_LDB(B1, 1, 1); PG8_SCHED; PG8_LDA(At, 1, 0); PG8_STAGE(PG8_SA(0, 1), a2 + hstep, voffA);
;             PG8_WAIT_V(8); PG8_WAIT_L(0); PG8_BAR; PG8_MMA(0, 0, At, B0); PG8_MMA(0, 1, At, B1); PG8_BAR; PG8_SCHED;
	v_mfma_f32_16x16x32_bf16 v[60:63], v[128:131], v[176:179], 0
	v_mfma_f32_16x16x32_bf16 v[56:59], v[146:149], v[176:179], 0
	v_mfma_f32_16x16x32_bf16 v[44:47], v[128:131], v[190:193], 0
	v_mfma_f32_16x16x32_bf16 v[40:43], v[146:149], v[190:193], 0
	v_mfma_f32_16x16x32_bf16 v[28:31], v[128:131], v[198:201], 0
	v_mfma_f32_16x16x32_bf16 v[24:27], v[146:149], v[198:201], 0
	v_mfma_f32_16x16x32_bf16 v[12:15], v[128:131], v[224:227], 0
	v_mfma_f32_16x16x32_bf16 v[8:11], v[146:149], v[224:227], 0
	v_mfma_f32_16x16x32_bf16 v[60:63], v[132:135], v[186:189], v[60:63]
	v_mfma_f32_16x16x32_bf16 v[56:59], v[150:153], v[186:189], v[56:59]
	v_mfma_f32_16x16x32_bf16 v[44:47], v[132:135], v[194:197], v[44:47]
	v_mfma_f32_16x16x32_bf16 v[40:43], v[150:153], v[194:197], v[40:43]
	v_mfma_f32_16x16x32_bf16 v[28:31], v[132:135], v[216:219], v[28:31]
	v_mfma_f32_16x16x32_bf16 v[24:27], v[150:153], v[216:219], v[24:27]
	v_mfma_f32_16x16x32_bf16 v[12:15], v[132:135], v[230:233], v[12:15]
	v_mfma_f32_16x16x32_bf16 v[8:11], v[150:153], v[230:233], v[8:11]
	s_setprio 0
	s_setprio 1
	v_mfma_f32_16x16x32_bf16 v[52:55], v[160:163], v[176:179], 0
	v_mfma_f32_16x16x32_bf16 v[48:51], v[168:171], v[176:179], 0
	v_mfma_f32_16x16x32_bf16 v[36:39], v[160:163], v[190:193], 0
	v_mfma_f32_16x16x32_bf16 v[32:35], v[168:171], v[190:193], 0
	v_mfma_f32_16x16x32_bf16 v[20:23], v[160:163], v[198:201], 0
	v_mfma_f32_16x16x32_bf16 v[16:19], v[168:171], v[198:201], 0
	v_mfma_f32_16x16x32_bf16 v[4:7], v[160:163], v[224:227], 0
	v_mfma_f32_16x16x32_bf16 v[0:3], v[168:171], v[224:227], 0
	v_mfma_f32_16x16x32_bf16 v[52:55], v[164:167], v[186:189], v[52:55]
	v_mfma_f32_16x16x32_bf16 v[48:51], v[172:175], v[186:189], v[48:51]
	v_mfma_f32_16x16x32_bf16 v[36:39], v[164:167], v[194:197], v[36:39]
	v_mfma_f32_16x16x32_bf16 v[32:35], v[172:175], v[194:197], v[32:35]
	v_mfma_f32_16x16x32_bf16 v[20:23], v[164:167], v[216:219], v[20:23]
	v_mfma_f32_16x16x32_bf16 v[16:19], v[172:175], v[216:219], v[16:19]
	v_mfma_f32_16x16x32_bf16 v[4:7], v[164:167], v[230:233], v[4:7]
	v_mfma_f32_16x16x32_bf16 v[0:3], v[172:175], v[230:233], v[0:3]
	s_barrier
	s_setprio 0
	s_add_i32 s68, 0, 0x18000
	s_add_i32 s73, 0, 0x1c000
	v_add_u32_e32 v150, s68, v157
	v_add_u32_e32 v172, s73, v157
	ds_read_b128 v[128:131], v150
	ds_read_b128 v[132:135], v150 offset:1024
	ds_read_b128 v[146:149], v150 offset:2048
	ds_read_b128 v[150:153], v150 offset:3072
	ds_read_b128 v[160:163], v172
	ds_read_b128 v[164:167], v172 offset:1024
	ds_read_b128 v[168:171], v172 offset:2048
	ds_read_b128 v[172:175], v172 offset:3072
	s_add_u32 s50, s60, 0xb0000
	s_addc_u32 s51, s61, 0
	s_mov_b32 m0, s47
	v_lshl_add_u64 v[234:235], s[50:51], 0, v[140:141]
	ds_read_b128 v[176:179], v159 offset:32768
	ds_read_b128 v[186:189], v159 offset:33792
	ds_read_b128 v[190:193], v159 offset:34816
	ds_read_b128 v[194:197], v159 offset:35840
	ds_read_b128 v[198:201], v159 offset:36864
	ds_read_b128 v[216:219], v159 offset:37888
	ds_read_b128 v[224:227], v159 offset:38912
	ds_read_b128 v[230:233], v159 offset:39936
	global_load_lds_dwordx4 v[234:235], off
	v_lshl_add_u64 v[234:235], s[50:51], 0, v[138:139]
	s_mov_b32 m0, s56
	s_nop 0
	global_load_lds_dwordx4 v[234:235], off
	s_waitcnt vmcnt(8)
	s_waitcnt lgkmcnt(0)
	s_setprio 1
	s_barrier
	v_mfma_f32_16x16x32_bf16 v[124:127], v[128:131], v[176:179], v[124:127]
	v_mfma_f32_16x16x32_bf16 v[120:123], v[146:149], v[176:179], v[120:123]
	v_mfma_f32_16x16x32_bf16 v[108:111], v[128:131], v[190:193], v[108:111]
	v_mfma_f32_16x16x32_bf16 v[104:107], v[146:149], v[190:193], v[104:107]
	v_mfma_f32_16x16x32_bf16 v[92:95], v[128:131], v[198:201], v[92:95]
	v_mfma_f32_16x16x32_bf16 v[88:91], v[146:149], v[198:201], v[88:91]
	v_mfma_f32_16x16x32_bf16 v[76:79], v[128:131], v[224:227], v[76:79]
	v_mfma_f32_16x16x32_bf16 v[72:75], v[146:149], v[224:227], v[72:75]
	v_mfma_f32_16x16x32_bf16 v[124:127], v[132:135], v[186:189], v[124:127]
	v_mfma_f32_16x16x32_bf16 v[120:123], v[150:153], v[186:189], v[120:123]
	v_mfma_f32_16x16x32_bf16 v[108:111], v[132:135], v[194:197], v[108:111]
	v_mfma_f32_16x16x32_bf16 v[104:107], v[150:153], v[194:197], v[104:107]
	v_mfma_f32_16x16x32_bf16 v[92:95], v[132:135], v[216:219], v[92:95]
	v_mfma_f32_16x16x32_bf16 v[88:91], v[150:153], v[216:219], v[88:91]
	v_mfma_f32_16x16x32_bf16 v[76:79], v[132:135], v[230:233], v[76:79]
	v_mfma_f32_16x16x32_bf16 v[72:75], v[150:153], v[230:233], v[72:75]
	s_setprio 0
	s_setprio 1
	v_mfma_f32_16x16x32_bf16 v[116:119], v[160:163], v[176:179], v[116:119]
	v_mfma_f32_16x16x32_bf16 v[112:115], v[168:171], v[176:179], v[112:115]
	v_mfma_f32_16x16x32_bf16 v[100:103], v[160:163], v[190:193], v[100:103]
	v_mfma_f32_16x16x32_bf16 v[96:99], v[168:171], v[190:193], v[96:99]
	v_mfma_f32_16x16x32_bf16 v[84:87], v[160:163], v[198:201], v[84:87]
	v_mfma_f32_16x16x32_bf16 v[80:83], v[168:171], v[198:201], v[80:83]
	v_mfma_f32_16x16x32_bf16 v[68:71], v[160:163], v[224:227], v[68:71]
	v_mfma_f32_16x16x32_bf16 v[64:67], v[168:171], v[224:227], v[64:67]
	v_mfma_f32_16x16x32_bf16 v[116:119], v[164:167], v[186:189], v[116:119]
	v_mfma_f32_16x16x32_bf16 v[112:115], v[172:175], v[186:189], v[112:115]
	v_mfma_f32_16x16x32_bf16 v[100:103], v[164:167], v[194:197], v[100:103]
	v_mfma_f32_16x16x32_bf16 v[96:99], v[172:175], v[194:197], v[96:99]
	v_mfma_f32_16x16x32_bf16 v[84:87], v[164:167], v[216:219], v[84:87]
	v_mfma_f32_16x16x32_bf16 v[80:83], v[172:175], v[216:219], v[80:83]
	v_mfma_f32_16x16x32_bf16 v[68:71], v[164:167], v[230:233], v[68:71]
	v_mfma_f32_16x16x32_bf16 v[64:67], v[172:175], v[230:233], v[64:67]
	s_barrier
; #define PG8_STAGE(bufoff, gbase, voff) do { _Pragma("unroll") for (int _i = 0; _i < 2; ++_i) \
;         __builtin_amdgcn_global_load_lds((const unsigned*)((const char*)(gbase) + (voff)[_i]), (PG8_LAS unsigned*)(lds + (bufoff) + ldsw + _i * 8192), 16, 0, 0); } while (0)
; #define PG8_LDA(dst, b, h) do { _Pragma("unroll") for (int m = 0; m < 4; ++m) _Pragma("unroll") for (int k = 0; k < 2; ++k) dst[m][k] = *(const PG8_LAS bf16x8*)(lds + PG8_SA(b, h) + aoff + m * 2048 + k * 1024); } while (0)
; #define PG8_LDB(dst, b, h) do { _Pragma("unroll") for (int n = 0; n < 2; ++n) _Pragma("unroll") for (int k = 0; k < 2; ++k) dst[n][k] = *(const PG8_LAS bf16x8*)(lds + PG8_SB(b, h) + boff + n * 2048 + k * 1024); } while (0)
; #define PG8_MMA(ai, bj, At, Bt) do { __builtin_amdgcn_s_setprio(1); _Pragma("unroll") for (int m = 0; m < 4; ++m) _Pragma("unroll") for (int n = 0; n < 2; ++n) _Pragma("unroll") for (int k = 0; k < 2; ++k) \
;         acc[ai][bj][m][n] = __builtin_amdgcn_mfma_f32_16x16x32_bf16(Bt[n][k], At[m][k], acc[ai][bj][m][n], 0, 0, 0); __builtin_amdgcn_s_setprio(0); } while (0)
; #define PG8_WAIT_V(n) asm volatile("s_waitcnt vmcnt(" #n ")" ::: "memory")
; #define PG8_WAIT_L(n) asm volatile("s_waitcnt lgkmcnt(" #n ")" ::: "memory")
; #define PG8_BAR __builtin_amdgcn_s_barrier()
; #define PG8_SCHED __builtin_amdgcn_sched_barrier(0)
; template <class Epi, class Sched, bool ALIGN_EPI = false, bool SP2 = false>
; __device__ __forceinline__ void gemm_phase(PG8_LAS unsigned char* lds, const Gemm g, const Sched& S, const Epi& E) {
;     ...
;         for (int t = 0; t < nt; t += 2) {
;             const bool last = (t == nt - 2);
;             const char* a1 = cA + (size_t)(t + 1) * kstep;
;             const char* a2 = last ? nA : cA + (size_t)(t + 2) * kstep; const char* b2 = last ? nB : cB + (size_t)(t + 2) * kstep;
;             const char* a3 = a2 + kstep; const char* b3 = b2 + kstep;
;             if (last && has_next) S.a_ready(nxt);
;             if constexpr (SP2) {
;             PG8_LDB(B0, 0, 0); PG8_LDB(B1, 0, 1); PG8_SCHED; PG8_LDA(At, 0, 0); PG8_STAGE(PG8_SA(1, 1), a1 + hstep, voffA);
;     ...
;             PG8_LDA(At, 1, 1); PG8_STAGE(PG8_SB(1, 0), b3, voffB); PG8_STAGE(PG8_SB(1, 1), b3 + hstep, voffB); PG8_STAGE(PG8_SA(1, 0), a3, voffA);
;             PG8_WAIT_V(8); PG8_WAIT_L(0); PG8_BAR; PG8_MMA(1, 0, At, B0); PG8_MMA(1, 1, At, B1); PG8_BAR; PG8_SCHED;
	s_setprio 0
	s_add_i32 s50, s68, s38
	v_lshl_add_u64 v[154:155], v[154:155], 0, s[70:71]
	s_mov_b32 m0, s50
	ds_read_b128 v[176:179], v159 offset:49152
	ds_read_b128 v[186:189], v159 offset:50176
	ds_read_b128 v[190:193], v159 offset:51200
	ds_read_b128 v[194:197], v159 offset:52224
	ds_read_b128 v[198:201], v159 offset:53248
	ds_read_b128 v[216:219], v159 offset:54272
	ds_read_b128 v[224:227], v159 offset:55296
	ds_read_b128 v[230:233], v159 offset:56320
	global_load_lds_dwordx4 v[154:155], off
	s_add_i32 m0, s50, 0x2000
	s_add_u32 s50, s54, 0xb0080
	v_lshl_add_u64 v[154:155], v[202:203], 0, s[70:71]
	s_addc_u32 s51, s55, 0
	s_add_i32 s54, s73, s38
	global_load_lds_dwordx4 v[154:155], off
	v_lshl_add_u64 v[154:155], s[50:51], 0, v[180:181]
	s_mov_b32 m0, s54
	s_nop 0
	global_load_lds_dwordx4 v[154:155], off
	v_lshl_add_u64 v[154:155], s[50:51], 0, v[136:137]
	s_add_i32 m0, s54, 0x2000
	s_nop 0
	global_load_lds_dwordx4 v[154:155], off
	v_lshl_add_u64 v[154:155], v[208:209], 0, s[70:71]
	s_mov_b32 m0, s58
	s_nop 0
	global_load_lds_dwordx4 v[154:155], off
	v_lshl_add_u64 v[154:155], v[220:221], 0, s[70:71]
	s_mov_b32 m0, s59
	s_nop 0
	global_load_lds_dwordx4 v[154:155], off
	s_waitcnt vmcnt(8)
	s_waitcnt lgkmcnt(0)
	s_setprio 1
	s_barrier
	v_mfma_f32_16x16x32_bf16 v[60:63], v[128:131], v[176:179], v[60:63]
	v_mfma_f32_16x16x32_bf16 v[56:59], v[146:149], v[176:179], v[56:59]
	v_mfma_f32_16x16x32_bf16 v[44:47], v[128:131], v[190:193], v[44:47]
	v_mfma_f32_16x16x32_bf16 v[40:43], v[146:149], v[190:193], v[40:43]
	v_mfma_f32_16x16x32_bf16 v[28:31], v[128:131], v[198:201], v[28:31]
	v_mfma_f32_16x16x32_bf16 v[24:27], v[146:149], v[198:201], v[24:27]
	v_mfma_f32_16x16x32_bf16 v[12:15], v[128:131], v[224:227], v[12:15]
	v_mfma_f32_16x16x32_bf16 v[8:11], v[146:149], v[224:227], v[8:11]
	v_mfma_f32_16x16x32_bf16 v[60:63], v[132:135], v[186:189], v[60:63]
	v_mfma_f32_16x16x32_bf16 v[56:59], v[150:153], v[186:189], v[56:59]
	v_mfma_f32_16x16x32_bf16 v[44:47], v[132:135], v[194:197], v[44:47]
	v_mfma_f32_16x16x32_bf16 v[40:43], v[150:153], v[194:197], v[40:43]
	v_mfma_f32_16x16x32_bf16 v[28:31], v[132:135], v[216:219], v[28:31]
	v_mfma_f32_16x16x32_bf16 v[24:27], v[150:153], v[216:219], v[24:27]
	v_mfma_f32_16x16x32_bf16 v[12:15], v[132:135], v[230:233], v[12:15]
	v_mfma_f32_16x16x32_bf16 v[8:11], v[150:153], v[230:233], v[8:11]
	s_setprio 0
	s_setprio 1
	v_mfma_f32_16x16x32_bf16 v[52:55], v[160:163], v[176:179], v[52:55]
	v_mfma_f32_16x16x32_bf16 v[48:51], v[168:171], v[176:179], v[48:51]
	v_mfma_f32_16x16x32_bf16 v[36:39], v[160:163], v[190:193], v[36:39]
	v_mfma_f32_16x16x32_bf16 v[32:35], v[168:171], v[190:193], v[32:35]
	v_mfma_f32_16x16x32_bf16 v[20:23], v[160:163], v[198:201], v[20:23]
	v_mfma_f32_16x16x32_bf16 v[16:19], v[168:171], v[198:201], v[16:19]
	v_mfma_f32_16x16x32_bf16 v[4:7], v[160:163], v[224:227], v[4:7]
	v_mfma_f32_16x16x32_bf16 v[0:3], v[168:171], v[224:227], v[0:3]
	v_mfma_f32_16x16x32_bf16 v[52:55], v[164:167], v[186:189], v[52:55]
	v_mfma_f32_16x16x32_bf16 v[48:51], v[172:175], v[186:189], v[48:51]
	v_mfma_f32_16x16x32_bf16 v[36:39], v[164:167], v[194:197], v[36:39]
	v_mfma_f32_16x16x32_bf16 v[32:35], v[172:175], v[194:197], v[32:35]
	v_mfma_f32_16x16x32_bf16 v[20:23], v[164:167], v[216:219], v[20:23]
	v_mfma_f32_16x16x32_bf16 v[16:19], v[172:175], v[216:219], v[16:19]
	v_mfma_f32_16x16x32_bf16 v[4:7], v[164:167], v[230:233], v[4:7]
	v_mfma_f32_16x16x32_bf16 v[0:3], v[172:175], v[230:233], v[0:3]
	s_barrier
	s_setprio 0
	s_add_i32 s63, s63, 2
	s_add_u32 s23, s23, 0x100
	s_addc_u32 s62, s62, 0
	s_cmp_gt_u32 s63, 41
	s_mov_b64 s[50:51], s[52:53]
.LBB0_274:
	s_add_u32 s52, s50, 0x100
	s_addc_u32 s53, s51, 0
	s_add_i32 s68, 0, 0x10000
	s_cmp_eq_u32 s63, 40
	s_cselect_b32 s61, s11, s53
	s_cselect_b32 s60, s10, s52
	s_cselect_b32 s55, s45, s62
	s_cselect_b32 s54, s44, s23
	s_add_i32 s73, 0, 0x14000
	v_add_u32_e32 v150, s68, v157
	v_add_u32_e32 v154, s73, v157
	ds_read_b128 v[128:131], v150
	ds_read_b128 v[132:135], v150 offset:1024
	ds_read_b128 v[146:149], v150 offset:2048
	ds_read_b128 v[150:153], v150 offset:3072
	ds_read_b128 v[160:163], v154
	ds_read_b128 v[164:167], v154 offset:1024
	ds_read_b128 v[168:171], v154 offset:2048
	ds_read_b128 v[172:175], v154 offset:3072
	v_lshl_add_u64 v[154:155], s[50:51], 0, v[142:143]
	s_add_i32 m0, s39, 0xc000
	ds_read_b128 v[176:179], v159
	ds_read_b128 v[186:189], v159 offset:1024
	ds_read_b128 v[190:193], v159 offset:2048
	ds_read_b128 v[194:197], v159 offset:3072
	ds_read_b128 v[198:201], v159 offset:4096
	ds_read_b128 v[216:219], v159 offset:5120
	ds_read_b128 v[224:227], v159 offset:6144
	ds_read_b128 v[230:233], v159 offset:7168
	global_load_lds_dwordx4 v[154:155], off
	v_lshl_add_u64 v[154:155], s[50:51], 0, v[144:145]
	s_add_i32 m0, s39, 0xe000
	s_nop 0
	global_load_lds_dwordx4 v[154:155], off
	s_waitcnt vmcnt(8)
	s_waitcnt lgkmcnt(0)
	s_setprio 1
	s_barrier
; #define PG8_STAGE(bufoff, gbase, voff) do { _Pragma("unroll") for (int _i = 0; _i < 2; ++_i) \
;         __builtin_amdgcn_global_load_lds((const unsigned*)((const char*)(gbase) + (voff)[_i]), (PG8_LAS unsigned*)(lds + (bufoff) + ldsw + _i * 8192), 16, 0, 0); } while (0)
; #define PG8_LDA(dst, b, h) do { _Pragma("unroll") for (int m = 0; m < 4; ++m) _Pragma("unroll") for (int k = 0; k < 2; ++k) dst[m][k] = *(const PG8_LAS bf16x8*)(lds + PG8_SA(b, h) + aoff + m * 2048 + k * 1024); } while (0)
; #define PG8_MMA(ai, bj, At, Bt) do { __builtin_amdgcn_s_setprio(1); _Pragma("unroll") for (int m = 0; m < 4; ++m) _Pragma("unroll") for (int n = 0; n < 2; ++n) _Pragma("unroll") for (int k = 0; k < 2; ++k) \
;         acc[ai][bj][m][n] = __builtin_amdgcn_mfma_f32_16x16x32_bf16(Bt[n][k], At[m][k], acc[ai][bj][m][n], 0, 0, 0); __builtin_amdgcn_s_setprio(0); } while (0)
; #define PG8_WAIT_V(n) asm volatile("s_waitcnt vmcnt(" #n ")" ::: "memory")
; #define PG8_WAIT_L(n) asm volatile("s_waitcnt lgkmcnt(" #n ")" ::: "memory")
; #define PG8_BAR __builtin_amdgcn_s_barrier()
; #define PG8_SCHED __builtin_amdgcn_sched_barrier(0)
; template <class Epi, class Sched, bool ALIGN_EPI = false, bool SP2 = false>
; __device__ __forceinline__ void gemm_phase(PG8_LAS unsigned char* lds, const Gemm g, const Sched& S, const Epi& E) {
;     ...
;             PG8_WAIT_V(8); PG8_WAIT_L(0); PG8_BAR; PG8_MMA(0, 0, At, B0); PG8_MMA(0, 1, At, B1); PG8_BAR; PG8_SCHED;
;             PG8_LDA(At, 0, 1); PG8_STAGE(PG8_SB(0, 0), b2, voffB); PG8_STAGE(PG8_SB(0, 1), b2 + hstep, voffB); PG8_STAGE(PG8_SA(0, 0), a2, voffA);
;             PG8_WAIT_V(8); PG8_WAIT_L(0); PG8_BAR; PG8_MMA(1, 0, At, B0); PG8_MMA(1, 1, At, B1); PG8_BAR; PG8_SCHED;
	v_mfma_f32_16x16x32_bf16 v[124:127], v[128:131], v[176:179], v[124:127]
	v_mfma_f32_16x16x32_bf16 v[120:123], v[146:149], v[176:179], v[120:123]
	v_mfma_f32_16x16x32_bf16 v[108:111], v[128:131], v[190:193], v[108:111]
	v_mfma_f32_16x16x32_bf16 v[104:107], v[146:149], v[190:193], v[104:107]
	v_mfma_f32_16x16x32_bf16 v[92:95], v[128:131], v[198:201], v[92:95]
	v_mfma_f32_16x16x32_bf16 v[88:91], v[146:149], v[198:201], v[88:91]
	v_mfma_f32_16x16x32_bf16 v[76:79], v[128:131], v[224:227], v[76:79]
	v_mfma_f32_16x16x32_bf16 v[72:75], v[146:149], v[224:227], v[72:75]
	v_mfma_f32_16x16x32_bf16 v[124:127], v[132:135], v[186:189], v[124:127]
	v_mfma_f32_16x16x32_bf16 v[120:123], v[150:153], v[186:189], v[120:123]
	v_mfma_f32_16x16x32_bf16 v[108:111], v[132:135], v[194:197], v[108:111]
	v_mfma_f32_16x16x32_bf16 v[104:107], v[150:153], v[194:197], v[104:107]
	v_mfma_f32_16x16x32_bf16 v[92:95], v[132:135], v[216:219], v[92:95]
	v_mfma_f32_16x16x32_bf16 v[88:91], v[150:153], v[216:219], v[88:91]
	v_mfma_f32_16x16x32_bf16 v[76:79], v[132:135], v[230:233], v[76:79]
	v_mfma_f32_16x16x32_bf16 v[72:75], v[150:153], v[230:233], v[72:75]
	s_setprio 0
	s_setprio 1
	v_mfma_f32_16x16x32_bf16 v[116:119], v[160:163], v[176:179], v[116:119]
	v_mfma_f32_16x16x32_bf16 v[112:115], v[168:171], v[176:179], v[112:115]
	v_mfma_f32_16x16x32_bf16 v[100:103], v[160:163], v[190:193], v[100:103]
	v_mfma_f32_16x16x32_bf16 v[96:99], v[168:171], v[190:193], v[96:99]
	v_mfma_f32_16x16x32_bf16 v[84:87], v[160:163], v[198:201], v[84:87]
	v_mfma_f32_16x16x32_bf16 v[80:83], v[168:171], v[198:201], v[80:83]
	v_mfma_f32_16x16x32_bf16 v[68:71], v[160:163], v[224:227], v[68:71]
	v_mfma_f32_16x16x32_bf16 v[64:67], v[168:171], v[224:227], v[64:67]
	v_mfma_f32_16x16x32_bf16 v[116:119], v[164:167], v[186:189], v[116:119]
	v_mfma_f32_16x16x32_bf16 v[112:115], v[172:175], v[186:189], v[112:115]
	v_mfma_f32_16x16x32_bf16 v[100:103], v[164:167], v[194:197], v[100:103]
	v_mfma_f32_16x16x32_bf16 v[96:99], v[172:175], v[194:197], v[96:99]
	v_mfma_f32_16x16x32_bf16 v[84:87], v[164:167], v[216:219], v[84:87]
	v_mfma_f32_16x16x32_bf16 v[80:83], v[172:175], v[216:219], v[80:83]
	v_mfma_f32_16x16x32_bf16 v[68:71], v[164:167], v[230:233], v[68:71]
	v_mfma_f32_16x16x32_bf16 v[64:67], v[172:175], v[230:233], v[64:67]
	s_barrier
	s_setprio 0
	s_add_i32 s50, s68, s38
	v_lshl_add_u64 v[154:155], s[54:55], 0, v[180:181]
	s_mov_b32 m0, s50
	ds_read_b128 v[176:179], v159 offset:16384
	ds_read_b128 v[186:189], v159 offset:17408
	ds_read_b128 v[190:193], v159 offset:18432
	ds_read_b128 v[194:197], v159 offset:19456
	ds_read_b128 v[198:201], v159 offset:20480
	ds_read_b128 v[216:219], v159 offset:21504
	ds_read_b128 v[224:227], v159 offset:22528
	ds_read_b128 v[230:233], v159 offset:23552
	global_load_lds_dwordx4 v[154:155], off
	s_add_i32 m0, s50, 0x2000
	s_add_u32 s50, s54, 0xb0000
	v_lshl_add_u64 v[202:203], s[54:55], 0, v[136:137]
	s_addc_u32 s51, s55, 0
	s_add_i32 s68, s73, s38
	global_load_lds_dwordx4 v[202:203], off
	v_lshl_add_u64 v[208:209], s[50:51], 0, v[180:181]
	s_mov_b32 m0, s68
	v_lshl_add_u64 v[220:221], s[60:61], 0, v[138:139]
	global_load_lds_dwordx4 v[208:209], off
	v_lshl_add_u64 v[208:209], s[50:51], 0, v[136:137]
	s_add_i32 m0, s68, 0x2000
	s_nop 0
	global_load_lds_dwordx4 v[208:209], off
	v_lshl_add_u64 v[208:209], s[60:61], 0, v[140:141]
	s_mov_b32 m0, s39
	s_nop 0
	global_load_lds_dwordx4 v[208:209], off
	s_mov_b32 m0, s46
	s_nop 0
	global_load_lds_dwordx4 v[220:221], off
	s_waitcnt vmcnt(8)
	s_waitcnt lgkmcnt(0)
	s_setprio 1
	s_barrier
	v_mfma_f32_16x16x32_bf16 v[60:63], v[128:131], v[176:179], v[60:63]
	v_mfma_f32_16x16x32_bf16 v[56:59], v[146:149], v[176:179], v[56:59]
	v_mfma_f32_16x16x32_bf16 v[44:47], v[128:131], v[190:193], v[44:47]
	v_mfma_f32_16x16x32_bf16 v[40:43], v[146:149], v[190:193], v[40:43]
	v_mfma_f32_16x16x32_bf16 v[28:31], v[128:131], v[198:201], v[28:31]
	v_mfma_f32_16x16x32_bf16 v[24:27], v[146:149], v[198:201], v[24:27]
	v_mfma_f32_16x16x32_bf16 v[12:15], v[128:131], v[224:227], v[12:15]
	v_mfma_f32_16x16x32_bf16 v[8:11], v[146:149], v[224:227], v[8:11]
	v_mfma_f32_16x16x32_bf16 v[60:63], v[132:135], v[186:189], v[60:63]
	v_mfma_f32_16x16x32_bf16 v[56:59], v[150:153], v[186:189], v[56:59]
	v_mfma_f32_16x16x32_bf16 v[44:47], v[132:135], v[194:197], v[44:47]
	v_mfma_f32_16x16x32_bf16 v[40:43], v[150:153], v[194:197], v[40:43]
	v_mfma_f32_16x16x32_bf16 v[28:31], v[132:135], v[216:219], v[28:31]
	v_mfma_f32_16x16x32_bf16 v[24:27], v[150:153], v[216:219], v[24:27]
	v_mfma_f32_16x16x32_bf16 v[12:15], v[132:135], v[230:233], v[12:15]
	v_mfma_f32_16x16x32_bf16 v[8:11], v[150:153], v[230:233], v[8:11]
	s_setprio 0
	s_setprio 1
	v_mfma_f32_16x16x32_bf16 v[52:55], v[160:163], v[176:179], v[52:55]
	v_mfma_f32_16x16x32_bf16 v[48:51], v[168:171], v[176:179], v[48:51]
	v_mfma_f32_16x16x32_bf16 v[36:39], v[160:163], v[190:193], v[36:39]
	v_mfma_f32_16x16x32_bf16 v[32:35], v[168:171], v[190:193], v[32:35]
	v_mfma_f32_16x16x32_bf16 v[20:23], v[160:163], v[198:201], v[20:23]
	v_mfma_f32_16x16x32_bf16 v[16:19], v[168:171], v[198:201], v[16:19]
	v_mfma_f32_16x16x32_bf16 v[4:7], v[160:163], v[224:227], v[4:7]
	v_mfma_f32_16x16x32_bf16 v[0:3], v[168:171], v[224:227], v[0:3]
	v_mfma_f32_16x16x32_bf16 v[52:55], v[164:167], v[186:189], v[52:55]
	v_mfma_f32_16x16x32_bf16 v[48:51], v[172:175], v[186:189], v[48:51]
	v_mfma_f32_16x16x32_bf16 v[36:39], v[164:167], v[194:197], v[36:39]
	v_mfma_f32_16x16x32_bf16 v[32:35], v[172:175], v[194:197], v[32:35]
	v_mfma_f32_16x16x32_bf16 v[20:23], v[164:167], v[216:219], v[20:23]
	v_mfma_f32_16x16x32_bf16 v[16:19], v[172:175], v[216:219], v[16:19]
	v_mfma_f32_16x16x32_bf16 v[4:7], v[164:167], v[230:233], v[4:7]
	v_mfma_f32_16x16x32_bf16 v[0:3], v[172:175], v[230:233], v[0:3]
	s_barrier
; #define PG8_STAGE(bufoff, gbase, voff) do { _Pragma("unroll") for (int _i = 0; _i < 2; ++_i) \
;         __builtin_amdgcn_global_load_lds((const unsigned*)((const char*)(gbase) + (voff)[_i]), (PG8_LAS unsigned*)(lds + (bufoff) + ldsw + _i * 8192), 16, 0, 0); } while (0)
; #define PG8_LDA(dst, b, h) do { _Pragma("unroll") for (int m = 0; m < 4; ++m) _Pragma("unroll") for (int k = 0; k < 2; ++k) dst[m][k] = *(const PG8_LAS bf16x8*)(lds + PG8_SA(b, h) + aoff + m * 2048 + k * 1024); } while (0)
; #define PG8_LDB(dst, b, h) do { _Pragma("unroll") for (int n = 0; n < 2; ++n) _Pragma("unroll") for (int k = 0; k < 2; ++k) dst[n][k] = *(const PG8_LAS bf16x8*)(lds + PG8_SB(b, h) + boff + n * 2048 + k * 1024); } while (0)
; #define PG8_MMA(ai, bj, At, Bt) do { __builtin_amdgcn_s_setprio(1); _Pragma("unroll") for (int m = 0; m < 4; ++m) _Pragma("unroll") for (int n = 0; n < 2; ++n) _Pragma("unroll") for (int k = 0; k < 2; ++k) \
;         acc[ai][bj][m][n] = __builtin_amdgcn_mfma_f32_16x16x32_bf16(Bt[n][k], At[m][k], acc[ai][bj][m][n], 0, 0, 0); __builtin_amdgcn_s_setprio(0); } while (0)
; #define PG8_WAIT_V(n) asm volatile("s_waitcnt vmcnt(" #n ")" ::: "memory")
; #define PG8_WAIT_L(n) asm volatile("s_waitcnt lgkmcnt(" #n ")" ::: "memory")
; #define PG8_BAR __builtin_amdgcn_s_barrier()
; #define PG8_SCHED __builtin_amdgcn_sched_barrier(0)
; template <class Epi, class Sched, bool ALIGN_EPI = false, bool SP2 = false>
; __device__ __forceinline__ void gemm_phase(PG8_LAS unsigned char* lds, const Gemm g, const Sched& S, const Epi& E) {
;     ...
;             PG8_LDB(B0, 1, 0); PG8_LDB(B1, 1, 1); PG8_SCHED; PG8_LDA(At, 1, 0); PG8_STAGE(PG8_SA(0, 1), a2 + hstep, voffA);
;             PG8_WAIT_V(8); PG8_WAIT_L(0); PG8_BAR; PG8_MMA(0, 0, At, B0); PG8_MMA(0, 1, At, B1); PG8_BAR; PG8_SCHED;
	s_setprio 0
	s_add_i32 s68, 0, 0x18000
	s_add_i32 s73, 0, 0x1c000
	v_add_u32_e32 v150, s68, v157
	v_add_u32_e32 v172, s73, v157
	ds_read_b128 v[128:131], v150
	ds_read_b128 v[132:135], v150 offset:1024
	ds_read_b128 v[146:149], v150 offset:2048
	ds_read_b128 v[150:153], v150 offset:3072
	ds_read_b128 v[160:163], v172
	ds_read_b128 v[164:167], v172 offset:1024
	ds_read_b128 v[168:171], v172 offset:2048
	ds_read_b128 v[172:175], v172 offset:3072
	s_add_u32 s50, s60, 0xb0000
	s_addc_u32 s51, s61, 0
	s_mov_b32 m0, s47
	v_lshl_add_u64 v[234:235], s[50:51], 0, v[140:141]
	ds_read_b128 v[176:179], v159 offset:32768
	ds_read_b128 v[186:189], v159 offset:33792
	ds_read_b128 v[190:193], v159 offset:34816
	ds_read_b128 v[194:197], v159 offset:35840
	ds_read_b128 v[198:201], v159 offset:36864
	ds_read_b128 v[216:219], v159 offset:37888
	ds_read_b128 v[224:227], v159 offset:38912
	ds_read_b128 v[230:233], v159 offset:39936
	global_load_lds_dwordx4 v[234:235], off
	v_lshl_add_u64 v[234:235], s[50:51], 0, v[138:139]
	s_mov_b32 m0, s56
	s_nop 0
	global_load_lds_dwordx4 v[234:235], off
	s_waitcnt vmcnt(8)
	s_waitcnt lgkmcnt(0)
	s_setprio 1
	s_barrier
	v_mfma_f32_16x16x32_bf16 v[124:127], v[128:131], v[176:179], v[124:127]
	v_mfma_f32_16x16x32_bf16 v[120:123], v[146:149], v[176:179], v[120:123]
	v_mfma_f32_16x16x32_bf16 v[108:111], v[128:131], v[190:193], v[108:111]
	v_mfma_f32_16x16x32_bf16 v[104:107], v[146:149], v[190:193], v[104:107]
	v_mfma_f32_16x16x32_bf16 v[92:95], v[128:131], v[198:201], v[92:95]
	v_mfma_f32_16x16x32_bf16 v[88:91], v[146:149], v[198:201], v[88:91]
	v_mfma_f32_16x16x32_bf16 v[76:79], v[128:131], v[224:227], v[76:79]
	v_mfma_f32_16x16x32_bf16 v[72:75], v[146:149], v[224:227], v[72:75]
	v_mfma_f32_16x16x32_bf16 v[124:127], v[132:135], v[186:189], v[124:127]
	v_mfma_f32_16x16x32_bf16 v[120:123], v[150:153], v[186:189], v[120:123]
	v_mfma_f32_16x16x32_bf16 v[108:111], v[132:135], v[194:197], v[108:111]
	v_mfma_f32_16x16x32_bf16 v[104:107], v[150:153], v[194:197], v[104:107]
	v_mfma_f32_16x16x32_bf16 v[92:95], v[132:135], v[216:219], v[92:95]
	v_mfma_f32_16x16x32_bf16 v[88:91], v[150:153], v[216:219], v[88:91]
	v_mfma_f32_16x16x32_bf16 v[76:79], v[132:135], v[230:233], v[76:79]
	v_mfma_f32_16x16x32_bf16 v[72:75], v[150:153], v[230:233], v[72:75]
	s_setprio 0
	s_setprio 1
	v_mfma_f32_16x16x32_bf16 v[116:119], v[160:163], v[176:179], v[116:119]
	v_mfma_f32_16x16x32_bf16 v[112:115], v[168:171], v[176:179], v[112:115]
	v_mfma_f32_16x16x32_bf16 v[100:103], v[160:163], v[190:193], v[100:103]
	v_mfma_f32_16x16x32_bf16 v[96:99], v[168:171], v[190:193], v[96:99]
	v_mfma_f32_16x16x32_bf16 v[84:87], v[160:163], v[198:201], v[84:87]
	v_mfma_f32_16x16x32_bf16 v[80:83], v[168:171], v[198:201], v[80:83]
	v_mfma_f32_16x16x32_bf16 v[68:71], v[160:163], v[224:227], v[68:71]
	v_mfma_f32_16x16x32_bf16 v[64:67], v[168:171], v[224:227], v[64:67]
	v_mfma_f32_16x16x32_bf16 v[116:119], v[164:167], v[186:189], v[116:119]
	v_mfma_f32_16x16x32_bf16 v[112:115], v[172:175], v[186:189], v[112:115]
	v_mfma_f32_16x16x32_bf16 v[100:103], v[164:167], v[194:197], v[100:103]
	v_mfma_f32_16x16x32_bf16 v[96:99], v[172:175], v[194:197], v[96:99]
	v_mfma_f32_16x16x32_bf16 v[84:87], v[164:167], v[216:219], v[84:87]
	v_mfma_f32_16x16x32_bf16 v[80:83], v[172:175], v[216:219], v[80:83]
	v_mfma_f32_16x16x32_bf16 v[68:71], v[164:167], v[230:233], v[68:71]
	v_mfma_f32_16x16x32_bf16 v[64:67], v[172:175], v[230:233], v[64:67]
	s_barrier
; #define PG8_STAGE(bufoff, gbase, voff) do { _Pragma("unroll") for (int _i = 0; _i < 2; ++_i) \
;         __builtin_amdgcn_global_load_lds((const unsigned*)((const char*)(gbase) + (voff)[_i]), (PG8_LAS unsigned*)(lds + (bufoff) + ldsw + _i * 8192), 16, 0, 0); } while (0)
; #define PG8_LDA(dst, b, h) do { _Pragma("unroll") for (int m = 0; m < 4; ++m) _Pragma("unroll") for (int k = 0; k < 2; ++k) dst[m][k] = *(const PG8_LAS bf16x8*)(lds + PG8_SA(b, h) + aoff + m * 2048 + k * 1024); } while (0)
; #define PG8_MMA(ai, bj, At, Bt) do { __builtin_amdgcn_s_setprio(1); _Pragma("unroll") for (int m = 0; m < 4; ++m) _Pragma("unroll") for (int n = 0; n < 2; ++n) _Pragma("unroll") for (int k = 0; k < 2; ++k) \
;         acc[ai][bj][m][n] = __builtin_amdgcn_mfma_f32_16x16x32_bf16(Bt[n][k], At[m][k], acc[ai][bj][m][n], 0, 0, 0); __builtin_amdgcn_s_setprio(0); } while (0)
; #define PG8_WAIT_V(n) asm volatile("s_waitcnt vmcnt(" #n ")" ::: "memory")
; #define PG8_WAIT_L(n) asm volatile("s_waitcnt lgkmcnt(" #n ")" ::: "memory")
; #define PG8_BAR __builtin_amdgcn_s_barrier()
; #define PG8_SCHED __builtin_amdgcn_sched_barrier(0)
; template <class Epi, class Sched, bool ALIGN_EPI = false, bool SP2 = false>
; __device__ __forceinline__ void gemm_phase(PG8_LAS unsigned char* lds, const Gemm g, const Sched& S, const Epi& E) {
;     ...
;             PG8_LDA(At, 1, 1); PG8_STAGE(PG8_SB(1, 0), b3, voffB); PG8_STAGE(PG8_SB(1, 1), b3 + hstep, voffB); PG8_STAGE(PG8_SA(1, 0), a3, voffA);
;             PG8_WAIT_V(8); PG8_WAIT_L(0); PG8_BAR; PG8_MMA(1, 0, At, B0); PG8_MMA(1, 1, At, B1); PG8_BAR; PG8_SCHED;
;     ...
;         if constexpr (ALIGN_EPI) { if (wr == 0) PG8_BAR; }
	s_setprio 0
	s_add_i32 s50, s68, s38
	v_lshl_add_u64 v[154:155], v[154:155], 0, s[70:71]
	s_mov_b32 m0, s50
	ds_read_b128 v[176:179], v159 offset:49152
	ds_read_b128 v[186:189], v159 offset:50176
	ds_read_b128 v[190:193], v159 offset:51200
	ds_read_b128 v[194:197], v159 offset:52224
	ds_read_b128 v[198:201], v159 offset:53248
	ds_read_b128 v[216:219], v159 offset:54272
	ds_read_b128 v[224:227], v159 offset:55296
	ds_read_b128 v[230:233], v159 offset:56320
	global_load_lds_dwordx4 v[154:155], off
	s_add_i32 m0, s50, 0x2000
	s_add_u32 s50, s54, 0xb0080
	v_lshl_add_u64 v[154:155], v[202:203], 0, s[70:71]
	s_addc_u32 s51, s55, 0
	s_add_i32 s54, s73, s38
	global_load_lds_dwordx4 v[154:155], off
	v_lshl_add_u64 v[154:155], s[50:51], 0, v[180:181]
	s_mov_b32 m0, s54
	s_nop 0
	global_load_lds_dwordx4 v[154:155], off
	v_lshl_add_u64 v[154:155], s[50:51], 0, v[136:137]
	s_add_i32 m0, s54, 0x2000
	s_nop 0
	global_load_lds_dwordx4 v[154:155], off
	v_lshl_add_u64 v[154:155], v[208:209], 0, s[70:71]
	s_mov_b32 m0, s58
	s_nop 0
	global_load_lds_dwordx4 v[154:155], off
	v_lshl_add_u64 v[154:155], v[220:221], 0, s[70:71]
	s_mov_b32 m0, s59
	s_nop 0
	global_load_lds_dwordx4 v[154:155], off
	s_waitcnt vmcnt(8)
	s_waitcnt lgkmcnt(0)
	s_setprio 1
	s_barrier
	v_mfma_f32_16x16x32_bf16 v[60:63], v[128:131], v[176:179], v[60:63]
	v_mfma_f32_16x16x32_bf16 v[56:59], v[146:149], v[176:179], v[56:59]
	v_mfma_f32_16x16x32_bf16 v[44:47], v[128:131], v[190:193], v[44:47]
	v_mfma_f32_16x16x32_bf16 v[40:43], v[146:149], v[190:193], v[40:43]
	v_mfma_f32_16x16x32_bf16 v[28:31], v[128:131], v[198:201], v[28:31]
	v_mfma_f32_16x16x32_bf16 v[24:27], v[146:149], v[198:201], v[24:27]
	v_mfma_f32_16x16x32_bf16 v[12:15], v[128:131], v[224:227], v[12:15]
	v_mfma_f32_16x16x32_bf16 v[8:11], v[146:149], v[224:227], v[8:11]
	v_mfma_f32_16x16x32_bf16 v[60:63], v[132:135], v[186:189], v[60:63]
	v_mfma_f32_16x16x32_bf16 v[56:59], v[150:153], v[186:189], v[56:59]
	v_mfma_f32_16x16x32_bf16 v[44:47], v[132:135], v[194:197], v[44:47]
	v_mfma_f32_16x16x32_bf16 v[40:43], v[150:153], v[194:197], v[40:43]
	v_mfma_f32_16x16x32_bf16 v[28:31], v[132:135], v[216:219], v[28:31]
	v_mfma_f32_16x16x32_bf16 v[24:27], v[150:153], v[216:219], v[24:27]
	v_mfma_f32_16x16x32_bf16 v[12:15], v[132:135], v[230:233], v[12:15]
	v_mfma_f32_16x16x32_bf16 v[8:11], v[150:153], v[230:233], v[8:11]
	s_setprio 0
	s_setprio 1
	v_mfma_f32_16x16x32_bf16 v[52:55], v[160:163], v[176:179], v[52:55]
	v_mfma_f32_16x16x32_bf16 v[48:51], v[168:171], v[176:179], v[48:51]
	v_mfma_f32_16x16x32_bf16 v[36:39], v[160:163], v[190:193], v[36:39]
	v_mfma_f32_16x16x32_bf16 v[32:35], v[168:171], v[190:193], v[32:35]
	v_mfma_f32_16x16x32_bf16 v[20:23], v[160:163], v[198:201], v[20:23]
	v_mfma_f32_16x16x32_bf16 v[16:19], v[168:171], v[198:201], v[16:19]
	v_mfma_f32_16x16x32_bf16 v[4:7], v[160:163], v[224:227], v[4:7]
	v_mfma_f32_16x16x32_bf16 v[0:3], v[168:171], v[224:227], v[0:3]
	v_mfma_f32_16x16x32_bf16 v[52:55], v[164:167], v[186:189], v[52:55]
	v_mfma_f32_16x16x32_bf16 v[48:51], v[172:175], v[186:189], v[48:51]
	v_mfma_f32_16x16x32_bf16 v[36:39], v[164:167], v[194:197], v[36:39]
	v_mfma_f32_16x16x32_bf16 v[32:35], v[172:175], v[194:197], v[32:35]
	v_mfma_f32_16x16x32_bf16 v[20:23], v[164:167], v[216:219], v[20:23]
	v_mfma_f32_16x16x32_bf16 v[16:19], v[172:175], v[216:219], v[16:19]
	v_mfma_f32_16x16x32_bf16 v[4:7], v[164:167], v[230:233], v[4:7]
	v_mfma_f32_16x16x32_bf16 v[0:3], v[172:175], v[230:233], v[0:3]
	s_barrier
	s_setprio 0
	s_add_i32 s63, s63, 2
	s_add_u32 s23, s23, 0x100
	s_addc_u32 s62, s62, 0
	s_cmp_gt_u32 s63, 41
	s_mov_b64 s[50:51], s[52:53]
	s_cbranch_scc0 .LBB0_274
	s_and_b64 vcc, exec, s[42:43]
	s_cbranch_vccz .LBB0_277
	s_barrier

; #define PG8_STAGE(bufoff, gbase, voff) do { _Pragma("unroll") for (int _i = 0; _i < 2; ++_i) \
;         __builtin_amdgcn_global_load_lds((const unsigned*)((const char*)(gbase) + (voff)[_i]), (PG8_LAS unsigned*)(lds + (bufoff) + ldsw + _i * 8192), 16, 0, 0); } while (0)
; #define PG8_LDA(dst, b, h) do { _Pragma("unroll") for (int m = 0; m < 4; ++m) _Pragma("unroll") for (int k = 0; k < 2; ++k) dst[m][k] = *(const PG8_LAS bf16x8*)(lds + PG8_SA(b, h) + aoff + m * 2048 + k * 1024); } while (0)
; #define PG8_LDB(dst, b, h) do { _Pragma("unroll") for (int n = 0; n < 2; ++n) _Pragma("unroll") for (int k = 0; k < 2; ++k) dst[n][k] = *(const PG8_LAS bf16x8*)(lds + PG8_SB(b, h) + boff + n * 2048 + k * 1024); } while (0)
; #define PG8_MMA(ai, bj, At, Bt) do { __builtin_amdgcn_s_setprio(1); _Pragma("unroll") for (int m = 0; m < 4; ++m) _Pragma("unroll") for (int n = 0; n < 2; ++n) _Pragma("unroll") for (int k = 0; k < 2; ++k) \
;         acc[ai][bj][m][n] = __builtin_amdgcn_mfma_f32_16x16x32_bf16(Bt[n][k], At[m][k], acc[ai][bj][m][n], 0, 0, 0); __builtin_amdgcn_s_setprio(0); } while (0)
; #define PG8_BAR __builtin_amdgcn_s_barrier()
; template <class Epi, class Sched, bool ALIGN_EPI = false, bool SP2 = false>
; __device__ __forceinline__ void gemm_phase(PG8_LAS unsigned char* lds, const Gemm g, const Sched& S, const Epi& E) {
;     ...
;         const bool has_next = S.next(ui + 1, nxt);
;         const char* nA = has_next ? (const char*)g.A + (size_t)nxt.pm * tstep : cA; const char* nB = has_next ? (const char*)g.Bt + (size_t)nxt.pn * tstep : cB;
;         for (int t = 0; t < nt; t += 2) {
;             const bool last = (t == nt - 2);
;             const char* a1 = cA + (size_t)(t + 1) * kstep;
;             const char* a2 = last ? nA : cA + (size_t)(t + 2) * kstep; const char* b2 = last ? nB : cB + (size_t)(t + 2) * kstep;
;             const char* a3 = a2 + kstep; const char* b3 = b2 + kstep;
;             if (last && has_next) S.a_ready(nxt);
;             if constexpr (SP2) {
;             PG8_LDB(B0, 0, 0); PG8_LDB(B1, 0, 1); PG8_SCHED; PG8_LDA(At, 0, 0); PG8_STAGE(PG8_SA(1, 1), a1 + hstep, voffA);
;             PG8_WAIT_V(8); PG8_WAIT_L(0); PG8_BAR; PG8_MMA(0, 0, At, B0); PG8_MMA(0, 1, At, B1); PG8_BAR; PG8_SCHED;
;             PG8_LDA(At, 0, 1); PG8_STAGE(PG8_SB(0, 0), b2, voffB); PG8_STAGE(PG8_SB(0, 1), b2 + hstep, voffB); PG8_STAGE(PG8_SA(0, 0), a2, voffA);
.LBB0_359:
	s_ashr_i32 s45, s44, 31
	s_lshl_b64 s[22:23], s[44:45], 19
	s_add_u32 s50, s5, s22
	s_addc_u32 s51, s13, s23
	s_and_b64 s[22:23], s[6:7], exec
	s_cselect_b32 s22, s51, s9
	s_cselect_b32 s23, s50, s8
	s_ashr_i32 s43, s42, 31
	s_lshl_b64 s[52:53], s[42:43], 19
	s_add_u32 s52, s38, s52
	s_addc_u32 s53, s39, s53
	s_and_b64 s[60:61], s[6:7], exec
	s_cselect_b32 s43, s53, s55
	s_cselect_b32 s45, s52, s54
	s_add_u32 s8, s8, 0x40080
	s_addc_u32 s9, s9, 0
	s_add_u32 s62, s54, 0x100
	s_addc_u32 s63, s55, 0
	s_mov_b32 s73, -2
	s_add_u32 s54, s8, 0xfffc0080
	s_addc_u32 s55, s9, -1
	s_add_i32 s76, 0, 0x10000
	s_cmp_eq_u32 s73, 12
	s_cselect_b32 s61, s22, s55
	s_cselect_b32 s60, s23, s54
	s_cselect_b32 s55, s43, s63
	s_cselect_b32 s54, s45, s62
	s_add_i32 s92, 0, 0x14000
	v_add_u32_e32 v140, s76, v217
	v_add_u32_e32 v156, s92, v217
	ds_read_b128 v[128:131], v140
	ds_read_b128 v[132:135], v140 offset:1024
	ds_read_b128 v[136:139], v140 offset:2048
	ds_read_b128 v[140:143], v140 offset:3072
	ds_read_b128 v[144:147], v156
	ds_read_b128 v[148:151], v156 offset:1024
	ds_read_b128 v[152:155], v156 offset:2048
	ds_read_b128 v[156:159], v156 offset:3072
	v_lshl_add_u64 v[202:203], s[8:9], 0, v[176:177]
	s_add_i32 m0, s47, 0xc000
	ds_read_b128 v[160:163], v219
	ds_read_b128 v[164:167], v219 offset:1024
	ds_read_b128 v[186:189], v219 offset:2048
	ds_read_b128 v[190:193], v219 offset:3072
	ds_read_b128 v[194:197], v219 offset:4096
	ds_read_b128 v[198:201], v219 offset:5120
	ds_read_b128 v[224:227], v219 offset:6144
	ds_read_b128 v[230:233], v219 offset:7168
	global_load_lds_dwordx4 v[202:203], off
	v_lshl_add_u64 v[202:203], s[8:9], 0, v[178:179]
	s_add_i32 m0, s47, 0xe000
	s_nop 0
	global_load_lds_dwordx4 v[202:203], off
	s_waitcnt vmcnt(8)
	s_waitcnt lgkmcnt(0)
	s_setprio 1
	s_barrier
	v_mfma_f32_16x16x32_bf16 v[124:127], v[128:131], v[160:163], 0
	v_mfma_f32_16x16x32_bf16 v[120:123], v[136:139], v[160:163], 0
	v_mfma_f32_16x16x32_bf16 v[112:115], v[128:131], v[186:189], 0
	v_mfma_f32_16x16x32_bf16 v[104:107], v[136:139], v[186:189], 0
	v_mfma_f32_16x16x32_bf16 v[96:99], v[128:131], v[194:197], 0
	v_mfma_f32_16x16x32_bf16 v[88:91], v[136:139], v[194:197], 0
	v_mfma_f32_16x16x32_bf16 v[80:83], v[128:131], v[224:227], 0
	v_mfma_f32_16x16x32_bf16 v[72:75], v[136:139], v[224:227], 0
	v_mfma_f32_16x16x32_bf16 v[124:127], v[132:135], v[164:167], v[124:127]
	v_mfma_f32_16x16x32_bf16 v[120:123], v[140:143], v[164:167], v[120:123]
	v_mfma_f32_16x16x32_bf16 v[112:115], v[132:135], v[190:193], v[112:115]
	v_mfma_f32_16x16x32_bf16 v[104:107], v[140:143], v[190:193], v[104:107]
	v_mfma_f32_16x16x32_bf16 v[96:99], v[132:135], v[198:201], v[96:99]
	v_mfma_f32_16x16x32_bf16 v[88:91], v[140:143], v[198:201], v[88:91]
	v_mfma_f32_16x16x32_bf16 v[80:83], v[132:135], v[230:233], v[80:83]
	v_mfma_f32_16x16x32_bf16 v[72:75], v[140:143], v[230:233], v[72:75]
	s_setprio 0
	s_setprio 1
	v_mfma_f32_16x16x32_bf16 v[116:119], v[144:147], v[160:163], 0
	v_mfma_f32_16x16x32_bf16 v[108:111], v[152:155], v[160:163], 0
	v_mfma_f32_16x16x32_bf16 v[100:103], v[144:147], v[186:189], 0
	v_mfma_f32_16x16x32_bf16 v[92:95], v[152:155], v[186:189], 0
	v_mfma_f32_16x16x32_bf16 v[84:87], v[144:147], v[194:197], 0
	v_mfma_f32_16x16x32_bf16 v[76:79], v[152:155], v[194:197], 0
	v_mfma_f32_16x16x32_bf16 v[68:71], v[144:147], v[224:227], 0
	v_mfma_f32_16x16x32_bf16 v[64:67], v[152:155], v[224:227], 0
	v_mfma_f32_16x16x32_bf16 v[116:119], v[148:151], v[164:167], v[116:119]
	v_mfma_f32_16x16x32_bf16 v[108:111], v[156:159], v[164:167], v[108:111]
	v_mfma_f32_16x16x32_bf16 v[100:103], v[148:151], v[190:193], v[100:103]
	v_mfma_f32_16x16x32_bf16 v[92:95], v[156:159], v[190:193], v[92:95]
	v_mfma_f32_16x16x32_bf16 v[84:87], v[148:151], v[198:201], v[84:87]
	v_mfma_f32_16x16x32_bf16 v[76:79], v[156:159], v[198:201], v[76:79]
	v_mfma_f32_16x16x32_bf16 v[68:71], v[148:151], v[230:233], v[68:71]
	v_mfma_f32_16x16x32_bf16 v[64:67], v[156:159], v[230:233], v[64:67]
	s_barrier
	s_setprio 0
	s_add_i32 s76, s76, s46
	v_lshl_add_u64 v[202:203], s[54:55], 0, v[180:181]
	s_mov_b32 m0, s76
	ds_read_b128 v[160:163], v219 offset:16384
	ds_read_b128 v[164:167], v219 offset:17408
	ds_read_b128 v[186:189], v219 offset:18432
	ds_read_b128 v[190:193], v219 offset:19456
	ds_read_b128 v[194:197], v219 offset:20480
	ds_read_b128 v[198:201], v219 offset:21504
	ds_read_b128 v[224:227], v219 offset:22528
	ds_read_b128 v[230:233], v219 offset:23552
	global_load_lds_dwordx4 v[202:203], off
	s_add_i32 m0, s76, 0x2000
	s_add_u32 s76, s54, 0x40000
	v_lshl_add_u64 v[208:209], s[54:55], 0, v[168:169]
	s_addc_u32 s77, s55, 0
	s_add_i32 s92, s92, s46
	global_load_lds_dwordx4 v[208:209], off
	v_lshl_add_u64 v[220:221], s[76:77], 0, v[180:181]
	s_mov_b32 m0, s92
	v_lshl_add_u64 v[234:235], s[60:61], 0, v[170:171]
	global_load_lds_dwordx4 v[220:221], off
	v_lshl_add_u64 v[220:221], s[76:77], 0, v[168:169]
	s_add_i32 m0, s92, 0x2000
	s_nop 0
	global_load_lds_dwordx4 v[220:221], off
	v_lshl_add_u64 v[220:221], s[60:61], 0, v[172:173]
	s_mov_b32 m0, s47
	s_nop 0
	global_load_lds_dwordx4 v[220:221], off
	s_mov_b32 m0, s56
	s_nop 0
	global_load_lds_dwordx4 v[234:235], off
	s_waitcnt vmcnt(8)
	s_waitcnt lgkmcnt(0)
	s_setprio 1
	s_barrier
; #define PG8_STAGE(bufoff, gbase, voff) do { _Pragma("unroll") for (int _i = 0; _i < 2; ++_i) \
;         __builtin_amdgcn_global_load_lds((const unsigned*)((const char*)(gbase) + (voff)[_i]), (PG8_LAS unsigned*)(lds + (bufoff) + ldsw + _i * 8192), 16, 0, 0); } while (0)
; #define PG8_LDA(dst, b, h) do { _Pragma("unroll") for (int m = 0; m < 4; ++m) _Pragma("unroll") for (int k = 0; k < 2; ++k) dst[m][k] = *(const PG8_LAS bf16x8*)(lds + PG8_SA(b, h) + aoff + m * 2048 + k * 1024); } while (0)
; #define PG8_LDB(dst, b, h) do { _Pragma("unroll") for (int n = 0; n < 2; ++n) _Pragma("unroll") for (int k = 0; k < 2; ++k) dst[n][k] = *(const PG8_LAS bf16x8*)(lds + PG8_SB(b, h) + boff + n * 2048 + k * 1024); } while (0)
; #define PG8_MMA(ai, bj, At, Bt) do { __builtin_amdgcn_s_setprio(1); _Pragma("unroll") for (int m = 0; m < 4; ++m) _Pragma("unroll") for (int n = 0; n < 2; ++n) _Pragma("unroll") for (int k = 0; k < 2; ++k) \
;         acc[ai][bj][m][n] = __builtin_amdgcn_mfma_f32_16x16x32_bf16(Bt[n][k], At[m][k], acc[ai][bj][m][n], 0, 0, 0); __builtin_amdgcn_s_setprio(0); } while (0)
; #define PG8_WAIT_V(n) asm volatile("s_waitcnt vmcnt(" #n ")" ::: "memory")
; #define PG8_WAIT_L(n) asm volatile("s_waitcnt lgkmcnt(" #n ")" ::: "memory")
; #define PG8_BAR __builtin_amdgcn_s_barrier()
; #define PG8_SCHED __builtin_amdgcn_sched_barrier(0)
; template <class Epi, class Sched, bool ALIGN_EPI = false, bool SP2 = false>
; __device__ __forceinline__ void gemm_phase(PG8_LAS unsigned char* lds, const Gemm g, const Sched& S, const Epi& E) {
;     ...
;             PG8_WAIT_V(8); PG8_WAIT_L(0); PG8_BAR; PG8_MMA(1, 0, At, B0); PG8_MMA(1, 1, At, B1); PG8_BAR; PG8_SCHED;
;             PG8_LDB(B0, 1, 0); PG8_LDB(B1, 1, 1); PG8_SCHED; PG8_LDA(At, 1, 0); PG8_STAGE(PG8_SA(0, 1), a2 + hstep, voffA);
;             PG8_WAIT_V(8); PG8_WAIT_L(0); PG8_BAR; PG8_MMA(0, 0, At, B0); PG8_MMA(0, 1, At, B1); PG8_BAR; PG8_SCHED;
	v_mfma_f32_16x16x32_bf16 v[60:63], v[128:131], v[160:163], 0
	v_mfma_f32_16x16x32_bf16 v[56:59], v[136:139], v[160:163], 0
	v_mfma_f32_16x16x32_bf16 v[48:51], v[128:131], v[186:189], 0
	v_mfma_f32_16x16x32_bf16 v[40:43], v[136:139], v[186:189], 0
	v_mfma_f32_16x16x32_bf16 v[32:35], v[128:131], v[194:197], 0
	v_mfma_f32_16x16x32_bf16 v[24:27], v[136:139], v[194:197], 0
	v_mfma_f32_16x16x32_bf16 v[16:19], v[128:131], v[224:227], 0
	v_mfma_f32_16x16x32_bf16 v[8:11], v[136:139], v[224:227], 0
	v_mfma_f32_16x16x32_bf16 v[60:63], v[132:135], v[164:167], v[60:63]
	v_mfma_f32_16x16x32_bf16 v[56:59], v[140:143], v[164:167], v[56:59]
	v_mfma_f32_16x16x32_bf16 v[48:51], v[132:135], v[190:193], v[48:51]
	v_mfma_f32_16x16x32_bf16 v[40:43], v[140:143], v[190:193], v[40:43]
	v_mfma_f32_16x16x32_bf16 v[32:35], v[132:135], v[198:201], v[32:35]
	v_mfma_f32_16x16x32_bf16 v[24:27], v[140:143], v[198:201], v[24:27]
	v_mfma_f32_16x16x32_bf16 v[16:19], v[132:135], v[230:233], v[16:19]
	v_mfma_f32_16x16x32_bf16 v[8:11], v[140:143], v[230:233], v[8:11]
	s_setprio 0
	s_setprio 1
	v_mfma_f32_16x16x32_bf16 v[52:55], v[144:147], v[160:163], 0
	v_mfma_f32_16x16x32_bf16 v[44:47], v[152:155], v[160:163], 0
	v_mfma_f32_16x16x32_bf16 v[36:39], v[144:147], v[186:189], 0
	v_mfma_f32_16x16x32_bf16 v[28:31], v[152:155], v[186:189], 0
	v_mfma_f32_16x16x32_bf16 v[20:23], v[144:147], v[194:197], 0
	v_mfma_f32_16x16x32_bf16 v[12:15], v[152:155], v[194:197], 0
	v_mfma_f32_16x16x32_bf16 v[4:7], v[144:147], v[224:227], 0
	v_mfma_f32_16x16x32_bf16 v[0:3], v[152:155], v[224:227], 0
	v_mfma_f32_16x16x32_bf16 v[52:55], v[148:151], v[164:167], v[52:55]
	v_mfma_f32_16x16x32_bf16 v[44:47], v[156:159], v[164:167], v[44:47]
	v_mfma_f32_16x16x32_bf16 v[36:39], v[148:151], v[190:193], v[36:39]
	v_mfma_f32_16x16x32_bf16 v[28:31], v[156:159], v[190:193], v[28:31]
	v_mfma_f32_16x16x32_bf16 v[20:23], v[148:151], v[198:201], v[20:23]
	v_mfma_f32_16x16x32_bf16 v[12:15], v[156:159], v[198:201], v[12:15]
	v_mfma_f32_16x16x32_bf16 v[4:7], v[148:151], v[230:233], v[4:7]
	v_mfma_f32_16x16x32_bf16 v[0:3], v[156:159], v[230:233], v[0:3]
	s_barrier
	s_setprio 0
	s_add_i32 s76, 0, 0x18000
	s_add_i32 s77, 0, 0x1c000
	v_add_u32_e32 v140, s76, v217
	v_add_u32_e32 v156, s77, v217
	ds_read_b128 v[128:131], v140
	ds_read_b128 v[132:135], v140 offset:1024
	ds_read_b128 v[136:139], v140 offset:2048
	ds_read_b128 v[140:143], v140 offset:3072
	ds_read_b128 v[144:147], v156
	ds_read_b128 v[148:151], v156 offset:1024
	ds_read_b128 v[152:155], v156 offset:2048
	ds_read_b128 v[156:159], v156 offset:3072
	s_add_u32 s60, s60, 0x40000
	s_addc_u32 s61, s61, 0
	s_mov_b32 m0, s57
	v_lshl_add_u64 v[236:237], s[60:61], 0, v[172:173]
	ds_read_b128 v[160:163], v219 offset:32768
	ds_read_b128 v[164:167], v219 offset:33792
	ds_read_b128 v[186:189], v219 offset:34816
	ds_read_b128 v[190:193], v219 offset:35840
	ds_read_b128 v[194:197], v219 offset:36864
	ds_read_b128 v[198:201], v219 offset:37888
	ds_read_b128 v[224:227], v219 offset:38912
	ds_read_b128 v[230:233], v219 offset:39936
	global_load_lds_dwordx4 v[236:237], off
	v_lshl_add_u64 v[236:237], s[60:61], 0, v[170:171]
	s_mov_b32 m0, s58
	s_nop 0
	global_load_lds_dwordx4 v[236:237], off
	s_waitcnt vmcnt(8)
	s_waitcnt lgkmcnt(0)
	s_setprio 1
	s_barrier
	v_mfma_f32_16x16x32_bf16 v[124:127], v[128:131], v[160:163], v[124:127]
	v_mfma_f32_16x16x32_bf16 v[120:123], v[136:139], v[160:163], v[120:123]
	v_mfma_f32_16x16x32_bf16 v[112:115], v[128:131], v[186:189], v[112:115]
	v_mfma_f32_16x16x32_bf16 v[104:107], v[136:139], v[186:189], v[104:107]
	v_mfma_f32_16x16x32_bf16 v[96:99], v[128:131], v[194:197], v[96:99]
	v_mfma_f32_16x16x32_bf16 v[88:91], v[136:139], v[194:197], v[88:91]
	v_mfma_f32_16x16x32_bf16 v[80:83], v[128:131], v[224:227], v[80:83]
	v_mfma_f32_16x16x32_bf16 v[72:75], v[136:139], v[224:227], v[72:75]
	v_mfma_f32_16x16x32_bf16 v[124:127], v[132:135], v[164:167], v[124:127]
	v_mfma_f32_16x16x32_bf16 v[120:123], v[140:143], v[164:167], v[120:123]
	v_mfma_f32_16x16x32_bf16 v[112:115], v[132:135], v[190:193], v[112:115]
	v_mfma_f32_16x16x32_bf16 v[104:107], v[140:143], v[190:193], v[104:107]
	v_mfma_f32_16x16x32_bf16 v[96:99], v[132:135], v[198:201], v[96:99]
	v_mfma_f32_16x16x32_bf16 v[88:91], v[140:143], v[198:201], v[88:91]
	v_mfma_f32_16x16x32_bf16 v[80:83], v[132:135], v[230:233], v[80:83]
	v_mfma_f32_16x16x32_bf16 v[72:75], v[140:143], v[230:233], v[72:75]
	s_setprio 0
	s_setprio 1
	v_mfma_f32_16x16x32_bf16 v[116:119], v[144:147], v[160:163], v[116:119]
	v_mfma_f32_16x16x32_bf16 v[108:111], v[152:155], v[160:163], v[108:111]
	v_mfma_f32_16x16x32_bf16 v[100:103], v[144:147], v[186:189], v[100:103]
	v_mfma_f32_16x16x32_bf16 v[92:95], v[152:155], v[186:189], v[92:95]
	v_mfma_f32_16x16x32_bf16 v[84:87], v[144:147], v[194:197], v[84:87]
	v_mfma_f32_16x16x32_bf16 v[76:79], v[152:155], v[194:197], v[76:79]
	v_mfma_f32_16x16x32_bf16 v[68:71], v[144:147], v[224:227], v[68:71]
	v_mfma_f32_16x16x32_bf16 v[64:67], v[152:155], v[224:227], v[64:67]
	v_mfma_f32_16x16x32_bf16 v[116:119], v[148:151], v[164:167], v[116:119]
	v_mfma_f32_16x16x32_bf16 v[108:111], v[156:159], v[164:167], v[108:111]
	v_mfma_f32_16x16x32_bf16 v[100:103], v[148:151], v[190:193], v[100:103]
	v_mfma_f32_16x16x32_bf16 v[92:95], v[156:159], v[190:193], v[92:95]
	v_mfma_f32_16x16x32_bf16 v[84:87], v[148:151], v[198:201], v[84:87]
	v_mfma_f32_16x16x32_bf16 v[76:79], v[156:159], v[198:201], v[76:79]
	v_mfma_f32_16x16x32_bf16 v[68:71], v[148:151], v[230:233], v[68:71]
	v_mfma_f32_16x16x32_bf16 v[64:67], v[156:159], v[230:233], v[64:67]
	s_barrier
; #define PG8_STAGE(bufoff, gbase, voff) do { _Pragma("unroll") for (int _i = 0; _i < 2; ++_i) \
;         __builtin_amdgcn_global_load_lds((const unsigned*)((const char*)(gbase) + (voff)[_i]), (PG8_LAS unsigned*)(lds + (bufoff) + ldsw + _i * 8192), 16, 0, 0); } while (0)
; #define PG8_LDA(dst, b, h) do { _Pragma("unroll") for (int m = 0; m < 4; ++m) _Pragma("unroll") for (int k = 0; k < 2; ++k) dst[m][k] = *(const PG8_LAS bf16x8*)(lds + PG8_SA(b, h) + aoff + m * 2048 + k * 1024); } while (0)
; #define PG8_LDB(dst, b, h) do { _Pragma("unroll") for (int n = 0; n < 2; ++n) _Pragma("unroll") for (int k = 0; k < 2; ++k) dst[n][k] = *(const PG8_LAS bf16x8*)(lds + PG8_SB(b, h) + boff + n * 2048 + k * 1024); } while (0)
; #define PG8_MMA(ai, bj, At, Bt) do { __builtin_amdgcn_s_setprio(1); _Pragma("unroll") for (int m = 0; m < 4; ++m) _Pragma("unroll") for (int n = 0; n < 2; ++n) _Pragma("unroll") for (int k = 0; k < 2; ++k) \
;         acc[ai][bj][m][n] = __builtin_amdgcn_mfma_f32_16x16x32_bf16(Bt[n][k], At[m][k], acc[ai][bj][m][n], 0, 0, 0); __builtin_amdgcn_s_setprio(0); } while (0)
; #define PG8_WAIT_V(n) asm volatile("s_waitcnt vmcnt(" #n ")" ::: "memory")
; #define PG8_WAIT_L(n) asm volatile("s_waitcnt lgkmcnt(" #n ")" ::: "memory")
; #define PG8_BAR __builtin_amdgcn_s_barrier()
; #define PG8_SCHED __builtin_amdgcn_sched_barrier(0)
; template <class Epi, class Sched, bool ALIGN_EPI = false, bool SP2 = false>
; __device__ __forceinline__ void gemm_phase(PG8_LAS unsigned char* lds, const Gemm g, const Sched& S, const Epi& E) {
;     ...
;         for (int t = 0; t < nt; t += 2) {
;             const bool last = (t == nt - 2);
;             const char* a1 = cA + (size_t)(t + 1) * kstep;
;             const char* a2 = last ? nA : cA + (size_t)(t + 2) * kstep; const char* b2 = last ? nB : cB + (size_t)(t + 2) * kstep;
;             const char* a3 = a2 + kstep; const char* b3 = b2 + kstep;
;             if (last && has_next) S.a_ready(nxt);
;             if constexpr (SP2) {
;             PG8_LDB(B0, 0, 0); PG8_LDB(B1, 0, 1); PG8_SCHED; PG8_LDA(At, 0, 0); PG8_STAGE(PG8_SA(1, 1), a1 + hstep, voffA);
;     ...
;             PG8_LDA(At, 1, 1); PG8_STAGE(PG8_SB(1, 0), b3, voffB); PG8_STAGE(PG8_SB(1, 1), b3 + hstep, voffB); PG8_STAGE(PG8_SA(1, 0), a3, voffA);
;             PG8_WAIT_V(8); PG8_WAIT_L(0); PG8_BAR; PG8_MMA(1, 0, At, B0); PG8_MMA(1, 1, At, B1); PG8_BAR; PG8_SCHED;
	s_setprio 0
	s_add_i32 s60, s76, s46
	v_lshl_add_u64 v[202:203], v[202:203], 0, s[70:71]
	s_mov_b32 m0, s60
	ds_read_b128 v[160:163], v219 offset:49152
	ds_read_b128 v[164:167], v219 offset:50176
	ds_read_b128 v[186:189], v219 offset:51200
	ds_read_b128 v[190:193], v219 offset:52224
	ds_read_b128 v[194:197], v219 offset:53248
	ds_read_b128 v[198:201], v219 offset:54272
	ds_read_b128 v[224:227], v219 offset:55296
	ds_read_b128 v[230:233], v219 offset:56320
	global_load_lds_dwordx4 v[202:203], off
	s_add_i32 m0, s60, 0x2000
	s_add_u32 s54, s54, 0x40080
	v_lshl_add_u64 v[202:203], v[208:209], 0, s[70:71]
	s_addc_u32 s55, s55, 0
	s_add_i32 s60, s77, s46
	global_load_lds_dwordx4 v[202:203], off
	v_lshl_add_u64 v[202:203], s[54:55], 0, v[180:181]
	s_mov_b32 m0, s60
	s_nop 0
	global_load_lds_dwordx4 v[202:203], off
	v_lshl_add_u64 v[202:203], s[54:55], 0, v[168:169]
	s_add_i32 m0, s60, 0x2000
	s_nop 0
	global_load_lds_dwordx4 v[202:203], off
	v_lshl_add_u64 v[202:203], v[220:221], 0, s[70:71]
	s_mov_b32 m0, s59
	s_nop 0
	global_load_lds_dwordx4 v[202:203], off
	v_lshl_add_u64 v[202:203], v[234:235], 0, s[70:71]
	s_mov_b32 m0, s68
	s_nop 0
	global_load_lds_dwordx4 v[202:203], off
	s_waitcnt vmcnt(8)
	s_waitcnt lgkmcnt(0)
	s_setprio 1
	s_barrier
	v_mfma_f32_16x16x32_bf16 v[60:63], v[128:131], v[160:163], v[60:63]
	v_mfma_f32_16x16x32_bf16 v[56:59], v[136:139], v[160:163], v[56:59]
	v_mfma_f32_16x16x32_bf16 v[48:51], v[128:131], v[186:189], v[48:51]
	v_mfma_f32_16x16x32_bf16 v[40:43], v[136:139], v[186:189], v[40:43]
	v_mfma_f32_16x16x32_bf16 v[32:35], v[128:131], v[194:197], v[32:35]
	v_mfma_f32_16x16x32_bf16 v[24:27], v[136:139], v[194:197], v[24:27]
	v_mfma_f32_16x16x32_bf16 v[16:19], v[128:131], v[224:227], v[16:19]
	v_mfma_f32_16x16x32_bf16 v[8:11], v[136:139], v[224:227], v[8:11]
	v_mfma_f32_16x16x32_bf16 v[60:63], v[132:135], v[164:167], v[60:63]
	v_mfma_f32_16x16x32_bf16 v[56:59], v[140:143], v[164:167], v[56:59]
	v_mfma_f32_16x16x32_bf16 v[48:51], v[132:135], v[190:193], v[48:51]
	v_mfma_f32_16x16x32_bf16 v[40:43], v[140:143], v[190:193], v[40:43]
	v_mfma_f32_16x16x32_bf16 v[32:35], v[132:135], v[198:201], v[32:35]
	v_mfma_f32_16x16x32_bf16 v[24:27], v[140:143], v[198:201], v[24:27]
	v_mfma_f32_16x16x32_bf16 v[16:19], v[132:135], v[230:233], v[16:19]
	v_mfma_f32_16x16x32_bf16 v[8:11], v[140:143], v[230:233], v[8:11]
	s_setprio 0
	s_setprio 1
	v_mfma_f32_16x16x32_bf16 v[52:55], v[144:147], v[160:163], v[52:55]
	v_mfma_f32_16x16x32_bf16 v[44:47], v[152:155], v[160:163], v[44:47]
	v_mfma_f32_16x16x32_bf16 v[36:39], v[144:147], v[186:189], v[36:39]
	v_mfma_f32_16x16x32_bf16 v[28:31], v[152:155], v[186:189], v[28:31]
	v_mfma_f32_16x16x32_bf16 v[20:23], v[144:147], v[194:197], v[20:23]
	v_mfma_f32_16x16x32_bf16 v[12:15], v[152:155], v[194:197], v[12:15]
	v_mfma_f32_16x16x32_bf16 v[4:7], v[144:147], v[224:227], v[4:7]
	v_mfma_f32_16x16x32_bf16 v[0:3], v[152:155], v[224:227], v[0:3]
	v_mfma_f32_16x16x32_bf16 v[52:55], v[148:151], v[164:167], v[52:55]
	v_mfma_f32_16x16x32_bf16 v[44:47], v[156:159], v[164:167], v[44:47]
	v_mfma_f32_16x16x32_bf16 v[36:39], v[148:151], v[190:193], v[36:39]
	v_mfma_f32_16x16x32_bf16 v[28:31], v[156:159], v[190:193], v[28:31]
	v_mfma_f32_16x16x32_bf16 v[20:23], v[148:151], v[198:201], v[20:23]
	v_mfma_f32_16x16x32_bf16 v[12:15], v[156:159], v[198:201], v[12:15]
	v_mfma_f32_16x16x32_bf16 v[4:7], v[148:151], v[230:233], v[4:7]
	v_mfma_f32_16x16x32_bf16 v[0:3], v[156:159], v[230:233], v[0:3]
	s_barrier
	s_setprio 0
	s_add_i32 s73, s73, 2
	s_add_u32 s8, s8, 0x100
	s_addc_u32 s9, s9, 0
	s_add_u32 s62, s62, 0x100
	s_addc_u32 s63, s63, 0
	s_cmp_gt_u32 s73, 13
.LBB0_360:
	s_add_u32 s54, s8, 0xfffc0080
	s_addc_u32 s55, s9, -1
	s_add_i32 s76, 0, 0x10000
	s_cmp_eq_u32 s73, 12
	s_cselect_b32 s61, s22, s55
	s_cselect_b32 s60, s23, s54
	s_cselect_b32 s55, s43, s63
	s_cselect_b32 s54, s45, s62
	s_add_i32 s92, 0, 0x14000
	v_add_u32_e32 v140, s76, v217
	v_add_u32_e32 v156, s92, v217
	ds_read_b128 v[128:131], v140
	ds_read_b128 v[132:135], v140 offset:1024
	ds_read_b128 v[136:139], v140 offset:2048
	ds_read_b128 v[140:143], v140 offset:3072
	ds_read_b128 v[144:147], v156
	ds_read_b128 v[148:151], v156 offset:1024
	ds_read_b128 v[152:155], v156 offset:2048
	ds_read_b128 v[156:159], v156 offset:3072
	v_lshl_add_u64 v[202:203], s[8:9], 0, v[176:177]
	s_add_i32 m0, s47, 0xc000
	ds_read_b128 v[160:163], v219
	ds_read_b128 v[164:167], v219 offset:1024
	ds_read_b128 v[186:189], v219 offset:2048
	ds_read_b128 v[190:193], v219 offset:3072
	ds_read_b128 v[194:197], v219 offset:4096
	ds_read_b128 v[198:201], v219 offset:5120
	ds_read_b128 v[224:227], v219 offset:6144
	ds_read_b128 v[230:233], v219 offset:7168
	global_load_lds_dwordx4 v[202:203], off
	v_lshl_add_u64 v[202:203], s[8:9], 0, v[178:179]
	s_add_i32 m0, s47, 0xe000
	s_nop 0
	global_load_lds_dwordx4 v[202:203], off
	s_waitcnt vmcnt(8)
	s_waitcnt lgkmcnt(0)
	s_setprio 1
	s_barrier
; #define PG8_STAGE(bufoff, gbase, voff) do { _Pragma("unroll") for (int _i = 0; _i < 2; ++_i) \
;         __builtin_amdgcn_global_load_lds((const unsigned*)((const char*)(gbase) + (voff)[_i]), (PG8_LAS unsigned*)(lds + (bufoff) + ldsw + _i * 8192), 16, 0, 0); } while (0)
; #define PG8_LDA(dst, b, h) do { _Pragma("unroll") for (int m = 0; m < 4; ++m) _Pragma("unroll") for (int k = 0; k < 2; ++k) dst[m][k] = *(const PG8_LAS bf16x8*)(lds + PG8_SA(b, h) + aoff + m * 2048 + k * 1024); } while (0)
; #define PG8_MMA(ai, bj, At, Bt) do { __builtin_amdgcn_s_setprio(1); _Pragma("unroll") for (int m = 0; m < 4; ++m) _Pragma("unroll") for (int n = 0; n < 2; ++n) _Pragma("unroll") for (int k = 0; k < 2; ++k) \
;         acc[ai][bj][m][n] = __builtin_amdgcn_mfma_f32_16x16x32_bf16(Bt[n][k], At[m][k], acc[ai][bj][m][n], 0, 0, 0); __builtin_amdgcn_s_setprio(0); } while (0)
; #define PG8_WAIT_V(n) asm volatile("s_waitcnt vmcnt(" #n ")" ::: "memory")
; #define PG8_WAIT_L(n) asm volatile("s_waitcnt lgkmcnt(" #n ")" ::: "memory")
; #define PG8_BAR __builtin_amdgcn_s_barrier()
; #define PG8_SCHED __builtin_amdgcn_sched_barrier(0)
; template <class Epi, class Sched, bool ALIGN_EPI = false, bool SP2 = false>
; __device__ __forceinline__ void gemm_phase(PG8_LAS unsigned char* lds, const Gemm g, const Sched& S, const Epi& E) {
;     ...
;             PG8_WAIT_V(8); PG8_WAIT_L(0); PG8_BAR; PG8_MMA(0, 0, At, B0); PG8_MMA(0, 1, At, B1); PG8_BAR; PG8_SCHED;
;             PG8_LDA(At, 0, 1); PG8_STAGE(PG8_SB(0, 0), b2, voffB); PG8_STAGE(PG8_SB(0, 1), b2 + hstep, voffB); PG8_STAGE(PG8_SA(0, 0), a2, voffA);
;             PG8_WAIT_V(8); PG8_WAIT_L(0); PG8_BAR; PG8_MMA(1, 0, At, B0); PG8_MMA(1, 1, At, B1); PG8_BAR; PG8_SCHED;
	v_mfma_f32_16x16x32_bf16 v[124:127], v[128:131], v[160:163], v[124:127]
	v_mfma_f32_16x16x32_bf16 v[120:123], v[136:139], v[160:163], v[120:123]
	v_mfma_f32_16x16x32_bf16 v[112:115], v[128:131], v[186:189], v[112:115]
	v_mfma_f32_16x16x32_bf16 v[104:107], v[136:139], v[186:189], v[104:107]
	v_mfma_f32_16x16x32_bf16 v[96:99], v[128:131], v[194:197], v[96:99]
	v_mfma_f32_16x16x32_bf16 v[88:91], v[136:139], v[194:197], v[88:91]
	v_mfma_f32_16x16x32_bf16 v[80:83], v[128:131], v[224:227], v[80:83]
	v_mfma_f32_16x16x32_bf16 v[72:75], v[136:139], v[224:227], v[72:75]
	v_mfma_f32_16x16x32_bf16 v[124:127], v[132:135], v[164:167], v[124:127]
	v_mfma_f32_16x16x32_bf16 v[120:123], v[140:143], v[164:167], v[120:123]
	v_mfma_f32_16x16x32_bf16 v[112:115], v[132:135], v[190:193], v[112:115]
	v_mfma_f32_16x16x32_bf16 v[104:107], v[140:143], v[190:193], v[104:107]
	v_mfma_f32_16x16x32_bf16 v[96:99], v[132:135], v[198:201], v[96:99]
	v_mfma_f32_16x16x32_bf16 v[88:91], v[140:143], v[198:201], v[88:91]
	v_mfma_f32_16x16x32_bf16 v[80:83], v[132:135], v[230:233], v[80:83]
	v_mfma_f32_16x16x32_bf16 v[72:75], v[140:143], v[230:233], v[72:75]
	s_setprio 0
	s_setprio 1
	v_mfma_f32_16x16x32_bf16 v[116:119], v[144:147], v[160:163], v[116:119]
	v_mfma_f32_16x16x32_bf16 v[108:111], v[152:155], v[160:163], v[108:111]
	v_mfma_f32_16x16x32_bf16 v[100:103], v[144:147], v[186:189], v[100:103]
	v_mfma_f32_16x16x32_bf16 v[92:95], v[152:155], v[186:189], v[92:95]
	v_mfma_f32_16x16x32_bf16 v[84:87], v[144:147], v[194:197], v[84:87]
	v_mfma_f32_16x16x32_bf16 v[76:79], v[152:155], v[194:197], v[76:79]
	v_mfma_f32_16x16x32_bf16 v[68:71], v[144:147], v[224:227], v[68:71]
	v_mfma_f32_16x16x32_bf16 v[64:67], v[152:155], v[224:227], v[64:67]
	v_mfma_f32_16x16x32_bf16 v[116:119], v[148:151], v[164:167], v[116:119]
	v_mfma_f32_16x16x32_bf16 v[108:111], v[156:159], v[164:167], v[108:111]
	v_mfma_f32_16x16x32_bf16 v[100:103], v[148:151], v[190:193], v[100:103]
	v_mfma_f32_16x16x32_bf16 v[92:95], v[156:159], v[190:193], v[92:95]
	v_mfma_f32_16x16x32_bf16 v[84:87], v[148:151], v[198:201], v[84:87]
	v_mfma_f32_16x16x32_bf16 v[76:79], v[156:159], v[198:201], v[76:79]
	v_mfma_f32_16x16x32_bf16 v[68:71], v[148:151], v[230:233], v[68:71]
	v_mfma_f32_16x16x32_bf16 v[64:67], v[156:159], v[230:233], v[64:67]
	s_barrier
	s_setprio 0
	s_add_i32 s76, s76, s46
	v_lshl_add_u64 v[202:203], s[54:55], 0, v[180:181]
	s_mov_b32 m0, s76
	ds_read_b128 v[160:163], v219 offset:16384
	ds_read_b128 v[164:167], v219 offset:17408
	ds_read_b128 v[186:189], v219 offset:18432
	ds_read_b128 v[190:193], v219 offset:19456
	ds_read_b128 v[194:197], v219 offset:20480
	ds_read_b128 v[198:201], v219 offset:21504
	ds_read_b128 v[224:227], v219 offset:22528
	ds_read_b128 v[230:233], v219 offset:23552
	global_load_lds_dwordx4 v[202:203], off
	s_add_i32 m0, s76, 0x2000
	s_add_u32 s76, s54, 0x40000
	v_lshl_add_u64 v[208:209], s[54:55], 0, v[168:169]
	s_addc_u32 s77, s55, 0
	s_add_i32 s92, s92, s46
	global_load_lds_dwordx4 v[208:209], off
	v_lshl_add_u64 v[220:221], s[76:77], 0, v[180:181]
	s_mov_b32 m0, s92
	v_lshl_add_u64 v[234:235], s[60:61], 0, v[170:171]
	global_load_lds_dwordx4 v[220:221], off
	v_lshl_add_u64 v[220:221], s[76:77], 0, v[168:169]
	s_add_i32 m0, s92, 0x2000
	s_nop 0
	global_load_lds_dwordx4 v[220:221], off
	v_lshl_add_u64 v[220:221], s[60:61], 0, v[172:173]
	s_mov_b32 m0, s47
	s_nop 0
	global_load_lds_dwordx4 v[220:221], off
	s_mov_b32 m0, s56
	s_nop 0
	global_load_lds_dwordx4 v[234:235], off
	s_waitcnt vmcnt(8)
	s_waitcnt lgkmcnt(0)
	s_setprio 1
	s_barrier
	v_mfma_f32_16x16x32_bf16 v[60:63], v[128:131], v[160:163], v[60:63]
	v_mfma_f32_16x16x32_bf16 v[56:59], v[136:139], v[160:163], v[56:59]
	v_mfma_f32_16x16x32_bf16 v[48:51], v[128:131], v[186:189], v[48:51]
	v_mfma_f32_16x16x32_bf16 v[40:43], v[136:139], v[186:189], v[40:43]
	v_mfma_f32_16x16x32_bf16 v[32:35], v[128:131], v[194:197], v[32:35]
	v_mfma_f32_16x16x32_bf16 v[24:27], v[136:139], v[194:197], v[24:27]
	v_mfma_f32_16x16x32_bf16 v[16:19], v[128:131], v[224:227], v[16:19]
	v_mfma_f32_16x16x32_bf16 v[8:11], v[136:139], v[224:227], v[8:11]
	v_mfma_f32_16x16x32_bf16 v[60:63], v[132:135], v[164:167], v[60:63]
	v_mfma_f32_16x16x32_bf16 v[56:59], v[140:143], v[164:167], v[56:59]
	v_mfma_f32_16x16x32_bf16 v[48:51], v[132:135], v[190:193], v[48:51]
	v_mfma_f32_16x16x32_bf16 v[40:43], v[140:143], v[190:193], v[40:43]
	v_mfma_f32_16x16x32_bf16 v[32:35], v[132:135], v[198:201], v[32:35]
	v_mfma_f32_16x16x32_bf16 v[24:27], v[140:143], v[198:201], v[24:27]
	v_mfma_f32_16x16x32_bf16 v[16:19], v[132:135], v[230:233], v[16:19]
	v_mfma_f32_16x16x32_bf16 v[8:11], v[140:143], v[230:233], v[8:11]
	s_setprio 0
	s_setprio 1
	v_mfma_f32_16x16x32_bf16 v[52:55], v[144:147], v[160:163], v[52:55]
	v_mfma_f32_16x16x32_bf16 v[44:47], v[152:155], v[160:163], v[44:47]
	v_mfma_f32_16x16x32_bf16 v[36:39], v[144:147], v[186:189], v[36:39]
	v_mfma_f32_16x16x32_bf16 v[28:31], v[152:155], v[186:189], v[28:31]
	v_mfma_f32_16x16x32_bf16 v[20:23], v[144:147], v[194:197], v[20:23]
	v_mfma_f32_16x16x32_bf16 v[12:15], v[152:155], v[194:197], v[12:15]
	v_mfma_f32_16x16x32_bf16 v[4:7], v[144:147], v[224:227], v[4:7]
	v_mfma_f32_16x16x32_bf16 v[0:3], v[152:155], v[224:227], v[0:3]
	v_mfma_f32_16x16x32_bf16 v[52:55], v[148:151], v[164:167], v[52:55]
	v_mfma_f32_16x16x32_bf16 v[44:47], v[156:159], v[164:167], v[44:47]
	v_mfma_f32_16x16x32_bf16 v[36:39], v[148:151], v[190:193], v[36:39]
	v_mfma_f32_16x16x32_bf16 v[28:31], v[156:159], v[190:193], v[28:31]
	v_mfma_f32_16x16x32_bf16 v[20:23], v[148:151], v[198:201], v[20:23]
	v_mfma_f32_16x16x32_bf16 v[12:15], v[156:159], v[198:201], v[12:15]
	v_mfma_f32_16x16x32_bf16 v[4:7], v[148:151], v[230:233], v[4:7]
	v_mfma_f32_16x16x32_bf16 v[0:3], v[156:159], v[230:233], v[0:3]
	s_barrier
; #define PG8_STAGE(bufoff, gbase, voff) do { _Pragma("unroll") for (int _i = 0; _i < 2; ++_i) \
;         __builtin_amdgcn_global_load_lds((const unsigned*)((const char*)(gbase) + (voff)[_i]), (PG8_LAS unsigned*)(lds + (bufoff) + ldsw + _i * 8192), 16, 0, 0); } while (0)
; #define PG8_LDA(dst, b, h) do { _Pragma("unroll") for (int m = 0; m < 4; ++m) _Pragma("unroll") for (int k = 0; k < 2; ++k) dst[m][k] = *(const PG8_LAS bf16x8*)(lds + PG8_SA(b, h) + aoff + m * 2048 + k * 1024); } while (0)
; #define PG8_LDB(dst, b, h) do { _Pragma("unroll") for (int n = 0; n < 2; ++n) _Pragma("unroll") for (int k = 0; k < 2; ++k) dst[n][k] = *(const PG8_LAS bf16x8*)(lds + PG8_SB(b, h) + boff + n * 2048 + k * 1024); } while (0)
; #define PG8_MMA(ai, bj, At, Bt) do { __builtin_amdgcn_s_setprio(1); _Pragma("unroll") for (int m = 0; m < 4; ++m) _Pragma("unroll") for (int n = 0; n < 2; ++n) _Pragma("unroll") for (int k = 0; k < 2; ++k) \
;         acc[ai][bj][m][n] = __builtin_amdgcn_mfma_f32_16x16x32_bf16(Bt[n][k], At[m][k], acc[ai][bj][m][n], 0, 0, 0); __builtin_amdgcn_s_setprio(0); } while (0)
; #define PG8_WAIT_V(n) asm volatile("s_waitcnt vmcnt(" #n ")" ::: "memory")
; #define PG8_WAIT_L(n) asm volatile("s_waitcnt lgkmcnt(" #n ")" ::: "memory")
; #define PG8_BAR __builtin_amdgcn_s_barrier()
; #define PG8_SCHED __builtin_amdgcn_sched_barrier(0)
; template <class Epi, class Sched, bool ALIGN_EPI = false, bool SP2 = false>
; __device__ __forceinline__ void gemm_phase(PG8_LAS unsigned char* lds, const Gemm g, const Sched& S, const Epi& E) {
;     ...
;             PG8_LDB(B0, 1, 0); PG8_LDB(B1, 1, 1); PG8_SCHED; PG8_LDA(At, 1, 0); PG8_STAGE(PG8_SA(0, 1), a2 + hstep, voffA);
;             PG8_WAIT_V(8); PG8_WAIT_L(0); PG8_BAR; PG8_MMA(0, 0, At, B0); PG8_MMA(0, 1, At, B1); PG8_BAR; PG8_SCHED;
	s_setprio 0
	s_add_i32 s76, 0, 0x18000
	s_add_i32 s77, 0, 0x1c000
	v_add_u32_e32 v140, s76, v217
	v_add_u32_e32 v156, s77, v217
	ds_read_b128 v[128:131], v140
	ds_read_b128 v[132:135], v140 offset:1024
	ds_read_b128 v[136:139], v140 offset:2048
	ds_read_b128 v[140:143], v140 offset:3072
	ds_read_b128 v[144:147], v156
	ds_read_b128 v[148:151], v156 offset:1024
	ds_read_b128 v[152:155], v156 offset:2048
	ds_read_b128 v[156:159], v156 offset:3072
	s_add_u32 s60, s60, 0x40000
	s_addc_u32 s61, s61, 0
	s_mov_b32 m0, s57
	v_lshl_add_u64 v[236:237], s[60:61], 0, v[172:173]
	ds_read_b128 v[160:163], v219 offset:32768
	ds_read_b128 v[164:167], v219 offset:33792
	ds_read_b128 v[186:189], v219 offset:34816
	ds_read_b128 v[190:193], v219 offset:35840
	ds_read_b128 v[194:197], v219 offset:36864
	ds_read_b128 v[198:201], v219 offset:37888
	ds_read_b128 v[224:227], v219 offset:38912
	ds_read_b128 v[230:233], v219 offset:39936
	global_load_lds_dwordx4 v[236:237], off
	v_lshl_add_u64 v[236:237], s[60:61], 0, v[170:171]
	s_mov_b32 m0, s58
	s_nop 0
	global_load_lds_dwordx4 v[236:237], off
	s_waitcnt vmcnt(8)
	s_waitcnt lgkmcnt(0)
	s_setprio 1
	s_barrier
	v_mfma_f32_16x16x32_bf16 v[124:127], v[128:131], v[160:163], v[124:127]
	v_mfma_f32_16x16x32_bf16 v[120:123], v[136:139], v[160:163], v[120:123]
	v_mfma_f32_16x16x32_bf16 v[112:115], v[128:131], v[186:189], v[112:115]
	v_mfma_f32_16x16x32_bf16 v[104:107], v[136:139], v[186:189], v[104:107]
	v_mfma_f32_16x16x32_bf16 v[96:99], v[128:131], v[194:197], v[96:99]
	v_mfma_f32_16x16x32_bf16 v[88:91], v[136:139], v[194:197], v[88:91]
	v_mfma_f32_16x16x32_bf16 v[80:83], v[128:131], v[224:227], v[80:83]
	v_mfma_f32_16x16x32_bf16 v[72:75], v[136:139], v[224:227], v[72:75]
	v_mfma_f32_16x16x32_bf16 v[124:127], v[132:135], v[164:167], v[124:127]
	v_mfma_f32_16x16x32_bf16 v[120:123], v[140:143], v[164:167], v[120:123]
	v_mfma_f32_16x16x32_bf16 v[112:115], v[132:135], v[190:193], v[112:115]
	v_mfma_f32_16x16x32_bf16 v[104:107], v[140:143], v[190:193], v[104:107]
	v_mfma_f32_16x16x32_bf16 v[96:99], v[132:135], v[198:201], v[96:99]
	v_mfma_f32_16x16x32_bf16 v[88:91], v[140:143], v[198:201], v[88:91]
	v_mfma_f32_16x16x32_bf16 v[80:83], v[132:135], v[230:233], v[80:83]
	v_mfma_f32_16x16x32_bf16 v[72:75], v[140:143], v[230:233], v[72:75]
	s_setprio 0
	s_setprio 1
	v_mfma_f32_16x16x32_bf16 v[116:119], v[144:147], v[160:163], v[116:119]
	v_mfma_f32_16x16x32_bf16 v[108:111], v[152:155], v[160:163], v[108:111]
	v_mfma_f32_16x16x32_bf16 v[100:103], v[144:147], v[186:189], v[100:103]
	v_mfma_f32_16x16x32_bf16 v[92:95], v[152:155], v[186:189], v[92:95]
	v_mfma_f32_16x16x32_bf16 v[84:87], v[144:147], v[194:197], v[84:87]
	v_mfma_f32_16x16x32_bf16 v[76:79], v[152:155], v[194:197], v[76:79]
	v_mfma_f32_16x16x32_bf16 v[68:71], v[144:147], v[224:227], v[68:71]
	v_mfma_f32_16x16x32_bf16 v[64:67], v[152:155], v[224:227], v[64:67]
	v_mfma_f32_16x16x32_bf16 v[116:119], v[148:151], v[164:167], v[116:119]
	v_mfma_f32_16x16x32_bf16 v[108:111], v[156:159], v[164:167], v[108:111]
	v_mfma_f32_16x16x32_bf16 v[100:103], v[148:151], v[190:193], v[100:103]
	v_mfma_f32_16x16x32_bf16 v[92:95], v[156:159], v[190:193], v[92:95]
	v_mfma_f32_16x16x32_bf16 v[84:87], v[148:151], v[198:201], v[84:87]
	v_mfma_f32_16x16x32_bf16 v[76:79], v[156:159], v[198:201], v[76:79]
	v_mfma_f32_16x16x32_bf16 v[68:71], v[148:151], v[230:233], v[68:71]
	v_mfma_f32_16x16x32_bf16 v[64:67], v[156:159], v[230:233], v[64:67]
	s_barrier
; #define PG8_STAGE(bufoff, gbase, voff) do { _Pragma("unroll") for (int _i = 0; _i < 2; ++_i) \
;         __builtin_amdgcn_global_load_lds((const unsigned*)((const char*)(gbase) + (voff)[_i]), (PG8_LAS unsigned*)(lds + (bufoff) + ldsw + _i * 8192), 16, 0, 0); } while (0)
; #define PG8_LDA(dst, b, h) do { _Pragma("unroll") for (int m = 0; m < 4; ++m) _Pragma("unroll") for (int k = 0; k < 2; ++k) dst[m][k] = *(const PG8_LAS bf16x8*)(lds + PG8_SA(b, h) + aoff + m * 2048 + k * 1024); } while (0)
; #define PG8_MMA(ai, bj, At, Bt) do { __builtin_amdgcn_s_setprio(1); _Pragma("unroll") for (int m = 0; m < 4; ++m) _Pragma("unroll") for (int n = 0; n < 2; ++n) _Pragma("unroll") for (int k = 0; k < 2; ++k) \
;         acc[ai][bj][m][n] = __builtin_amdgcn_mfma_f32_16x16x32_bf16(Bt[n][k], At[m][k], acc[ai][bj][m][n], 0, 0, 0); __builtin_amdgcn_s_setprio(0); } while (0)
; #define PG8_WAIT_V(n) asm volatile("s_waitcnt vmcnt(" #n ")" ::: "memory")
; #define PG8_WAIT_L(n) asm volatile("s_waitcnt lgkmcnt(" #n ")" ::: "memory")
; #define PG8_BAR __builtin_amdgcn_s_barrier()
; #define PG8_SCHED __builtin_amdgcn_sched_barrier(0)
; template <class Epi, class Sched, bool ALIGN_EPI = false, bool SP2 = false>
; __device__ __forceinline__ void gemm_phase(PG8_LAS unsigned char* lds, const Gemm g, const Sched& S, const Epi& E) {
;     ...
;             PG8_LDA(At, 1, 1); PG8_STAGE(PG8_SB(1, 0), b3, voffB); PG8_STAGE(PG8_SB(1, 1), b3 + hstep, voffB); PG8_STAGE(PG8_SA(1, 0), a3, voffA);
;             PG8_WAIT_V(8); PG8_WAIT_L(0); PG8_BAR; PG8_MMA(1, 0, At, B0); PG8_MMA(1, 1, At, B1); PG8_BAR; PG8_SCHED;
;     ...
;         if constexpr (ALIGN_EPI) { if (wr == 0) PG8_BAR; }
	s_setprio 0
	s_add_i32 s60, s76, s46
	v_lshl_add_u64 v[202:203], v[202:203], 0, s[70:71]
	s_mov_b32 m0, s60
	ds_read_b128 v[160:163], v219 offset:49152
	ds_read_b128 v[164:167], v219 offset:50176
	ds_read_b128 v[186:189], v219 offset:51200
	ds_read_b128 v[190:193], v219 offset:52224
	ds_read_b128 v[194:197], v219 offset:53248
	ds_read_b128 v[198:201], v219 offset:54272
	ds_read_b128 v[224:227], v219 offset:55296
	ds_read_b128 v[230:233], v219 offset:56320
	global_load_lds_dwordx4 v[202:203], off
	s_add_i32 m0, s60, 0x2000
	s_add_u32 s54, s54, 0x40080
	v_lshl_add_u64 v[202:203], v[208:209], 0, s[70:71]
	s_addc_u32 s55, s55, 0
	s_add_i32 s60, s77, s46
	global_load_lds_dwordx4 v[202:203], off
	v_lshl_add_u64 v[202:203], s[54:55], 0, v[180:181]
	s_mov_b32 m0, s60
	s_nop 0
	global_load_lds_dwordx4 v[202:203], off
	v_lshl_add_u64 v[202:203], s[54:55], 0, v[168:169]
	s_add_i32 m0, s60, 0x2000
	s_nop 0
	global_load_lds_dwordx4 v[202:203], off
	v_lshl_add_u64 v[202:203], v[220:221], 0, s[70:71]
	s_mov_b32 m0, s59
	s_nop 0
	global_load_lds_dwordx4 v[202:203], off
	v_lshl_add_u64 v[202:203], v[234:235], 0, s[70:71]
	s_mov_b32 m0, s68
	s_nop 0
	global_load_lds_dwordx4 v[202:203], off
	s_waitcnt vmcnt(8)
	s_waitcnt lgkmcnt(0)
	s_setprio 1
	s_barrier
	v_mfma_f32_16x16x32_bf16 v[60:63], v[128:131], v[160:163], v[60:63]
	v_mfma_f32_16x16x32_bf16 v[56:59], v[136:139], v[160:163], v[56:59]
	v_mfma_f32_16x16x32_bf16 v[48:51], v[128:131], v[186:189], v[48:51]
	v_mfma_f32_16x16x32_bf16 v[40:43], v[136:139], v[186:189], v[40:43]
	v_mfma_f32_16x16x32_bf16 v[32:35], v[128:131], v[194:197], v[32:35]
	v_mfma_f32_16x16x32_bf16 v[24:27], v[136:139], v[194:197], v[24:27]
	v_mfma_f32_16x16x32_bf16 v[16:19], v[128:131], v[224:227], v[16:19]
	v_mfma_f32_16x16x32_bf16 v[8:11], v[136:139], v[224:227], v[8:11]
	v_mfma_f32_16x16x32_bf16 v[60:63], v[132:135], v[164:167], v[60:63]
	v_mfma_f32_16x16x32_bf16 v[56:59], v[140:143], v[164:167], v[56:59]
	v_mfma_f32_16x16x32_bf16 v[48:51], v[132:135], v[190:193], v[48:51]
	v_mfma_f32_16x16x32_bf16 v[40:43], v[140:143], v[190:193], v[40:43]
	v_mfma_f32_16x16x32_bf16 v[32:35], v[132:135], v[198:201], v[32:35]
	v_mfma_f32_16x16x32_bf16 v[24:27], v[140:143], v[198:201], v[24:27]
	v_mfma_f32_16x16x32_bf16 v[16:19], v[132:135], v[230:233], v[16:19]
	v_mfma_f32_16x16x32_bf16 v[8:11], v[140:143], v[230:233], v[8:11]
	s_setprio 0
	s_setprio 1
	v_mfma_f32_16x16x32_bf16 v[52:55], v[144:147], v[160:163], v[52:55]
	v_mfma_f32_16x16x32_bf16 v[44:47], v[152:155], v[160:163], v[44:47]
	v_mfma_f32_16x16x32_bf16 v[36:39], v[144:147], v[186:189], v[36:39]
	v_mfma_f32_16x16x32_bf16 v[28:31], v[152:155], v[186:189], v[28:31]
	v_mfma_f32_16x16x32_bf16 v[20:23], v[144:147], v[194:197], v[20:23]
	v_mfma_f32_16x16x32_bf16 v[12:15], v[152:155], v[194:197], v[12:15]
	v_mfma_f32_16x16x32_bf16 v[4:7], v[144:147], v[224:227], v[4:7]
	v_mfma_f32_16x16x32_bf16 v[0:3], v[152:155], v[224:227], v[0:3]
	v_mfma_f32_16x16x32_bf16 v[52:55], v[148:151], v[164:167], v[52:55]
	v_mfma_f32_16x16x32_bf16 v[44:47], v[156:159], v[164:167], v[44:47]
	v_mfma_f32_16x16x32_bf16 v[36:39], v[148:151], v[190:193], v[36:39]
	v_mfma_f32_16x16x32_bf16 v[28:31], v[156:159], v[190:193], v[28:31]
	v_mfma_f32_16x16x32_bf16 v[20:23], v[148:151], v[198:201], v[20:23]
	v_mfma_f32_16x16x32_bf16 v[12:15], v[156:159], v[198:201], v[12:15]
	v_mfma_f32_16x16x32_bf16 v[4:7], v[148:151], v[230:233], v[4:7]
	v_mfma_f32_16x16x32_bf16 v[0:3], v[156:159], v[230:233], v[0:3]
	s_barrier
	s_setprio 0
	s_add_i32 s73, s73, 2
	s_add_u32 s8, s8, 0x100
	s_addc_u32 s9, s9, 0
	s_add_u32 s62, s62, 0x100
	s_addc_u32 s63, s63, 0
	s_cmp_gt_u32 s73, 13
	s_cbranch_scc0 .LBB0_360
	s_and_b64 vcc, exec, s[18:19]
	s_cbranch_vccz .LBB0_363
	s_barrier

; #define PG8_STAGE(bufoff, gbase, voff) do { _Pragma("unroll") for (int _i = 0; _i < 2; ++_i) \
;         __builtin_amdgcn_global_load_lds((const unsigned*)((const char*)(gbase) + (voff)[_i]), (PG8_LAS unsigned*)(lds + (bufoff) + ldsw + _i * 8192), 16, 0, 0); } while (0)
; #define PG8_LDA(dst, b, h) do { _Pragma("unroll") for (int m = 0; m < 4; ++m) _Pragma("unroll") for (int k = 0; k < 2; ++k) dst[m][k] = *(const PG8_LAS bf16x8*)(lds + PG8_SA(b, h) + aoff + m * 2048 + k * 1024); } while (0)
; #define PG8_LDB(dst, b, h) do { _Pragma("unroll") for (int n = 0; n < 2; ++n) _Pragma("unroll") for (int k = 0; k < 2; ++k) dst[n][k] = *(const PG8_LAS bf16x8*)(lds + PG8_SB(b, h) + boff + n * 2048 + k * 1024); } while (0)
; #define PG8_MMA(ai, bj, At, Bt) do { __builtin_amdgcn_s_setprio(1); _Pragma("unroll") for (int m = 0; m < 4; ++m) _Pragma("unroll") for (int n = 0; n < 2; ++n) _Pragma("unroll") for (int k = 0; k < 2; ++k) \
;         acc[ai][bj][m][n] = __builtin_amdgcn_mfma_f32_16x16x32_bf16(Bt[n][k], At[m][k], acc[ai][bj][m][n], 0, 0, 0); __builtin_amdgcn_s_setprio(0); } while (0)
; #define PG8_BAR __builtin_amdgcn_s_barrier()
; template <class Epi, class Sched, bool ALIGN_EPI = false, bool SP2 = false>
; __device__ __forceinline__ void gemm_phase(PG8_LAS unsigned char* lds, const Gemm g, const Sched& S, const Epi& E) {
;     ...
;         const bool has_next = S.next(ui + 1, nxt);
;         const char* nA = has_next ? (const char*)g.A + (size_t)nxt.pm * tstep : cA; const char* nB = has_next ? (const char*)g.Bt + (size_t)nxt.pn * tstep : cB;
;         for (int t = 0; t < nt; t += 2) {
;             const bool last = (t == nt - 2);
;             const char* a1 = cA + (size_t)(t + 1) * kstep;
;             const char* a2 = last ? nA : cA + (size_t)(t + 2) * kstep; const char* b2 = last ? nB : cB + (size_t)(t + 2) * kstep;
;             const char* a3 = a2 + kstep; const char* b3 = b2 + kstep;
;             if (last && has_next) S.a_ready(nxt);
;             if constexpr (SP2) {
;             PG8_LDB(B0, 0, 0); PG8_LDB(B1, 0, 1); PG8_SCHED; PG8_LDA(At, 0, 0); PG8_STAGE(PG8_SA(1, 1), a1 + hstep, voffA);
;             PG8_WAIT_V(8); PG8_WAIT_L(0); PG8_BAR; PG8_MMA(0, 0, At, B0); PG8_MMA(0, 1, At, B1); PG8_BAR; PG8_SCHED;
;             PG8_LDA(At, 0, 1); PG8_STAGE(PG8_SB(0, 0), b2, voffB); PG8_STAGE(PG8_SB(0, 1), b2 + hstep, voffB); PG8_STAGE(PG8_SA(0, 0), a2, voffA);
.LBB0_675:
	s_ashr_i32 s53, s52, 31
	s_lshl_b64 s[22:23], s[52:53], 19
	s_add_u32 s54, s5, s22
	s_addc_u32 s55, s36, s23
	s_and_b64 s[22:23], s[10:11], exec
	s_cselect_b32 s22, s55, s15
	s_cselect_b32 s23, s54, s14
	s_ashr_i32 s51, s50, 31
	s_lshl_b64 s[38:39], s[50:51], 19
	s_add_u32 s60, s37, s38
	s_addc_u32 s61, s46, s39
	s_and_b64 s[38:39], s[10:11], exec
	s_cselect_b32 s38, s61, s97
	s_cselect_b32 s39, s60, s96
	s_add_u32 s14, s14, 0x40080
	s_addc_u32 s15, s15, 0
	s_add_u32 s51, s96, 0x100
	s_addc_u32 s53, s97, 0
	s_mov_b32 s62, -2
	s_add_u32 s63, s14, 0xfffc0080
	s_addc_u32 s73, s15, -1
	s_add_i32 s93, 0, 0x10000
	s_cmp_eq_u32 s62, 12
	s_cselect_b32 vcc_hi, s22, s73
	s_cselect_b32 vcc_lo, s23, s63
	s_cselect_b32 s97, s38, s53
	s_cselect_b32 s96, s39, s51
	s_add_i32 s63, 0, 0x14000
	v_add_u32_e32 v140, s93, v197
	v_add_u32_e32 v170, s63, v197
	ds_read_b128 v[128:131], v140
	ds_read_b128 v[132:135], v140 offset:1024
	ds_read_b128 v[136:139], v140 offset:2048
	ds_read_b128 v[140:143], v140 offset:3072
	ds_read_b128 v[144:147], v170
	ds_read_b128 v[148:151], v170 offset:1024
	ds_read_b128 v[166:169], v170 offset:2048
	ds_read_b128 v[170:173], v170 offset:3072
	v_lshl_add_u64 v[178:179], s[14:15], 0, v[162:163]
	s_add_i32 m0, s56, 0xc000
	ds_read_b128 v[174:177], v220
	ds_read_b128 v[186:189], v220 offset:1024
	ds_read_b128 v[190:193], v220 offset:2048
	ds_read_b128 v[224:227], v220 offset:3072
	ds_read_b128 v[230:233], v220 offset:4096
	ds_read_b128 v[234:237], v220 offset:5120
	ds_read_b128 v[238:241], v220 offset:6144
	ds_read_b128 v[242:245], v220 offset:7168
	global_load_lds_dwordx4 v[178:179], off
	v_lshl_add_u64 v[178:179], s[14:15], 0, v[164:165]
	s_add_i32 m0, s56, 0xe000
	s_nop 0
	global_load_lds_dwordx4 v[178:179], off
	s_waitcnt vmcnt(8)
	s_waitcnt lgkmcnt(0)
	s_setprio 1
	s_barrier
	v_mfma_f32_16x16x32_bf16 v[124:127], v[128:131], v[174:177], 0
	v_mfma_f32_16x16x32_bf16 v[120:123], v[136:139], v[174:177], 0
	v_mfma_f32_16x16x32_bf16 v[112:115], v[128:131], v[190:193], 0
	v_mfma_f32_16x16x32_bf16 v[104:107], v[136:139], v[190:193], 0
	v_mfma_f32_16x16x32_bf16 v[96:99], v[128:131], v[230:233], 0
	v_mfma_f32_16x16x32_bf16 v[88:91], v[136:139], v[230:233], 0
	v_mfma_f32_16x16x32_bf16 v[80:83], v[128:131], v[238:241], 0
	v_mfma_f32_16x16x32_bf16 v[72:75], v[136:139], v[238:241], 0
	v_mfma_f32_16x16x32_bf16 v[124:127], v[132:135], v[186:189], v[124:127]
	v_mfma_f32_16x16x32_bf16 v[120:123], v[140:143], v[186:189], v[120:123]
	v_mfma_f32_16x16x32_bf16 v[112:115], v[132:135], v[224:227], v[112:115]
	v_mfma_f32_16x16x32_bf16 v[104:107], v[140:143], v[224:227], v[104:107]
	v_mfma_f32_16x16x32_bf16 v[96:99], v[132:135], v[234:237], v[96:99]
	v_mfma_f32_16x16x32_bf16 v[88:91], v[140:143], v[234:237], v[88:91]
	v_mfma_f32_16x16x32_bf16 v[80:83], v[132:135], v[242:245], v[80:83]
	v_mfma_f32_16x16x32_bf16 v[72:75], v[140:143], v[242:245], v[72:75]
	s_setprio 0
	s_setprio 1
	v_mfma_f32_16x16x32_bf16 v[116:119], v[144:147], v[174:177], 0
	v_mfma_f32_16x16x32_bf16 v[108:111], v[166:169], v[174:177], 0
	v_mfma_f32_16x16x32_bf16 v[100:103], v[144:147], v[190:193], 0
	v_mfma_f32_16x16x32_bf16 v[92:95], v[166:169], v[190:193], 0
	v_mfma_f32_16x16x32_bf16 v[84:87], v[144:147], v[230:233], 0
	v_mfma_f32_16x16x32_bf16 v[76:79], v[166:169], v[230:233], 0
	v_mfma_f32_16x16x32_bf16 v[68:71], v[144:147], v[238:241], 0
	v_mfma_f32_16x16x32_bf16 v[64:67], v[166:169], v[238:241], 0
	v_mfma_f32_16x16x32_bf16 v[116:119], v[148:151], v[186:189], v[116:119]
	v_mfma_f32_16x16x32_bf16 v[108:111], v[170:173], v[186:189], v[108:111]
	v_mfma_f32_16x16x32_bf16 v[100:103], v[148:151], v[224:227], v[100:103]
	v_mfma_f32_16x16x32_bf16 v[92:95], v[170:173], v[224:227], v[92:95]
	v_mfma_f32_16x16x32_bf16 v[84:87], v[148:151], v[234:237], v[84:87]
	v_mfma_f32_16x16x32_bf16 v[76:79], v[170:173], v[234:237], v[76:79]
	v_mfma_f32_16x16x32_bf16 v[68:71], v[148:151], v[242:245], v[68:71]
	v_mfma_f32_16x16x32_bf16 v[64:67], v[170:173], v[242:245], v[64:67]
	s_barrier
	s_setprio 0
	s_add_i32 s73, s93, s47
	v_lshl_add_u64 v[178:179], s[96:97], 0, v[156:157]
	s_mov_b32 m0, s73
	ds_read_b128 v[174:177], v220 offset:16384
	ds_read_b128 v[186:189], v220 offset:17408
	ds_read_b128 v[190:193], v220 offset:18432
	ds_read_b128 v[224:227], v220 offset:19456
	ds_read_b128 v[230:233], v220 offset:20480
	ds_read_b128 v[234:237], v220 offset:21504
	ds_read_b128 v[238:241], v220 offset:22528
	ds_read_b128 v[242:245], v220 offset:23552
	global_load_lds_dwordx4 v[178:179], off
	s_add_i32 m0, s73, 0x2000
	s_add_u32 s94, s96, 0x40000
	v_lshl_add_u64 v[194:195], s[96:97], 0, v[152:153]
	s_addc_u32 s95, s97, 0
	s_add_i32 s63, s63, s47
	global_load_lds_dwordx4 v[194:195], off
	v_lshl_add_u64 v[246:247], s[94:95], 0, v[156:157]
	s_mov_b32 m0, s63
	v_lshl_add_u64 v[248:249], vcc, 0, v[154:155]
	global_load_lds_dwordx4 v[246:247], off
	v_lshl_add_u64 v[246:247], s[94:95], 0, v[152:153]
	s_add_i32 m0, s63, 0x2000
	s_nop 0
	global_load_lds_dwordx4 v[246:247], off
	v_lshl_add_u64 v[246:247], vcc, 0, v[158:159]
	s_mov_b32 m0, s56
	s_nop 0
	global_load_lds_dwordx4 v[246:247], off
	s_mov_b32 m0, s57
	s_nop 0
	global_load_lds_dwordx4 v[248:249], off
	s_waitcnt vmcnt(8)
	s_waitcnt lgkmcnt(0)
	s_setprio 1
	s_barrier
; #define PG8_STAGE(bufoff, gbase, voff) do { _Pragma("unroll") for (int _i = 0; _i < 2; ++_i) \
;         __builtin_amdgcn_global_load_lds((const unsigned*)((const char*)(gbase) + (voff)[_i]), (PG8_LAS unsigned*)(lds + (bufoff) + ldsw + _i * 8192), 16, 0, 0); } while (0)
; #define PG8_LDA(dst, b, h) do { _Pragma("unroll") for (int m = 0; m < 4; ++m) _Pragma("unroll") for (int k = 0; k < 2; ++k) dst[m][k] = *(const PG8_LAS bf16x8*)(lds + PG8_SA(b, h) + aoff + m * 2048 + k * 1024); } while (0)
; #define PG8_LDB(dst, b, h) do { _Pragma("unroll") for (int n = 0; n < 2; ++n) _Pragma("unroll") for (int k = 0; k < 2; ++k) dst[n][k] = *(const PG8_LAS bf16x8*)(lds + PG8_SB(b, h) + boff + n * 2048 + k * 1024); } while (0)
; #define PG8_MMA(ai, bj, At, Bt) do { __builtin_amdgcn_s_setprio(1); _Pragma("unroll") for (int m = 0; m < 4; ++m) _Pragma("unroll") for (int n = 0; n < 2; ++n) _Pragma("unroll") for (int k = 0; k < 2; ++k) \
;         acc[ai][bj][m][n] = __builtin_amdgcn_mfma_f32_16x16x32_bf16(Bt[n][k], At[m][k], acc[ai][bj][m][n], 0, 0, 0); __builtin_amdgcn_s_setprio(0); } while (0)
; #define PG8_WAIT_V(n) asm volatile("s_waitcnt vmcnt(" #n ")" ::: "memory")
; template <class Epi, class Sched, bool ALIGN_EPI = false, bool SP2 = false>
; __device__ __forceinline__ void gemm_phase(PG8_LAS unsigned char* lds, const Gemm g, const Sched& S, const Epi& E) {
;     ...
;             PG8_LDB(B0, 0, 0); PG8_LDB(B1, 0, 1); PG8_SCHED; PG8_LDA(At, 0, 0); PG8_STAGE(PG8_SA(1, 1), a1 + hstep, voffA);
;             PG8_WAIT_V(8); PG8_WAIT_L(0); PG8_BAR; PG8_MMA(0, 0, At, B0); PG8_MMA(0, 1, At, B1); PG8_BAR; PG8_SCHED;
;             PG8_LDA(At, 0, 1); PG8_STAGE(PG8_SB(0, 0), b2, voffB); PG8_STAGE(PG8_SB(0, 1), b2 + hstep, voffB); PG8_STAGE(PG8_SA(0, 0), a2, voffA);
;             PG8_WAIT_V(8); PG8_WAIT_L(0); PG8_BAR; PG8_MMA(1, 0, At, B0); PG8_MMA(1, 1, At, B1); PG8_BAR; PG8_SCHED;
;             PG8_LDB(B0, 1, 0); PG8_LDB(B1, 1, 1); PG8_SCHED; PG8_LDA(At, 1, 0); PG8_STAGE(PG8_SA(0, 1), a2 + hstep, voffA);
;             PG8_WAIT_V(8); PG8_WAIT_L(0); PG8_BAR; PG8_MMA(0, 0, At, B0); PG8_MMA(0, 1, At, B1); PG8_BAR; PG8_SCHED;
;             PG8_LDA(At, 1, 1); PG8_STAGE(PG8_SB(1, 0), b3, voffB); PG8_STAGE(PG8_SB(1, 1), b3 + hstep, voffB); PG8_STAGE(PG8_SA(1, 0), a3, voffA);
;             PG8_WAIT_V(8); PG8_WAIT_L(0); PG8_BAR; PG8_MMA(1, 0, At, B0); PG8_MMA(1, 1, At, B1); PG8_BAR; PG8_SCHED;
	v_mfma_f32_16x16x32_bf16 v[60:63], v[128:131], v[174:177], 0
	v_mfma_f32_16x16x32_bf16 v[56:59], v[136:139], v[174:177], 0
	v_mfma_f32_16x16x32_bf16 v[48:51], v[128:131], v[190:193], 0
	v_mfma_f32_16x16x32_bf16 v[40:43], v[136:139], v[190:193], 0
	v_mfma_f32_16x16x32_bf16 v[32:35], v[128:131], v[230:233], 0
	v_mfma_f32_16x16x32_bf16 v[24:27], v[136:139], v[230:233], 0
	v_mfma_f32_16x16x32_bf16 v[16:19], v[128:131], v[238:241], 0
	v_mfma_f32_16x16x32_bf16 v[8:11], v[136:139], v[238:241], 0
	v_mfma_f32_16x16x32_bf16 v[60:63], v[132:135], v[186:189], v[60:63]
	v_mfma_f32_16x16x32_bf16 v[56:59], v[140:143], v[186:189], v[56:59]
	v_mfma_f32_16x16x32_bf16 v[48:51], v[132:135], v[224:227], v[48:51]
	v_mfma_f32_16x16x32_bf16 v[40:43], v[140:143], v[224:227], v[40:43]
	v_mfma_f32_16x16x32_bf16 v[32:35], v[132:135], v[234:237], v[32:35]
	v_mfma_f32_16x16x32_bf16 v[24:27], v[140:143], v[234:237], v[24:27]
	v_mfma_f32_16x16x32_bf16 v[16:19], v[132:135], v[242:245], v[16:19]
	v_mfma_f32_16x16x32_bf16 v[8:11], v[140:143], v[242:245], v[8:11]
	s_setprio 0
	s_setprio 1
	v_mfma_f32_16x16x32_bf16 v[52:55], v[144:147], v[174:177], 0
	v_mfma_f32_16x16x32_bf16 v[44:47], v[166:169], v[174:177], 0
	v_mfma_f32_16x16x32_bf16 v[36:39], v[144:147], v[190:193], 0
	v_mfma_f32_16x16x32_bf16 v[28:31], v[166:169], v[190:193], 0
	v_mfma_f32_16x16x32_bf16 v[20:23], v[144:147], v[230:233], 0
	v_mfma_f32_16x16x32_bf16 v[12:15], v[166:169], v[230:233], 0
	v_mfma_f32_16x16x32_bf16 v[4:7], v[144:147], v[238:241], 0
	v_mfma_f32_16x16x32_bf16 v[0:3], v[166:169], v[238:241], 0
	v_mfma_f32_16x16x32_bf16 v[52:55], v[148:151], v[186:189], v[52:55]
	v_mfma_f32_16x16x32_bf16 v[44:47], v[170:173], v[186:189], v[44:47]
	v_mfma_f32_16x16x32_bf16 v[36:39], v[148:151], v[224:227], v[36:39]
	v_mfma_f32_16x16x32_bf16 v[28:31], v[170:173], v[224:227], v[28:31]
	v_mfma_f32_16x16x32_bf16 v[20:23], v[148:151], v[234:237], v[20:23]
	v_mfma_f32_16x16x32_bf16 v[12:15], v[170:173], v[234:237], v[12:15]
	v_mfma_f32_16x16x32_bf16 v[4:7], v[148:151], v[242:245], v[4:7]
	v_mfma_f32_16x16x32_bf16 v[0:3], v[170:173], v[242:245], v[0:3]
	s_barrier
	s_setprio 0
	s_add_i32 s63, 0, 0x18000
	s_add_i32 s73, 0, 0x1c000
	v_add_u32_e32 v140, s63, v197
	v_add_u32_e32 v170, s73, v197
	ds_read_b128 v[128:131], v140
	ds_read_b128 v[132:135], v140 offset:1024
	ds_read_b128 v[136:139], v140 offset:2048
	ds_read_b128 v[140:143], v140 offset:3072
	ds_read_b128 v[144:147], v170
	ds_read_b128 v[148:151], v170 offset:1024
	ds_read_b128 v[166:169], v170 offset:2048
	ds_read_b128 v[170:173], v170 offset:3072
	s_add_u32 s94, vcc_lo, 0x40000
	s_addc_u32 s95, vcc_hi, 0
	s_mov_b32 m0, s58
	v_lshl_add_u64 v[250:251], s[94:95], 0, v[158:159]
	ds_read_b128 v[174:177], v220 offset:32768
	ds_read_b128 v[186:189], v220 offset:33792
	ds_read_b128 v[190:193], v220 offset:34816
	ds_read_b128 v[224:227], v220 offset:35840
	ds_read_b128 v[230:233], v220 offset:36864
	ds_read_b128 v[234:237], v220 offset:37888
	ds_read_b128 v[238:241], v220 offset:38912
	ds_read_b128 v[242:245], v220 offset:39936
	global_load_lds_dwordx4 v[250:251], off
	v_lshl_add_u64 v[250:251], s[94:95], 0, v[154:155]
	s_mov_b32 m0, s59
	s_nop 0
	global_load_lds_dwordx4 v[250:251], off
	s_waitcnt vmcnt(8)
	s_waitcnt lgkmcnt(0)
	s_setprio 1
	s_barrier
	v_mfma_f32_16x16x32_bf16 v[124:127], v[128:131], v[174:177], v[124:127]
	v_mfma_f32_16x16x32_bf16 v[120:123], v[136:139], v[174:177], v[120:123]
	v_mfma_f32_16x16x32_bf16 v[112:115], v[128:131], v[190:193], v[112:115]
	v_mfma_f32_16x16x32_bf16 v[104:107], v[136:139], v[190:193], v[104:107]
	v_mfma_f32_16x16x32_bf16 v[96:99], v[128:131], v[230:233], v[96:99]
	v_mfma_f32_16x16x32_bf16 v[88:91], v[136:139], v[230:233], v[88:91]
	v_mfma_f32_16x16x32_bf16 v[80:83], v[128:131], v[238:241], v[80:83]
	v_mfma_f32_16x16x32_bf16 v[72:75], v[136:139], v[238:241], v[72:75]
	v_mfma_f32_16x16x32_bf16 v[124:127], v[132:135], v[186:189], v[124:127]
	v_mfma_f32_16x16x32_bf16 v[120:123], v[140:143], v[186:189], v[120:123]
	v_mfma_f32_16x16x32_bf16 v[112:115], v[132:135], v[224:227], v[112:115]
	v_mfma_f32_16x16x32_bf16 v[104:107], v[140:143], v[224:227], v[104:107]
	v_mfma_f32_16x16x32_bf16 v[96:99], v[132:135], v[234:237], v[96:99]
	v_mfma_f32_16x16x32_bf16 v[88:91], v[140:143], v[234:237], v[88:91]
	v_mfma_f32_16x16x32_bf16 v[80:83], v[132:135], v[242:245], v[80:83]
	v_mfma_f32_16x16x32_bf16 v[72:75], v[140:143], v[242:245], v[72:75]
	s_setprio 0
	s_setprio 1
	v_mfma_f32_16x16x32_bf16 v[116:119], v[144:147], v[174:177], v[116:119]
	v_mfma_f32_16x16x32_bf16 v[108:111], v[166:169], v[174:177], v[108:111]
	v_mfma_f32_16x16x32_bf16 v[100:103], v[144:147], v[190:193], v[100:103]
	v_mfma_f32_16x16x32_bf16 v[92:95], v[166:169], v[190:193], v[92:95]
	v_mfma_f32_16x16x32_bf16 v[84:87], v[144:147], v[230:233], v[84:87]
	v_mfma_f32_16x16x32_bf16 v[76:79], v[166:169], v[230:233], v[76:79]
	v_mfma_f32_16x16x32_bf16 v[68:71], v[144:147], v[238:241], v[68:71]
	v_mfma_f32_16x16x32_bf16 v[64:67], v[166:169], v[238:241], v[64:67]
	v_mfma_f32_16x16x32_bf16 v[116:119], v[148:151], v[186:189], v[116:119]
	v_mfma_f32_16x16x32_bf16 v[108:111], v[170:173], v[186:189], v[108:111]
	v_mfma_f32_16x16x32_bf16 v[100:103], v[148:151], v[224:227], v[100:103]
	v_mfma_f32_16x16x32_bf16 v[92:95], v[170:173], v[224:227], v[92:95]
	v_mfma_f32_16x16x32_bf16 v[84:87], v[148:151], v[234:237], v[84:87]
	v_mfma_f32_16x16x32_bf16 v[76:79], v[170:173], v[234:237], v[76:79]
	v_mfma_f32_16x16x32_bf16 v[68:71], v[148:151], v[242:245], v[68:71]
	v_mfma_f32_16x16x32_bf16 v[64:67], v[170:173], v[242:245], v[64:67]
	s_barrier
; #define PG8_STAGE(bufoff, gbase, voff) do { _Pragma("unroll") for (int _i = 0; _i < 2; ++_i) \
;         __builtin_amdgcn_global_load_lds((const unsigned*)((const char*)(gbase) + (voff)[_i]), (PG8_LAS unsigned*)(lds + (bufoff) + ldsw + _i * 8192), 16, 0, 0); } while (0)
; #define PG8_LDA(dst, b, h) do { _Pragma("unroll") for (int m = 0; m < 4; ++m) _Pragma("unroll") for (int k = 0; k < 2; ++k) dst[m][k] = *(const PG8_LAS bf16x8*)(lds + PG8_SA(b, h) + aoff + m * 2048 + k * 1024); } while (0)
; #define PG8_LDB(dst, b, h) do { _Pragma("unroll") for (int n = 0; n < 2; ++n) _Pragma("unroll") for (int k = 0; k < 2; ++k) dst[n][k] = *(const PG8_LAS bf16x8*)(lds + PG8_SB(b, h) + boff + n * 2048 + k * 1024); } while (0)
; #define PG8_MMA(ai, bj, At, Bt) do { __builtin_amdgcn_s_setprio(1); _Pragma("unroll") for (int m = 0; m < 4; ++m) _Pragma("unroll") for (int n = 0; n < 2; ++n) _Pragma("unroll") for (int k = 0; k < 2; ++k) \
;         acc[ai][bj][m][n] = __builtin_amdgcn_mfma_f32_16x16x32_bf16(Bt[n][k], At[m][k], acc[ai][bj][m][n], 0, 0, 0); __builtin_amdgcn_s_setprio(0); } while (0)
; #define PG8_WAIT_V(n) asm volatile("s_waitcnt vmcnt(" #n ")" ::: "memory")
; template <class Epi, class Sched, bool ALIGN_EPI = false, bool SP2 = false>
; __device__ __forceinline__ void gemm_phase(PG8_LAS unsigned char* lds, const Gemm g, const Sched& S, const Epi& E) {
;     ...
;             PG8_LDB(B0, 0, 0); PG8_LDB(B1, 0, 1); PG8_SCHED; PG8_LDA(At, 0, 0); PG8_STAGE(PG8_SA(1, 1), a1 + hstep, voffA);
;             PG8_WAIT_V(8); PG8_WAIT_L(0); PG8_BAR; PG8_MMA(0, 0, At, B0); PG8_MMA(0, 1, At, B1); PG8_BAR; PG8_SCHED;
;             PG8_LDA(At, 0, 1); PG8_STAGE(PG8_SB(0, 0), b2, voffB); PG8_STAGE(PG8_SB(0, 1), b2 + hstep, voffB); PG8_STAGE(PG8_SA(0, 0), a2, voffA);
;             PG8_WAIT_V(8); PG8_WAIT_L(0); PG8_BAR; PG8_MMA(1, 0, At, B0); PG8_MMA(1, 1, At, B1); PG8_BAR; PG8_SCHED;
;             PG8_LDB(B0, 1, 0); PG8_LDB(B1, 1, 1); PG8_SCHED; PG8_LDA(At, 1, 0); PG8_STAGE(PG8_SA(0, 1), a2 + hstep, voffA);
;             PG8_WAIT_V(8); PG8_WAIT_L(0); PG8_BAR; PG8_MMA(0, 0, At, B0); PG8_MMA(0, 1, At, B1); PG8_BAR; PG8_SCHED;
;             PG8_LDA(At, 1, 1); PG8_STAGE(PG8_SB(1, 0), b3, voffB); PG8_STAGE(PG8_SB(1, 1), b3 + hstep, voffB); PG8_STAGE(PG8_SA(1, 0), a3, voffA);
;             PG8_WAIT_V(8); PG8_WAIT_L(0); PG8_BAR; PG8_MMA(1, 0, At, B0); PG8_MMA(1, 1, At, B1); PG8_BAR; PG8_SCHED;
	s_setprio 0
	s_add_i32 s63, s63, s47
	v_lshl_add_u64 v[178:179], v[178:179], 0, s[70:71]
	s_mov_b32 m0, s63
	ds_read_b128 v[174:177], v220 offset:49152
	ds_read_b128 v[186:189], v220 offset:50176
	ds_read_b128 v[190:193], v220 offset:51200
	ds_read_b128 v[224:227], v220 offset:52224
	ds_read_b128 v[230:233], v220 offset:53248
	ds_read_b128 v[234:237], v220 offset:54272
	ds_read_b128 v[238:241], v220 offset:55296
	ds_read_b128 v[242:245], v220 offset:56320
	global_load_lds_dwordx4 v[178:179], off
	s_add_i32 m0, s63, 0x2000
	s_add_u32 s94, s96, 0x40080
	v_lshl_add_u64 v[178:179], v[194:195], 0, s[70:71]
	s_addc_u32 s95, s97, 0
	s_add_i32 s63, s73, s47
	global_load_lds_dwordx4 v[178:179], off
	v_lshl_add_u64 v[178:179], s[94:95], 0, v[156:157]
	s_mov_b32 m0, s63
	s_nop 0
	global_load_lds_dwordx4 v[178:179], off
	v_lshl_add_u64 v[178:179], s[94:95], 0, v[152:153]
	s_add_i32 m0, s63, 0x2000
	s_nop 0
	global_load_lds_dwordx4 v[178:179], off
	v_lshl_add_u64 v[178:179], v[246:247], 0, s[70:71]
	s_mov_b32 m0, s68
	s_nop 0
	global_load_lds_dwordx4 v[178:179], off
	v_lshl_add_u64 v[178:179], v[248:249], 0, s[70:71]
	s_mov_b32 m0, s76
	s_nop 0
	global_load_lds_dwordx4 v[178:179], off
	s_waitcnt vmcnt(8)
	s_waitcnt lgkmcnt(0)
	s_setprio 1
	s_barrier
	v_mfma_f32_16x16x32_bf16 v[60:63], v[128:131], v[174:177], v[60:63]
	v_mfma_f32_16x16x32_bf16 v[56:59], v[136:139], v[174:177], v[56:59]
	v_mfma_f32_16x16x32_bf16 v[48:51], v[128:131], v[190:193], v[48:51]
	v_mfma_f32_16x16x32_bf16 v[40:43], v[136:139], v[190:193], v[40:43]
	v_mfma_f32_16x16x32_bf16 v[32:35], v[128:131], v[230:233], v[32:35]
	v_mfma_f32_16x16x32_bf16 v[24:27], v[136:139], v[230:233], v[24:27]
	v_mfma_f32_16x16x32_bf16 v[16:19], v[128:131], v[238:241], v[16:19]
	v_mfma_f32_16x16x32_bf16 v[8:11], v[136:139], v[238:241], v[8:11]
	v_mfma_f32_16x16x32_bf16 v[60:63], v[132:135], v[186:189], v[60:63]
	v_mfma_f32_16x16x32_bf16 v[56:59], v[140:143], v[186:189], v[56:59]
	v_mfma_f32_16x16x32_bf16 v[48:51], v[132:135], v[224:227], v[48:51]
	v_mfma_f32_16x16x32_bf16 v[40:43], v[140:143], v[224:227], v[40:43]
	v_mfma_f32_16x16x32_bf16 v[32:35], v[132:135], v[234:237], v[32:35]
	v_mfma_f32_16x16x32_bf16 v[24:27], v[140:143], v[234:237], v[24:27]
	v_mfma_f32_16x16x32_bf16 v[16:19], v[132:135], v[242:245], v[16:19]
	v_mfma_f32_16x16x32_bf16 v[8:11], v[140:143], v[242:245], v[8:11]
	s_setprio 0
	s_setprio 1
	v_mfma_f32_16x16x32_bf16 v[52:55], v[144:147], v[174:177], v[52:55]
	v_mfma_f32_16x16x32_bf16 v[44:47], v[166:169], v[174:177], v[44:47]
	v_mfma_f32_16x16x32_bf16 v[36:39], v[144:147], v[190:193], v[36:39]
	v_mfma_f32_16x16x32_bf16 v[28:31], v[166:169], v[190:193], v[28:31]
	v_mfma_f32_16x16x32_bf16 v[20:23], v[144:147], v[230:233], v[20:23]
	v_mfma_f32_16x16x32_bf16 v[12:15], v[166:169], v[230:233], v[12:15]
	v_mfma_f32_16x16x32_bf16 v[4:7], v[144:147], v[238:241], v[4:7]
	v_mfma_f32_16x16x32_bf16 v[0:3], v[166:169], v[238:241], v[0:3]
	v_mfma_f32_16x16x32_bf16 v[52:55], v[148:151], v[186:189], v[52:55]
	v_mfma_f32_16x16x32_bf16 v[44:47], v[170:173], v[186:189], v[44:47]
	v_mfma_f32_16x16x32_bf16 v[36:39], v[148:151], v[224:227], v[36:39]
	v_mfma_f32_16x16x32_bf16 v[28:31], v[170:173], v[224:227], v[28:31]
	v_mfma_f32_16x16x32_bf16 v[20:23], v[148:151], v[234:237], v[20:23]
	v_mfma_f32_16x16x32_bf16 v[12:15], v[170:173], v[234:237], v[12:15]
	v_mfma_f32_16x16x32_bf16 v[4:7], v[148:151], v[242:245], v[4:7]
	v_mfma_f32_16x16x32_bf16 v[0:3], v[170:173], v[242:245], v[0:3]
	s_barrier
	s_setprio 0
	s_add_i32 s62, s62, 2
	s_add_u32 s14, s14, 0x100
	s_addc_u32 s15, s15, 0
	s_add_u32 s51, s51, 0x100
	s_addc_u32 s53, s53, 0
	s_cmp_gt_u32 s62, 13
.LBB0_676:
	s_add_u32 s63, s14, 0xfffc0080
	s_addc_u32 s73, s15, -1
	s_add_i32 s93, 0, 0x10000
	s_cmp_eq_u32 s62, 12
	s_cselect_b32 vcc_hi, s22, s73
	s_cselect_b32 vcc_lo, s23, s63
	s_cselect_b32 s97, s38, s53
	s_cselect_b32 s96, s39, s51
	s_add_i32 s63, 0, 0x14000
	v_add_u32_e32 v140, s93, v197
	v_add_u32_e32 v170, s63, v197
	ds_read_b128 v[128:131], v140
	ds_read_b128 v[132:135], v140 offset:1024
	ds_read_b128 v[136:139], v140 offset:2048
	ds_read_b128 v[140:143], v140 offset:3072
	ds_read_b128 v[144:147], v170
	ds_read_b128 v[148:151], v170 offset:1024
	ds_read_b128 v[166:169], v170 offset:2048
	ds_read_b128 v[170:173], v170 offset:3072
	v_lshl_add_u64 v[178:179], s[14:15], 0, v[162:163]
	s_add_i32 m0, s56, 0xc000
	ds_read_b128 v[174:177], v220
	ds_read_b128 v[186:189], v220 offset:1024
	ds_read_b128 v[190:193], v220 offset:2048
	ds_read_b128 v[224:227], v220 offset:3072
	ds_read_b128 v[230:233], v220 offset:4096
	ds_read_b128 v[234:237], v220 offset:5120
	ds_read_b128 v[238:241], v220 offset:6144
	ds_read_b128 v[242:245], v220 offset:7168
	global_load_lds_dwordx4 v[178:179], off
	v_lshl_add_u64 v[178:179], s[14:15], 0, v[164:165]
	s_add_i32 m0, s56, 0xe000
	s_nop 0
	global_load_lds_dwordx4 v[178:179], off
	s_waitcnt vmcnt(8)
	s_waitcnt lgkmcnt(0)
	s_setprio 1
	s_barrier
; #define PG8_STAGE(bufoff, gbase, voff) do { _Pragma("unroll") for (int _i = 0; _i < 2; ++_i) \
;         __builtin_amdgcn_global_load_lds((const unsigned*)((const char*)(gbase) + (voff)[_i]), (PG8_LAS unsigned*)(lds + (bufoff) + ldsw + _i * 8192), 16, 0, 0); } while (0)
; #define PG8_LDA(dst, b, h) do { _Pragma("unroll") for (int m = 0; m < 4; ++m) _Pragma("unroll") for (int k = 0; k < 2; ++k) dst[m][k] = *(const PG8_LAS bf16x8*)(lds + PG8_SA(b, h) + aoff + m * 2048 + k * 1024); } while (0)
; #define PG8_LDB(dst, b, h) do { _Pragma("unroll") for (int n = 0; n < 2; ++n) _Pragma("unroll") for (int k = 0; k < 2; ++k) dst[n][k] = *(const PG8_LAS bf16x8*)(lds + PG8_SB(b, h) + boff + n * 2048 + k * 1024); } while (0)
; #define PG8_MMA(ai, bj, At, Bt) do { __builtin_amdgcn_s_setprio(1); _Pragma("unroll") for (int m = 0; m < 4; ++m) _Pragma("unroll") for (int n = 0; n < 2; ++n) _Pragma("unroll") for (int k = 0; k < 2; ++k) \
;         acc[ai][bj][m][n] = __builtin_amdgcn_mfma_f32_16x16x32_bf16(Bt[n][k], At[m][k], acc[ai][bj][m][n], 0, 0, 0); __builtin_amdgcn_s_setprio(0); } while (0)
; #define PG8_WAIT_V(n) asm volatile("s_waitcnt vmcnt(" #n ")" ::: "memory")
; template <class Epi, class Sched, bool ALIGN_EPI = false, bool SP2 = false>
; __device__ __forceinline__ void gemm_phase(PG8_LAS unsigned char* lds, const Gemm g, const Sched& S, const Epi& E) {
;     ...
;             PG8_LDB(B0, 0, 0); PG8_LDB(B1, 0, 1); PG8_SCHED; PG8_LDA(At, 0, 0); PG8_STAGE(PG8_SA(1, 1), a1 + hstep, voffA);
;             PG8_WAIT_V(8); PG8_WAIT_L(0); PG8_BAR; PG8_MMA(0, 0, At, B0); PG8_MMA(0, 1, At, B1); PG8_BAR; PG8_SCHED;
;             PG8_LDA(At, 0, 1); PG8_STAGE(PG8_SB(0, 0), b2, voffB); PG8_STAGE(PG8_SB(0, 1), b2 + hstep, voffB); PG8_STAGE(PG8_SA(0, 0), a2, voffA);
;             PG8_WAIT_V(8); PG8_WAIT_L(0); PG8_BAR; PG8_MMA(1, 0, At, B0); PG8_MMA(1, 1, At, B1); PG8_BAR; PG8_SCHED;
;             PG8_LDB(B0, 1, 0); PG8_LDB(B1, 1, 1); PG8_SCHED; PG8_LDA(At, 1, 0); PG8_STAGE(PG8_SA(0, 1), a2 + hstep, voffA);
;             PG8_WAIT_V(8); PG8_WAIT_L(0); PG8_BAR; PG8_MMA(0, 0, At, B0); PG8_MMA(0, 1, At, B1); PG8_BAR; PG8_SCHED;
;             PG8_LDA(At, 1, 1); PG8_STAGE(PG8_SB(1, 0), b3, voffB); PG8_STAGE(PG8_SB(1, 1), b3 + hstep, voffB); PG8_STAGE(PG8_SA(1, 0), a3, voffA);
;             PG8_WAIT_V(8); PG8_WAIT_L(0); PG8_BAR; PG8_MMA(1, 0, At, B0); PG8_MMA(1, 1, At, B1); PG8_BAR; PG8_SCHED;
	v_mfma_f32_16x16x32_bf16 v[124:127], v[128:131], v[174:177], v[124:127]
	v_mfma_f32_16x16x32_bf16 v[120:123], v[136:139], v[174:177], v[120:123]
	v_mfma_f32_16x16x32_bf16 v[112:115], v[128:131], v[190:193], v[112:115]
	v_mfma_f32_16x16x32_bf16 v[104:107], v[136:139], v[190:193], v[104:107]
	v_mfma_f32_16x16x32_bf16 v[96:99], v[128:131], v[230:233], v[96:99]
	v_mfma_f32_16x16x32_bf16 v[88:91], v[136:139], v[230:233], v[88:91]
	v_mfma_f32_16x16x32_bf16 v[80:83], v[128:131], v[238:241], v[80:83]
	v_mfma_f32_16x16x32_bf16 v[72:75], v[136:139], v[238:241], v[72:75]
	v_mfma_f32_16x16x32_bf16 v[124:127], v[132:135], v[186:189], v[124:127]
	v_mfma_f32_16x16x32_bf16 v[120:123], v[140:143], v[186:189], v[120:123]
	v_mfma_f32_16x16x32_bf16 v[112:115], v[132:135], v[224:227], v[112:115]
	v_mfma_f32_16x16x32_bf16 v[104:107], v[140:143], v[224:227], v[104:107]
	v_mfma_f32_16x16x32_bf16 v[96:99], v[132:135], v[234:237], v[96:99]
	v_mfma_f32_16x16x32_bf16 v[88:91], v[140:143], v[234:237], v[88:91]
	v_mfma_f32_16x16x32_bf16 v[80:83], v[132:135], v[242:245], v[80:83]
	v_mfma_f32_16x16x32_bf16 v[72:75], v[140:143], v[242:245], v[72:75]
	s_setprio 0
	s_setprio 1
	v_mfma_f32_16x16x32_bf16 v[116:119], v[144:147], v[174:177], v[116:119]
	v_mfma_f32_16x16x32_bf16 v[108:111], v[166:169], v[174:177], v[108:111]
	v_mfma_f32_16x16x32_bf16 v[100:103], v[144:147], v[190:193], v[100:103]
	v_mfma_f32_16x16x32_bf16 v[92:95], v[166:169], v[190:193], v[92:95]
	v_mfma_f32_16x16x32_bf16 v[84:87], v[144:147], v[230:233], v[84:87]
	v_mfma_f32_16x16x32_bf16 v[76:79], v[166:169], v[230:233], v[76:79]
	v_mfma_f32_16x16x32_bf16 v[68:71], v[144:147], v[238:241], v[68:71]
	v_mfma_f32_16x16x32_bf16 v[64:67], v[166:169], v[238:241], v[64:67]
	v_mfma_f32_16x16x32_bf16 v[116:119], v[148:151], v[186:189], v[116:119]
	v_mfma_f32_16x16x32_bf16 v[108:111], v[170:173], v[186:189], v[108:111]
	v_mfma_f32_16x16x32_bf16 v[100:103], v[148:151], v[224:227], v[100:103]
	v_mfma_f32_16x16x32_bf16 v[92:95], v[170:173], v[224:227], v[92:95]
	v_mfma_f32_16x16x32_bf16 v[84:87], v[148:151], v[234:237], v[84:87]
	v_mfma_f32_16x16x32_bf16 v[76:79], v[170:173], v[234:237], v[76:79]
	v_mfma_f32_16x16x32_bf16 v[68:71], v[148:151], v[242:245], v[68:71]
	v_mfma_f32_16x16x32_bf16 v[64:67], v[170:173], v[242:245], v[64:67]
	s_barrier
	s_setprio 0
	s_add_i32 s73, s93, s47
	v_lshl_add_u64 v[178:179], s[96:97], 0, v[156:157]
	s_mov_b32 m0, s73
	ds_read_b128 v[174:177], v220 offset:16384
	ds_read_b128 v[186:189], v220 offset:17408
	ds_read_b128 v[190:193], v220 offset:18432
	ds_read_b128 v[224:227], v220 offset:19456
	ds_read_b128 v[230:233], v220 offset:20480
	ds_read_b128 v[234:237], v220 offset:21504
	ds_read_b128 v[238:241], v220 offset:22528
	ds_read_b128 v[242:245], v220 offset:23552
	global_load_lds_dwordx4 v[178:179], off
	s_add_i32 m0, s73, 0x2000
	s_add_u32 s94, s96, 0x40000
	v_lshl_add_u64 v[194:195], s[96:97], 0, v[152:153]
	s_addc_u32 s95, s97, 0
	s_add_i32 s63, s63, s47
	global_load_lds_dwordx4 v[194:195], off
	v_lshl_add_u64 v[246:247], s[94:95], 0, v[156:157]
	s_mov_b32 m0, s63
	v_lshl_add_u64 v[248:249], vcc, 0, v[154:155]
	global_load_lds_dwordx4 v[246:247], off
	v_lshl_add_u64 v[246:247], s[94:95], 0, v[152:153]
	s_add_i32 m0, s63, 0x2000
	s_nop 0
	global_load_lds_dwordx4 v[246:247], off
	v_lshl_add_u64 v[246:247], vcc, 0, v[158:159]
	s_mov_b32 m0, s56
	s_nop 0
	global_load_lds_dwordx4 v[246:247], off
	s_mov_b32 m0, s57
	s_nop 0
	global_load_lds_dwordx4 v[248:249], off
	s_waitcnt vmcnt(8)
	s_waitcnt lgkmcnt(0)
	s_setprio 1
	s_barrier
	v_mfma_f32_16x16x32_bf16 v[60:63], v[128:131], v[174:177], v[60:63]
	v_mfma_f32_16x16x32_bf16 v[56:59], v[136:139], v[174:177], v[56:59]
	v_mfma_f32_16x16x32_bf16 v[48:51], v[128:131], v[190:193], v[48:51]
	v_mfma_f32_16x16x32_bf16 v[40:43], v[136:139], v[190:193], v[40:43]
	v_mfma_f32_16x16x32_bf16 v[32:35], v[128:131], v[230:233], v[32:35]
	v_mfma_f32_16x16x32_bf16 v[24:27], v[136:139], v[230:233], v[24:27]
	v_mfma_f32_16x16x32_bf16 v[16:19], v[128:131], v[238:241], v[16:19]
	v_mfma_f32_16x16x32_bf16 v[8:11], v[136:139], v[238:241], v[8:11]
	v_mfma_f32_16x16x32_bf16 v[60:63], v[132:135], v[186:189], v[60:63]
	v_mfma_f32_16x16x32_bf16 v[56:59], v[140:143], v[186:189], v[56:59]
	v_mfma_f32_16x16x32_bf16 v[48:51], v[132:135], v[224:227], v[48:51]
	v_mfma_f32_16x16x32_bf16 v[40:43], v[140:143], v[224:227], v[40:43]
	v_mfma_f32_16x16x32_bf16 v[32:35], v[132:135], v[234:237], v[32:35]
	v_mfma_f32_16x16x32_bf16 v[24:27], v[140:143], v[234:237], v[24:27]
	v_mfma_f32_16x16x32_bf16 v[16:19], v[132:135], v[242:245], v[16:19]
	v_mfma_f32_16x16x32_bf16 v[8:11], v[140:143], v[242:245], v[8:11]
	s_setprio 0
	s_setprio 1
	v_mfma_f32_16x16x32_bf16 v[52:55], v[144:147], v[174:177], v[52:55]
	v_mfma_f32_16x16x32_bf16 v[44:47], v[166:169], v[174:177], v[44:47]
	v_mfma_f32_16x16x32_bf16 v[36:39], v[144:147], v[190:193], v[36:39]
	v_mfma_f32_16x16x32_bf16 v[28:31], v[166:169], v[190:193], v[28:31]
	v_mfma_f32_16x16x32_bf16 v[20:23], v[144:147], v[230:233], v[20:23]
	v_mfma_f32_16x16x32_bf16 v[12:15], v[166:169], v[230:233], v[12:15]
	v_mfma_f32_16x16x32_bf16 v[4:7], v[144:147], v[238:241], v[4:7]
	v_mfma_f32_16x16x32_bf16 v[0:3], v[166:169], v[238:241], v[0:3]
	v_mfma_f32_16x16x32_bf16 v[52:55], v[148:151], v[186:189], v[52:55]
	v_mfma_f32_16x16x32_bf16 v[44:47], v[170:173], v[186:189], v[44:47]
	v_mfma_f32_16x16x32_bf16 v[36:39], v[148:151], v[224:227], v[36:39]
	v_mfma_f32_16x16x32_bf16 v[28:31], v[170:173], v[224:227], v[28:31]
	v_mfma_f32_16x16x32_bf16 v[20:23], v[148:151], v[234:237], v[20:23]
	v_mfma_f32_16x16x32_bf16 v[12:15], v[170:173], v[234:237], v[12:15]
	v_mfma_f32_16x16x32_bf16 v[4:7], v[148:151], v[242:245], v[4:7]
	v_mfma_f32_16x16x32_bf16 v[0:3], v[170:173], v[242:245], v[0:3]
	s_barrier
; #define PG8_STAGE(bufoff, gbase, voff) do { _Pragma("unroll") for (int _i = 0; _i < 2; ++_i) \
;         __builtin_amdgcn_global_load_lds((const unsigned*)((const char*)(gbase) + (voff)[_i]), (PG8_LAS unsigned*)(lds + (bufoff) + ldsw + _i * 8192), 16, 0, 0); } while (0)
; #define PG8_LDA(dst, b, h) do { _Pragma("unroll") for (int m = 0; m < 4; ++m) _Pragma("unroll") for (int k = 0; k < 2; ++k) dst[m][k] = *(const PG8_LAS bf16x8*)(lds + PG8_SA(b, h) + aoff + m * 2048 + k * 1024); } while (0)
; #define PG8_LDB(dst, b, h) do { _Pragma("unroll") for (int n = 0; n < 2; ++n) _Pragma("unroll") for (int k = 0; k < 2; ++k) dst[n][k] = *(const PG8_LAS bf16x8*)(lds + PG8_SB(b, h) + boff + n * 2048 + k * 1024); } while (0)
; #define PG8_MMA(ai, bj, At, Bt) do { __builtin_amdgcn_s_setprio(1); _Pragma("unroll") for (int m = 0; m < 4; ++m) _Pragma("unroll") for (int n = 0; n < 2; ++n) _Pragma("unroll") for (int k = 0; k < 2; ++k) \
;         acc[ai][bj][m][n] = __builtin_amdgcn_mfma_f32_16x16x32_bf16(Bt[n][k], At[m][k], acc[ai][bj][m][n], 0, 0, 0); __builtin_amdgcn_s_setprio(0); } while (0)
; #define PG8_WAIT_V(n) asm volatile("s_waitcnt vmcnt(" #n ")" ::: "memory")
; template <class Epi, class Sched, bool ALIGN_EPI = false, bool SP2 = false>
; __device__ __forceinline__ void gemm_phase(PG8_LAS unsigned char* lds, const Gemm g, const Sched& S, const Epi& E) {
;     ...
;             PG8_LDB(B0, 0, 0); PG8_LDB(B1, 0, 1); PG8_SCHED; PG8_LDA(At, 0, 0); PG8_STAGE(PG8_SA(1, 1), a1 + hstep, voffA);
;             PG8_WAIT_V(8); PG8_WAIT_L(0); PG8_BAR; PG8_MMA(0, 0, At, B0); PG8_MMA(0, 1, At, B1); PG8_BAR; PG8_SCHED;
;             PG8_LDA(At, 0, 1); PG8_STAGE(PG8_SB(0, 0), b2, voffB); PG8_STAGE(PG8_SB(0, 1), b2 + hstep, voffB); PG8_STAGE(PG8_SA(0, 0), a2, voffA);
;             PG8_WAIT_V(8); PG8_WAIT_L(0); PG8_BAR; PG8_MMA(1, 0, At, B0); PG8_MMA(1, 1, At, B1); PG8_BAR; PG8_SCHED;
;             PG8_LDB(B0, 1, 0); PG8_LDB(B1, 1, 1); PG8_SCHED; PG8_LDA(At, 1, 0); PG8_STAGE(PG8_SA(0, 1), a2 + hstep, voffA);
;             PG8_WAIT_V(8); PG8_WAIT_L(0); PG8_BAR; PG8_MMA(0, 0, At, B0); PG8_MMA(0, 1, At, B1); PG8_BAR; PG8_SCHED;
;             PG8_LDA(At, 1, 1); PG8_STAGE(PG8_SB(1, 0), b3, voffB); PG8_STAGE(PG8_SB(1, 1), b3 + hstep, voffB); PG8_STAGE(PG8_SA(1, 0), a3, voffA);
;             PG8_WAIT_V(8); PG8_WAIT_L(0); PG8_BAR; PG8_MMA(1, 0, At, B0); PG8_MMA(1, 1, At, B1); PG8_BAR; PG8_SCHED;
	s_setprio 0
	s_add_i32 s63, 0, 0x18000
	s_add_i32 s73, 0, 0x1c000
	v_add_u32_e32 v140, s63, v197
	v_add_u32_e32 v170, s73, v197
	ds_read_b128 v[128:131], v140
	ds_read_b128 v[132:135], v140 offset:1024
	ds_read_b128 v[136:139], v140 offset:2048
	ds_read_b128 v[140:143], v140 offset:3072
	ds_read_b128 v[144:147], v170
	ds_read_b128 v[148:151], v170 offset:1024
	ds_read_b128 v[166:169], v170 offset:2048
	ds_read_b128 v[170:173], v170 offset:3072
	s_add_u32 s94, vcc_lo, 0x40000
	s_addc_u32 s95, vcc_hi, 0
	s_mov_b32 m0, s58
	v_lshl_add_u64 v[250:251], s[94:95], 0, v[158:159]
	ds_read_b128 v[174:177], v220 offset:32768
	ds_read_b128 v[186:189], v220 offset:33792
	ds_read_b128 v[190:193], v220 offset:34816
	ds_read_b128 v[224:227], v220 offset:35840
	ds_read_b128 v[230:233], v220 offset:36864
	ds_read_b128 v[234:237], v220 offset:37888
	ds_read_b128 v[238:241], v220 offset:38912
	ds_read_b128 v[242:245], v220 offset:39936
	global_load_lds_dwordx4 v[250:251], off
	v_lshl_add_u64 v[250:251], s[94:95], 0, v[154:155]
	s_mov_b32 m0, s59
	s_nop 0
	global_load_lds_dwordx4 v[250:251], off
	s_waitcnt vmcnt(8)
	s_waitcnt lgkmcnt(0)
	s_setprio 1
	s_barrier
	v_mfma_f32_16x16x32_bf16 v[124:127], v[128:131], v[174:177], v[124:127]
	v_mfma_f32_16x16x32_bf16 v[120:123], v[136:139], v[174:177], v[120:123]
	v_mfma_f32_16x16x32_bf16 v[112:115], v[128:131], v[190:193], v[112:115]
	v_mfma_f32_16x16x32_bf16 v[104:107], v[136:139], v[190:193], v[104:107]
	v_mfma_f32_16x16x32_bf16 v[96:99], v[128:131], v[230:233], v[96:99]
	v_mfma_f32_16x16x32_bf16 v[88:91], v[136:139], v[230:233], v[88:91]
	v_mfma_f32_16x16x32_bf16 v[80:83], v[128:131], v[238:241], v[80:83]
	v_mfma_f32_16x16x32_bf16 v[72:75], v[136:139], v[238:241], v[72:75]
	v_mfma_f32_16x16x32_bf16 v[124:127], v[132:135], v[186:189], v[124:127]
	v_mfma_f32_16x16x32_bf16 v[120:123], v[140:143], v[186:189], v[120:123]
	v_mfma_f32_16x16x32_bf16 v[112:115], v[132:135], v[224:227], v[112:115]
	v_mfma_f32_16x16x32_bf16 v[104:107], v[140:143], v[224:227], v[104:107]
	v_mfma_f32_16x16x32_bf16 v[96:99], v[132:135], v[234:237], v[96:99]
	v_mfma_f32_16x16x32_bf16 v[88:91], v[140:143], v[234:237], v[88:91]
	v_mfma_f32_16x16x32_bf16 v[80:83], v[132:135], v[242:245], v[80:83]
	v_mfma_f32_16x16x32_bf16 v[72:75], v[140:143], v[242:245], v[72:75]
	s_setprio 0
	s_setprio 1
	v_mfma_f32_16x16x32_bf16 v[116:119], v[144:147], v[174:177], v[116:119]
	v_mfma_f32_16x16x32_bf16 v[108:111], v[166:169], v[174:177], v[108:111]
	v_mfma_f32_16x16x32_bf16 v[100:103], v[144:147], v[190:193], v[100:103]
	v_mfma_f32_16x16x32_bf16 v[92:95], v[166:169], v[190:193], v[92:95]
	v_mfma_f32_16x16x32_bf16 v[84:87], v[144:147], v[230:233], v[84:87]
	v_mfma_f32_16x16x32_bf16 v[76:79], v[166:169], v[230:233], v[76:79]
	v_mfma_f32_16x16x32_bf16 v[68:71], v[144:147], v[238:241], v[68:71]
	v_mfma_f32_16x16x32_bf16 v[64:67], v[166:169], v[238:241], v[64:67]
	v_mfma_f32_16x16x32_bf16 v[116:119], v[148:151], v[186:189], v[116:119]
	v_mfma_f32_16x16x32_bf16 v[108:111], v[170:173], v[186:189], v[108:111]
	v_mfma_f32_16x16x32_bf16 v[100:103], v[148:151], v[224:227], v[100:103]
	v_mfma_f32_16x16x32_bf16 v[92:95], v[170:173], v[224:227], v[92:95]
	v_mfma_f32_16x16x32_bf16 v[84:87], v[148:151], v[234:237], v[84:87]
	v_mfma_f32_16x16x32_bf16 v[76:79], v[170:173], v[234:237], v[76:79]
	v_mfma_f32_16x16x32_bf16 v[68:71], v[148:151], v[242:245], v[68:71]
	v_mfma_f32_16x16x32_bf16 v[64:67], v[170:173], v[242:245], v[64:67]
	s_barrier
; #define PG8_STAGE(bufoff, gbase, voff) do { _Pragma("unroll") for (int _i = 0; _i < 2; ++_i) \
;         __builtin_amdgcn_global_load_lds((const unsigned*)((const char*)(gbase) + (voff)[_i]), (PG8_LAS unsigned*)(lds + (bufoff) + ldsw + _i * 8192), 16, 0, 0); } while (0)
; #define PG8_LDA(dst, b, h) do { _Pragma("unroll") for (int m = 0; m < 4; ++m) _Pragma("unroll") for (int k = 0; k < 2; ++k) dst[m][k] = *(const PG8_LAS bf16x8*)(lds + PG8_SA(b, h) + aoff + m * 2048 + k * 1024); } while (0)
; #define PG8_LDB(dst, b, h) do { _Pragma("unroll") for (int n = 0; n < 2; ++n) _Pragma("unroll") for (int k = 0; k < 2; ++k) dst[n][k] = *(const PG8_LAS bf16x8*)(lds + PG8_SB(b, h) + boff + n * 2048 + k * 1024); } while (0)
; #define PG8_MMA(ai, bj, At, Bt) do { __builtin_amdgcn_s_setprio(1); _Pragma("unroll") for (int m = 0; m < 4; ++m) _Pragma("unroll") for (int n = 0; n < 2; ++n) _Pragma("unroll") for (int k = 0; k < 2; ++k) \
;         acc[ai][bj][m][n] = __builtin_amdgcn_mfma_f32_16x16x32_bf16(Bt[n][k], At[m][k], acc[ai][bj][m][n], 0, 0, 0); __builtin_amdgcn_s_setprio(0); } while (0)
; template <class Epi, class Sched, bool ALIGN_EPI = false, bool SP2 = false>
; __device__ __forceinline__ void gemm_phase(PG8_LAS unsigned char* lds, const Gemm g, const Sched& S, const Epi& E) {
;     ...
;             PG8_LDB(B0, 0, 0); PG8_LDB(B1, 0, 1); PG8_SCHED; PG8_LDA(At, 0, 0); PG8_STAGE(PG8_SA(1, 1), a1 + hstep, voffA);
;             PG8_WAIT_V(8); PG8_WAIT_L(0); PG8_BAR; PG8_MMA(0, 0, At, B0); PG8_MMA(0, 1, At, B1); PG8_BAR; PG8_SCHED;
;             PG8_LDA(At, 0, 1); PG8_STAGE(PG8_SB(0, 0), b2, voffB); PG8_STAGE(PG8_SB(0, 1), b2 + hstep, voffB); PG8_STAGE(PG8_SA(0, 0), a2, voffA);
;             PG8_WAIT_V(8); PG8_WAIT_L(0); PG8_BAR; PG8_MMA(1, 0, At, B0); PG8_MMA(1, 1, At, B1); PG8_BAR; PG8_SCHED;
;             PG8_LDB(B0, 1, 0); PG8_LDB(B1, 1, 1); PG8_SCHED; PG8_LDA(At, 1, 0); PG8_STAGE(PG8_SA(0, 1), a2 + hstep, voffA);
;             PG8_WAIT_V(8); PG8_WAIT_L(0); PG8_BAR; PG8_MMA(0, 0, At, B0); PG8_MMA(0, 1, At, B1); PG8_BAR; PG8_SCHED;
;             PG8_LDA(At, 1, 1); PG8_STAGE(PG8_SB(1, 0), b3, voffB); PG8_STAGE(PG8_SB(1, 1), b3 + hstep, voffB); PG8_STAGE(PG8_SA(1, 0), a3, voffA);
;             PG8_WAIT_V(8); PG8_WAIT_L(0); PG8_BAR; PG8_MMA(1, 0, At, B0); PG8_MMA(1, 1, At, B1); PG8_BAR; PG8_SCHED;
;     ...
;         if constexpr (ALIGN_EPI) { if (wr == 0) PG8_BAR; }
	s_setprio 0
	s_add_i32 s63, s63, s47
	v_lshl_add_u64 v[178:179], v[178:179], 0, s[70:71]
	s_mov_b32 m0, s63
	ds_read_b128 v[174:177], v220 offset:49152
	ds_read_b128 v[186:189], v220 offset:50176
	ds_read_b128 v[190:193], v220 offset:51200
	ds_read_b128 v[224:227], v220 offset:52224
	ds_read_b128 v[230:233], v220 offset:53248
	ds_read_b128 v[234:237], v220 offset:54272
	ds_read_b128 v[238:241], v220 offset:55296
	ds_read_b128 v[242:245], v220 offset:56320
	global_load_lds_dwordx4 v[178:179], off
	s_add_i32 m0, s63, 0x2000
	s_add_u32 s94, s96, 0x40080
	v_lshl_add_u64 v[178:179], v[194:195], 0, s[70:71]
	s_addc_u32 s95, s97, 0
	s_add_i32 s63, s73, s47
	global_load_lds_dwordx4 v[178:179], off
	v_lshl_add_u64 v[178:179], s[94:95], 0, v[156:157]
	s_mov_b32 m0, s63
	s_nop 0
	global_load_lds_dwordx4 v[178:179], off
	v_lshl_add_u64 v[178:179], s[94:95], 0, v[152:153]
	s_add_i32 m0, s63, 0x2000
	s_nop 0
	global_load_lds_dwordx4 v[178:179], off
	v_lshl_add_u64 v[178:179], v[246:247], 0, s[70:71]
	s_mov_b32 m0, s68
	s_nop 0
	global_load_lds_dwordx4 v[178:179], off
	v_lshl_add_u64 v[178:179], v[248:249], 0, s[70:71]
	s_mov_b32 m0, s76
	s_nop 0
	global_load_lds_dwordx4 v[178:179], off
	s_waitcnt vmcnt(8)
	s_waitcnt lgkmcnt(0)
	s_setprio 1
	s_barrier
	v_mfma_f32_16x16x32_bf16 v[60:63], v[128:131], v[174:177], v[60:63]
	v_mfma_f32_16x16x32_bf16 v[56:59], v[136:139], v[174:177], v[56:59]
	v_mfma_f32_16x16x32_bf16 v[48:51], v[128:131], v[190:193], v[48:51]
	v_mfma_f32_16x16x32_bf16 v[40:43], v[136:139], v[190:193], v[40:43]
	v_mfma_f32_16x16x32_bf16 v[32:35], v[128:131], v[230:233], v[32:35]
	v_mfma_f32_16x16x32_bf16 v[24:27], v[136:139], v[230:233], v[24:27]
	v_mfma_f32_16x16x32_bf16 v[16:19], v[128:131], v[238:241], v[16:19]
	v_mfma_f32_16x16x32_bf16 v[8:11], v[136:139], v[238:241], v[8:11]
	v_mfma_f32_16x16x32_bf16 v[60:63], v[132:135], v[186:189], v[60:63]
	v_mfma_f32_16x16x32_bf16 v[56:59], v[140:143], v[186:189], v[56:59]
	v_mfma_f32_16x16x32_bf16 v[48:51], v[132:135], v[224:227], v[48:51]
	v_mfma_f32_16x16x32_bf16 v[40:43], v[140:143], v[224:227], v[40:43]
	v_mfma_f32_16x16x32_bf16 v[32:35], v[132:135], v[234:237], v[32:35]
	v_mfma_f32_16x16x32_bf16 v[24:27], v[140:143], v[234:237], v[24:27]
	v_mfma_f32_16x16x32_bf16 v[16:19], v[132:135], v[242:245], v[16:19]
	v_mfma_f32_16x16x32_bf16 v[8:11], v[140:143], v[242:245], v[8:11]
	s_setprio 0
	s_setprio 1
	v_mfma_f32_16x16x32_bf16 v[52:55], v[144:147], v[174:177], v[52:55]
	v_mfma_f32_16x16x32_bf16 v[44:47], v[166:169], v[174:177], v[44:47]
	v_mfma_f32_16x16x32_bf16 v[36:39], v[144:147], v[190:193], v[36:39]
	v_mfma_f32_16x16x32_bf16 v[28:31], v[166:169], v[190:193], v[28:31]
	v_mfma_f32_16x16x32_bf16 v[20:23], v[144:147], v[230:233], v[20:23]
	v_mfma_f32_16x16x32_bf16 v[12:15], v[166:169], v[230:233], v[12:15]
	v_mfma_f32_16x16x32_bf16 v[4:7], v[144:147], v[238:241], v[4:7]
	v_mfma_f32_16x16x32_bf16 v[0:3], v[166:169], v[238:241], v[0:3]
	v_mfma_f32_16x16x32_bf16 v[52:55], v[148:151], v[186:189], v[52:55]
	v_mfma_f32_16x16x32_bf16 v[44:47], v[170:173], v[186:189], v[44:47]
	v_mfma_f32_16x16x32_bf16 v[36:39], v[148:151], v[224:227], v[36:39]
	v_mfma_f32_16x16x32_bf16 v[28:31], v[170:173], v[224:227], v[28:31]
	v_mfma_f32_16x16x32_bf16 v[20:23], v[148:151], v[234:237], v[20:23]
	v_mfma_f32_16x16x32_bf16 v[12:15], v[170:173], v[234:237], v[12:15]
	v_mfma_f32_16x16x32_bf16 v[4:7], v[148:151], v[242:245], v[4:7]
	v_mfma_f32_16x16x32_bf16 v[0:3], v[170:173], v[242:245], v[0:3]
	s_barrier
	s_setprio 0
	s_add_i32 s62, s62, 2
	s_add_u32 s14, s14, 0x100
	s_addc_u32 s15, s15, 0
	s_add_u32 s51, s51, 0x100
	s_addc_u32 s53, s53, 0
	s_cmp_gt_u32 s62, 13
	s_cbranch_scc0 .LBB0_676
	s_and_b64 vcc, exec, s[44:45]
	s_cbranch_vccz .LBB0_679
	s_barrier

; #define PG8_STAGE(bufoff, gbase, voff) do { _Pragma("unroll") for (int _i = 0; _i < 2; ++_i) \
;         __builtin_amdgcn_global_load_lds((const unsigned*)((const char*)(gbase) + (voff)[_i]), (PG8_LAS unsigned*)(lds + (bufoff) + ldsw + _i * 8192), 16, 0, 0); } while (0)
; #define PG8_LDA(dst, b, h) do { _Pragma("unroll") for (int m = 0; m < 4; ++m) _Pragma("unroll") for (int k = 0; k < 2; ++k) dst[m][k] = *(const PG8_LAS bf16x8*)(lds + PG8_SA(b, h) + aoff + m * 2048 + k * 1024); } while (0)
; template <class Epi, class Sched, bool ALIGN_EPI = false, bool SP2 = false>
; __device__ __forceinline__ void gemm_phase(PG8_LAS unsigned char* lds, const Gemm g, const Sched& S, const Epi& E) {
;     ...
;         const bool has_next = S.next(ui + 1, nxt);
;         const char* nA = has_next ? (const char*)g.A + (size_t)nxt.pm * tstep : cA; const char* nB = has_next ? (const char*)g.Bt + (size_t)nxt.pn * tstep : cB;
;         for (int t = 0; t < nt; t += 2) {
;             const bool last = (t == nt - 2);
;             const char* a1 = cA + (size_t)(t + 1) * kstep;
;             const char* a2 = last ? nA : cA + (size_t)(t + 2) * kstep; const char* b2 = last ? nB : cB + (size_t)(t + 2) * kstep;
;             const char* a3 = a2 + kstep; const char* b3 = b2 + kstep;
;             if (last && has_next) S.a_ready(nxt);
;             if constexpr (SP2) {
;             PG8_LDB(B0, 0, 0); PG8_LDB(B1, 0, 1); PG8_SCHED; PG8_LDA(At, 0, 0); PG8_STAGE(PG8_SA(1, 1), a1 + hstep, voffA);
;             PG8_WAIT_V(8); PG8_WAIT_L(0); PG8_BAR; PG8_MMA(0, 0, At, B0); PG8_MMA(0, 1, At, B1); PG8_BAR; PG8_SCHED;
;             PG8_LDA(At, 0, 1); PG8_STAGE(PG8_SB(0, 0), b2, voffB); PG8_STAGE(PG8_SB(0, 1), b2 + hstep, voffB); PG8_STAGE(PG8_SA(0, 0), a2, voffA);
;             PG8_WAIT_V(8); PG8_WAIT_L(0); PG8_BAR; PG8_MMA(1, 0, At, B0); PG8_MMA(1, 1, At, B1); PG8_BAR; PG8_SCHED;
;             PG8_LDB(B0, 1, 0); PG8_LDB(B1, 1, 1); PG8_SCHED; PG8_LDA(At, 1, 0); PG8_STAGE(PG8_SA(0, 1), a2 + hstep, voffA);
;             PG8_WAIT_V(8); PG8_WAIT_L(0); PG8_BAR; PG8_MMA(0, 0, At, B0); PG8_MMA(0, 1, At, B1); PG8_BAR; PG8_SCHED;
;             PG8_LDA(At, 1, 1); PG8_STAGE(PG8_SB(1, 0), b3, voffB); PG8_STAGE(PG8_SB(1, 1), b3 + hstep, voffB); PG8_STAGE(PG8_SA(1, 0), a3, voffA);
;             PG8_WAIT_V(8); PG8_WAIT_L(0); PG8_BAR; PG8_MMA(1, 0, At, B0); PG8_MMA(1, 1, At, B1); PG8_BAR; PG8_SCHED;
.LBB0_898:
	s_ashr_i32 s53, s52, 31
	s_lshl_b64 s[22:23], s[52:53], 19
	s_add_u32 s54, s10, s22
	s_addc_u32 s55, s11, s23
	s_and_b64 s[22:23], s[6:7], exec
	s_cselect_b32 s22, s55, s9
	s_cselect_b32 s23, s54, s8
	s_ashr_i32 s51, s50, 31
	s_lshl_b64 s[76:77], s[50:51], 19
	s_add_u32 s96, s13, s76
	s_addc_u32 s97, s36, s77
	s_and_b64 s[76:77], s[6:7], exec
	s_cselect_b32 s51, s97, s61
	s_cselect_b32 s53, s96, s60
	s_add_u32 s8, s8, 0x40080
	s_addc_u32 s9, s9, 0
	s_add_u32 s63, s60, 0x100
	s_addc_u32 s68, s61, 0
	s_mov_b32 s73, -2
	s_waitcnt lgkmcnt(0)
	s_add_u32 s60, s8, 0xfffc0080
	s_addc_u32 s61, s9, -1
	s_add_i32 s76, 0, 0x10000
	s_cmp_eq_u32 s73, 12
	s_cselect_b32 vcc_hi, s22, s61
	s_cselect_b32 vcc_lo, s23, s60
	s_cselect_b32 s61, s51, s68
	s_cselect_b32 s60, s53, s63
	s_add_i32 s92, 0, 0x14000
	v_add_u32_e32 v100, s76, v173
	v_add_u32_e32 v166, s92, v173
	ds_read_b128 v[84:87], v100
	ds_read_b128 v[88:91], v100 offset:1024
	ds_read_b128 v[92:95], v100 offset:2048
	ds_read_b128 v[100:103], v100 offset:3072
	ds_read_b128 v[144:147], v166
	ds_read_b128 v[148:151], v166 offset:1024
	ds_read_b128 v[162:165], v166 offset:2048
	ds_read_b128 v[166:169], v166 offset:3072
	v_lshl_add_u64 v[170:171], s[8:9], 0, v[158:159]
	s_add_i32 m0, s38, 0xc000
	ds_read_b128 v[176:179], v175
	ds_read_b128 v[186:189], v175 offset:1024
	ds_read_b128 v[190:193], v175 offset:2048
	ds_read_b128 v[194:197], v175 offset:3072
	ds_read_b128 v[198:201], v175 offset:4096
	ds_read_b128 v[216:219], v175 offset:5120
	ds_read_b128 v[224:227], v175 offset:6144
	ds_read_b128 v[230:233], v175 offset:7168
	global_load_lds_dwordx4 v[170:171], off
	v_lshl_add_u64 v[170:171], s[8:9], 0, v[160:161]
	s_add_i32 m0, s38, 0xe000
	s_nop 0
	global_load_lds_dwordx4 v[170:171], off
	s_waitcnt vmcnt(8)
	s_waitcnt lgkmcnt(0)
	s_setprio 1
	s_barrier
	v_mfma_f32_16x16x32_bf16 v[140:143], v[84:87], v[176:179], 0
	v_mfma_f32_16x16x32_bf16 v[136:139], v[92:95], v[176:179], 0
	v_mfma_f32_16x16x32_bf16 v[124:127], v[84:87], v[190:193], 0
	v_mfma_f32_16x16x32_bf16 v[120:123], v[92:95], v[190:193], 0
	v_mfma_f32_16x16x32_bf16 v[108:111], v[84:87], v[198:201], 0
	v_mfma_f32_16x16x32_bf16 v[104:107], v[92:95], v[198:201], 0
	v_mfma_f32_16x16x32_bf16 v[76:79], v[84:87], v[224:227], 0
	v_mfma_f32_16x16x32_bf16 v[72:75], v[92:95], v[224:227], 0
	v_mfma_f32_16x16x32_bf16 v[140:143], v[88:91], v[186:189], v[140:143]
	v_mfma_f32_16x16x32_bf16 v[136:139], v[100:103], v[186:189], v[136:139]
	v_mfma_f32_16x16x32_bf16 v[124:127], v[88:91], v[194:197], v[124:127]
	v_mfma_f32_16x16x32_bf16 v[120:123], v[100:103], v[194:197], v[120:123]
	v_mfma_f32_16x16x32_bf16 v[108:111], v[88:91], v[216:219], v[108:111]
	v_mfma_f32_16x16x32_bf16 v[104:107], v[100:103], v[216:219], v[104:107]
	v_mfma_f32_16x16x32_bf16 v[76:79], v[88:91], v[230:233], v[76:79]
	v_mfma_f32_16x16x32_bf16 v[72:75], v[100:103], v[230:233], v[72:75]
	s_setprio 0
	s_setprio 1
	v_mfma_f32_16x16x32_bf16 v[132:135], v[144:147], v[176:179], 0
	v_mfma_f32_16x16x32_bf16 v[128:131], v[162:165], v[176:179], 0
	v_mfma_f32_16x16x32_bf16 v[116:119], v[144:147], v[190:193], 0
	v_mfma_f32_16x16x32_bf16 v[112:115], v[162:165], v[190:193], 0
	v_mfma_f32_16x16x32_bf16 v[96:99], v[144:147], v[198:201], 0
	v_mfma_f32_16x16x32_bf16 v[80:83], v[162:165], v[198:201], 0
	v_mfma_f32_16x16x32_bf16 v[68:71], v[144:147], v[224:227], 0
	v_mfma_f32_16x16x32_bf16 v[64:67], v[162:165], v[224:227], 0
	v_mfma_f32_16x16x32_bf16 v[132:135], v[148:151], v[186:189], v[132:135]
	v_mfma_f32_16x16x32_bf16 v[128:131], v[166:169], v[186:189], v[128:131]
	v_mfma_f32_16x16x32_bf16 v[116:119], v[148:151], v[194:197], v[116:119]
	v_mfma_f32_16x16x32_bf16 v[112:115], v[166:169], v[194:197], v[112:115]
	v_mfma_f32_16x16x32_bf16 v[96:99], v[148:151], v[216:219], v[96:99]
	v_mfma_f32_16x16x32_bf16 v[80:83], v[166:169], v[216:219], v[80:83]
	v_mfma_f32_16x16x32_bf16 v[68:71], v[148:151], v[230:233], v[68:71]
	v_mfma_f32_16x16x32_bf16 v[64:67], v[166:169], v[230:233], v[64:67]
	s_barrier
	s_setprio 0
	s_add_i32 s76, s76, s37
	v_lshl_add_u64 v[170:171], s[60:61], 0, v[180:181]
	s_mov_b32 m0, s76
	ds_read_b128 v[176:179], v175 offset:16384
	ds_read_b128 v[186:189], v175 offset:17408
	ds_read_b128 v[190:193], v175 offset:18432
	ds_read_b128 v[194:197], v175 offset:19456
	ds_read_b128 v[198:201], v175 offset:20480
	ds_read_b128 v[216:219], v175 offset:21504
	ds_read_b128 v[224:227], v175 offset:22528
	ds_read_b128 v[230:233], v175 offset:23552
	global_load_lds_dwordx4 v[170:171], off
	s_add_i32 m0, s76, 0x2000
	s_add_u32 s76, s60, 0x40000
	v_lshl_add_u64 v[202:203], s[60:61], 0, v[152:153]
	s_addc_u32 s77, s61, 0
	s_add_i32 s92, s92, s37
	global_load_lds_dwordx4 v[202:203], off
	v_lshl_add_u64 v[208:209], s[76:77], 0, v[180:181]
	s_mov_b32 m0, s92
	v_lshl_add_u64 v[214:215], vcc, 0, v[154:155]
	global_load_lds_dwordx4 v[208:209], off
	v_lshl_add_u64 v[208:209], s[76:77], 0, v[152:153]
	s_add_i32 m0, s92, 0x2000
	s_nop 0
	global_load_lds_dwordx4 v[208:209], off
	v_lshl_add_u64 v[208:209], vcc, 0, v[156:157]
	s_mov_b32 m0, s38
	s_nop 0
	global_load_lds_dwordx4 v[208:209], off
	s_mov_b32 m0, s39
	s_nop 0
	global_load_lds_dwordx4 v[214:215], off
	s_waitcnt vmcnt(8)
	s_waitcnt lgkmcnt(0)
	s_setprio 1
	s_barrier
; #define PG8_STAGE(bufoff, gbase, voff) do { _Pragma("unroll") for (int _i = 0; _i < 2; ++_i) \
;         __builtin_amdgcn_global_load_lds((const unsigned*)((const char*)(gbase) + (voff)[_i]), (PG8_LAS unsigned*)(lds + (bufoff) + ldsw + _i * 8192), 16, 0, 0); } while (0)
; #define PG8_LDA(dst, b, h) do { _Pragma("unroll") for (int m = 0; m < 4; ++m) _Pragma("unroll") for (int k = 0; k < 2; ++k) dst[m][k] = *(const PG8_LAS bf16x8*)(lds + PG8_SA(b, h) + aoff + m * 2048 + k * 1024); } while (0)
; #define PG8_LDB(dst, b, h) do { _Pragma("unroll") for (int n = 0; n < 2; ++n) _Pragma("unroll") for (int k = 0; k < 2; ++k) dst[n][k] = *(const PG8_LAS bf16x8*)(lds + PG8_SB(b, h) + boff + n * 2048 + k * 1024); } while (0)
; #define PG8_MMA(ai, bj, At, Bt) do { __builtin_amdgcn_s_setprio(1); _Pragma("unroll") for (int m = 0; m < 4; ++m) _Pragma("unroll") for (int n = 0; n < 2; ++n) _Pragma("unroll") for (int k = 0; k < 2; ++k) \
;         acc[ai][bj][m][n] = __builtin_amdgcn_mfma_f32_16x16x32_bf16(Bt[n][k], At[m][k], acc[ai][bj][m][n], 0, 0, 0); __builtin_amdgcn_s_setprio(0); } while (0)
; #define PG8_WAIT_V(n) asm volatile("s_waitcnt vmcnt(" #n ")" ::: "memory")
; template <class Epi, class Sched, bool ALIGN_EPI = false, bool SP2 = false>
; __device__ __forceinline__ void gemm_phase(PG8_LAS unsigned char* lds, const Gemm g, const Sched& S, const Epi& E) {
;     ...
;             PG8_LDB(B0, 0, 0); PG8_LDB(B1, 0, 1); PG8_SCHED; PG8_LDA(At, 0, 0); PG8_STAGE(PG8_SA(1, 1), a1 + hstep, voffA);
;             PG8_WAIT_V(8); PG8_WAIT_L(0); PG8_BAR; PG8_MMA(0, 0, At, B0); PG8_MMA(0, 1, At, B1); PG8_BAR; PG8_SCHED;
;             PG8_LDA(At, 0, 1); PG8_STAGE(PG8_SB(0, 0), b2, voffB); PG8_STAGE(PG8_SB(0, 1), b2 + hstep, voffB); PG8_STAGE(PG8_SA(0, 0), a2, voffA);
;             PG8_WAIT_V(8); PG8_WAIT_L(0); PG8_BAR; PG8_MMA(1, 0, At, B0); PG8_MMA(1, 1, At, B1); PG8_BAR; PG8_SCHED;
;             PG8_LDB(B0, 1, 0); PG8_LDB(B1, 1, 1); PG8_SCHED; PG8_LDA(At, 1, 0); PG8_STAGE(PG8_SA(0, 1), a2 + hstep, voffA);
;             PG8_WAIT_V(8); PG8_WAIT_L(0); PG8_BAR; PG8_MMA(0, 0, At, B0); PG8_MMA(0, 1, At, B1); PG8_BAR; PG8_SCHED;
;             PG8_LDA(At, 1, 1); PG8_STAGE(PG8_SB(1, 0), b3, voffB); PG8_STAGE(PG8_SB(1, 1), b3 + hstep, voffB); PG8_STAGE(PG8_SA(1, 0), a3, voffA);
;             PG8_WAIT_V(8); PG8_WAIT_L(0); PG8_BAR; PG8_MMA(1, 0, At, B0); PG8_MMA(1, 1, At, B1); PG8_BAR; PG8_SCHED;
	v_mfma_f32_16x16x32_bf16 v[60:63], v[84:87], v[176:179], 0
	v_mfma_f32_16x16x32_bf16 v[56:59], v[92:95], v[176:179], 0
	v_mfma_f32_16x16x32_bf16 v[44:47], v[84:87], v[190:193], 0
	v_mfma_f32_16x16x32_bf16 v[40:43], v[92:95], v[190:193], 0
	v_mfma_f32_16x16x32_bf16 v[28:31], v[84:87], v[198:201], 0
	v_mfma_f32_16x16x32_bf16 v[24:27], v[92:95], v[198:201], 0
	v_mfma_f32_16x16x32_bf16 v[12:15], v[84:87], v[224:227], 0
	v_mfma_f32_16x16x32_bf16 v[8:11], v[92:95], v[224:227], 0
	v_mfma_f32_16x16x32_bf16 v[60:63], v[88:91], v[186:189], v[60:63]
	v_mfma_f32_16x16x32_bf16 v[56:59], v[100:103], v[186:189], v[56:59]
	v_mfma_f32_16x16x32_bf16 v[44:47], v[88:91], v[194:197], v[44:47]
	v_mfma_f32_16x16x32_bf16 v[40:43], v[100:103], v[194:197], v[40:43]
	v_mfma_f32_16x16x32_bf16 v[28:31], v[88:91], v[216:219], v[28:31]
	v_mfma_f32_16x16x32_bf16 v[24:27], v[100:103], v[216:219], v[24:27]
	v_mfma_f32_16x16x32_bf16 v[12:15], v[88:91], v[230:233], v[12:15]
	v_mfma_f32_16x16x32_bf16 v[8:11], v[100:103], v[230:233], v[8:11]
	s_setprio 0
	s_setprio 1
	v_mfma_f32_16x16x32_bf16 v[52:55], v[144:147], v[176:179], 0
	v_mfma_f32_16x16x32_bf16 v[48:51], v[162:165], v[176:179], 0
	v_mfma_f32_16x16x32_bf16 v[36:39], v[144:147], v[190:193], 0
	v_mfma_f32_16x16x32_bf16 v[32:35], v[162:165], v[190:193], 0
	v_mfma_f32_16x16x32_bf16 v[20:23], v[144:147], v[198:201], 0
	v_mfma_f32_16x16x32_bf16 v[16:19], v[162:165], v[198:201], 0
	v_mfma_f32_16x16x32_bf16 v[4:7], v[144:147], v[224:227], 0
	v_mfma_f32_16x16x32_bf16 v[0:3], v[162:165], v[224:227], 0
	v_mfma_f32_16x16x32_bf16 v[52:55], v[148:151], v[186:189], v[52:55]
	v_mfma_f32_16x16x32_bf16 v[48:51], v[166:169], v[186:189], v[48:51]
	v_mfma_f32_16x16x32_bf16 v[36:39], v[148:151], v[194:197], v[36:39]
	v_mfma_f32_16x16x32_bf16 v[32:35], v[166:169], v[194:197], v[32:35]
	v_mfma_f32_16x16x32_bf16 v[20:23], v[148:151], v[216:219], v[20:23]
	v_mfma_f32_16x16x32_bf16 v[16:19], v[166:169], v[216:219], v[16:19]
	v_mfma_f32_16x16x32_bf16 v[4:7], v[148:151], v[230:233], v[4:7]
	v_mfma_f32_16x16x32_bf16 v[0:3], v[166:169], v[230:233], v[0:3]
	s_barrier
	s_setprio 0
	s_add_i32 s92, 0, 0x18000
	s_add_i32 s93, 0, 0x1c000
	v_add_u32_e32 v100, s92, v173
	v_add_u32_e32 v166, s93, v173
	ds_read_b128 v[84:87], v100
	ds_read_b128 v[88:91], v100 offset:1024
	ds_read_b128 v[92:95], v100 offset:2048
	ds_read_b128 v[100:103], v100 offset:3072
	ds_read_b128 v[144:147], v166
	ds_read_b128 v[148:151], v166 offset:1024
	ds_read_b128 v[162:165], v166 offset:2048
	ds_read_b128 v[166:169], v166 offset:3072
	s_add_u32 s76, vcc_lo, 0x40000
	s_addc_u32 s77, vcc_hi, 0
	s_mov_b32 m0, s46
	v_lshl_add_u64 v[220:221], s[76:77], 0, v[156:157]
	ds_read_b128 v[176:179], v175 offset:32768
	ds_read_b128 v[186:189], v175 offset:33792
	ds_read_b128 v[190:193], v175 offset:34816
	ds_read_b128 v[194:197], v175 offset:35840
	ds_read_b128 v[198:201], v175 offset:36864
	ds_read_b128 v[216:219], v175 offset:37888
	ds_read_b128 v[224:227], v175 offset:38912
	ds_read_b128 v[230:233], v175 offset:39936
	global_load_lds_dwordx4 v[220:221], off
	v_lshl_add_u64 v[220:221], s[76:77], 0, v[154:155]
	s_mov_b32 m0, s47
	s_nop 0
	global_load_lds_dwordx4 v[220:221], off
	s_waitcnt vmcnt(8)
	s_waitcnt lgkmcnt(0)
	s_setprio 1
	s_barrier
	v_mfma_f32_16x16x32_bf16 v[140:143], v[84:87], v[176:179], v[140:143]
	v_mfma_f32_16x16x32_bf16 v[136:139], v[92:95], v[176:179], v[136:139]
	v_mfma_f32_16x16x32_bf16 v[124:127], v[84:87], v[190:193], v[124:127]
	v_mfma_f32_16x16x32_bf16 v[120:123], v[92:95], v[190:193], v[120:123]
	v_mfma_f32_16x16x32_bf16 v[108:111], v[84:87], v[198:201], v[108:111]
	v_mfma_f32_16x16x32_bf16 v[104:107], v[92:95], v[198:201], v[104:107]
	v_mfma_f32_16x16x32_bf16 v[76:79], v[84:87], v[224:227], v[76:79]
	v_mfma_f32_16x16x32_bf16 v[72:75], v[92:95], v[224:227], v[72:75]
	v_mfma_f32_16x16x32_bf16 v[140:143], v[88:91], v[186:189], v[140:143]
	v_mfma_f32_16x16x32_bf16 v[136:139], v[100:103], v[186:189], v[136:139]
	v_mfma_f32_16x16x32_bf16 v[124:127], v[88:91], v[194:197], v[124:127]
	v_mfma_f32_16x16x32_bf16 v[120:123], v[100:103], v[194:197], v[120:123]
	v_mfma_f32_16x16x32_bf16 v[108:111], v[88:91], v[216:219], v[108:111]
	v_mfma_f32_16x16x32_bf16 v[104:107], v[100:103], v[216:219], v[104:107]
	v_mfma_f32_16x16x32_bf16 v[76:79], v[88:91], v[230:233], v[76:79]
	v_mfma_f32_16x16x32_bf16 v[72:75], v[100:103], v[230:233], v[72:75]
	s_setprio 0
	s_setprio 1
	v_mfma_f32_16x16x32_bf16 v[132:135], v[144:147], v[176:179], v[132:135]
	v_mfma_f32_16x16x32_bf16 v[128:131], v[162:165], v[176:179], v[128:131]
	v_mfma_f32_16x16x32_bf16 v[116:119], v[144:147], v[190:193], v[116:119]
	v_mfma_f32_16x16x32_bf16 v[112:115], v[162:165], v[190:193], v[112:115]
	v_mfma_f32_16x16x32_bf16 v[96:99], v[144:147], v[198:201], v[96:99]
	v_mfma_f32_16x16x32_bf16 v[80:83], v[162:165], v[198:201], v[80:83]
	v_mfma_f32_16x16x32_bf16 v[68:71], v[144:147], v[224:227], v[68:71]
	v_mfma_f32_16x16x32_bf16 v[64:67], v[162:165], v[224:227], v[64:67]
	v_mfma_f32_16x16x32_bf16 v[132:135], v[148:151], v[186:189], v[132:135]
	v_mfma_f32_16x16x32_bf16 v[128:131], v[166:169], v[186:189], v[128:131]
	v_mfma_f32_16x16x32_bf16 v[116:119], v[148:151], v[194:197], v[116:119]
	v_mfma_f32_16x16x32_bf16 v[112:115], v[166:169], v[194:197], v[112:115]
	v_mfma_f32_16x16x32_bf16 v[96:99], v[148:151], v[216:219], v[96:99]
	v_mfma_f32_16x16x32_bf16 v[80:83], v[166:169], v[216:219], v[80:83]
	v_mfma_f32_16x16x32_bf16 v[68:71], v[148:151], v[230:233], v[68:71]
	v_mfma_f32_16x16x32_bf16 v[64:67], v[166:169], v[230:233], v[64:67]
	s_barrier
; #define PG8_STAGE(bufoff, gbase, voff) do { _Pragma("unroll") for (int _i = 0; _i < 2; ++_i) \
;         __builtin_amdgcn_global_load_lds((const unsigned*)((const char*)(gbase) + (voff)[_i]), (PG8_LAS unsigned*)(lds + (bufoff) + ldsw + _i * 8192), 16, 0, 0); } while (0)
; #define PG8_LDA(dst, b, h) do { _Pragma("unroll") for (int m = 0; m < 4; ++m) _Pragma("unroll") for (int k = 0; k < 2; ++k) dst[m][k] = *(const PG8_LAS bf16x8*)(lds + PG8_SA(b, h) + aoff + m * 2048 + k * 1024); } while (0)
; #define PG8_LDB(dst, b, h) do { _Pragma("unroll") for (int n = 0; n < 2; ++n) _Pragma("unroll") for (int k = 0; k < 2; ++k) dst[n][k] = *(const PG8_LAS bf16x8*)(lds + PG8_SB(b, h) + boff + n * 2048 + k * 1024); } while (0)
; #define PG8_MMA(ai, bj, At, Bt) do { __builtin_amdgcn_s_setprio(1); _Pragma("unroll") for (int m = 0; m < 4; ++m) _Pragma("unroll") for (int n = 0; n < 2; ++n) _Pragma("unroll") for (int k = 0; k < 2; ++k) \
;         acc[ai][bj][m][n] = __builtin_amdgcn_mfma_f32_16x16x32_bf16(Bt[n][k], At[m][k], acc[ai][bj][m][n], 0, 0, 0); __builtin_amdgcn_s_setprio(0); } while (0)
; #define PG8_WAIT_V(n) asm volatile("s_waitcnt vmcnt(" #n ")" ::: "memory")
; template <class Epi, class Sched, bool ALIGN_EPI = false, bool SP2 = false>
; __device__ __forceinline__ void gemm_phase(PG8_LAS unsigned char* lds, const Gemm g, const Sched& S, const Epi& E) {
;     ...
;             PG8_LDB(B0, 0, 0); PG8_LDB(B1, 0, 1); PG8_SCHED; PG8_LDA(At, 0, 0); PG8_STAGE(PG8_SA(1, 1), a1 + hstep, voffA);
;             PG8_WAIT_V(8); PG8_WAIT_L(0); PG8_BAR; PG8_MMA(0, 0, At, B0); PG8_MMA(0, 1, At, B1); PG8_BAR; PG8_SCHED;
;             PG8_LDA(At, 0, 1); PG8_STAGE(PG8_SB(0, 0), b2, voffB); PG8_STAGE(PG8_SB(0, 1), b2 + hstep, voffB); PG8_STAGE(PG8_SA(0, 0), a2, voffA);
;             PG8_WAIT_V(8); PG8_WAIT_L(0); PG8_BAR; PG8_MMA(1, 0, At, B0); PG8_MMA(1, 1, At, B1); PG8_BAR; PG8_SCHED;
;             PG8_LDB(B0, 1, 0); PG8_LDB(B1, 1, 1); PG8_SCHED; PG8_LDA(At, 1, 0); PG8_STAGE(PG8_SA(0, 1), a2 + hstep, voffA);
;             PG8_WAIT_V(8); PG8_WAIT_L(0); PG8_BAR; PG8_MMA(0, 0, At, B0); PG8_MMA(0, 1, At, B1); PG8_BAR; PG8_SCHED;
;             PG8_LDA(At, 1, 1); PG8_STAGE(PG8_SB(1, 0), b3, voffB); PG8_STAGE(PG8_SB(1, 1), b3 + hstep, voffB); PG8_STAGE(PG8_SA(1, 0), a3, voffA);
;             PG8_WAIT_V(8); PG8_WAIT_L(0); PG8_BAR; PG8_MMA(1, 0, At, B0); PG8_MMA(1, 1, At, B1); PG8_BAR; PG8_SCHED;
	s_setprio 0
	s_add_i32 s76, s92, s37
	v_lshl_add_u64 v[170:171], v[170:171], 0, s[70:71]
	s_mov_b32 m0, s76
	ds_read_b128 v[176:179], v175 offset:49152
	ds_read_b128 v[186:189], v175 offset:50176
	ds_read_b128 v[190:193], v175 offset:51200
	ds_read_b128 v[194:197], v175 offset:52224
	ds_read_b128 v[198:201], v175 offset:53248
	ds_read_b128 v[216:219], v175 offset:54272
	ds_read_b128 v[224:227], v175 offset:55296
	ds_read_b128 v[230:233], v175 offset:56320
	global_load_lds_dwordx4 v[170:171], off
	s_add_i32 m0, s76, 0x2000
	s_add_u32 s60, s60, 0x40080
	v_lshl_add_u64 v[170:171], v[202:203], 0, s[70:71]
	s_addc_u32 s61, s61, 0
	s_add_i32 s76, s93, s37
	global_load_lds_dwordx4 v[170:171], off
	v_lshl_add_u64 v[170:171], s[60:61], 0, v[180:181]
	s_mov_b32 m0, s76
	s_nop 0
	global_load_lds_dwordx4 v[170:171], off
	v_lshl_add_u64 v[170:171], s[60:61], 0, v[152:153]
	s_add_i32 m0, s76, 0x2000
	s_nop 0
	global_load_lds_dwordx4 v[170:171], off
	v_lshl_add_u64 v[170:171], v[208:209], 0, s[70:71]
	s_mov_b32 m0, s57
	s_nop 0
	global_load_lds_dwordx4 v[170:171], off
	v_lshl_add_u64 v[170:171], v[214:215], 0, s[70:71]
	s_mov_b32 m0, s58
	s_nop 0
	global_load_lds_dwordx4 v[170:171], off
	s_waitcnt vmcnt(8)
	s_waitcnt lgkmcnt(0)
	s_setprio 1
	s_barrier
	v_mfma_f32_16x16x32_bf16 v[60:63], v[84:87], v[176:179], v[60:63]
	v_mfma_f32_16x16x32_bf16 v[56:59], v[92:95], v[176:179], v[56:59]
	v_mfma_f32_16x16x32_bf16 v[44:47], v[84:87], v[190:193], v[44:47]
	v_mfma_f32_16x16x32_bf16 v[40:43], v[92:95], v[190:193], v[40:43]
	v_mfma_f32_16x16x32_bf16 v[28:31], v[84:87], v[198:201], v[28:31]
	v_mfma_f32_16x16x32_bf16 v[24:27], v[92:95], v[198:201], v[24:27]
	v_mfma_f32_16x16x32_bf16 v[12:15], v[84:87], v[224:227], v[12:15]
	v_mfma_f32_16x16x32_bf16 v[8:11], v[92:95], v[224:227], v[8:11]
	v_mfma_f32_16x16x32_bf16 v[60:63], v[88:91], v[186:189], v[60:63]
	v_mfma_f32_16x16x32_bf16 v[56:59], v[100:103], v[186:189], v[56:59]
	v_mfma_f32_16x16x32_bf16 v[44:47], v[88:91], v[194:197], v[44:47]
	v_mfma_f32_16x16x32_bf16 v[40:43], v[100:103], v[194:197], v[40:43]
	v_mfma_f32_16x16x32_bf16 v[28:31], v[88:91], v[216:219], v[28:31]
	v_mfma_f32_16x16x32_bf16 v[24:27], v[100:103], v[216:219], v[24:27]
	v_mfma_f32_16x16x32_bf16 v[12:15], v[88:91], v[230:233], v[12:15]
	v_mfma_f32_16x16x32_bf16 v[8:11], v[100:103], v[230:233], v[8:11]
	s_setprio 0
	s_setprio 1
	v_mfma_f32_16x16x32_bf16 v[52:55], v[144:147], v[176:179], v[52:55]
	v_mfma_f32_16x16x32_bf16 v[48:51], v[162:165], v[176:179], v[48:51]
	v_mfma_f32_16x16x32_bf16 v[36:39], v[144:147], v[190:193], v[36:39]
	v_mfma_f32_16x16x32_bf16 v[32:35], v[162:165], v[190:193], v[32:35]
	v_mfma_f32_16x16x32_bf16 v[20:23], v[144:147], v[198:201], v[20:23]
	v_mfma_f32_16x16x32_bf16 v[16:19], v[162:165], v[198:201], v[16:19]
	v_mfma_f32_16x16x32_bf16 v[4:7], v[144:147], v[224:227], v[4:7]
	v_mfma_f32_16x16x32_bf16 v[0:3], v[162:165], v[224:227], v[0:3]
	v_mfma_f32_16x16x32_bf16 v[52:55], v[148:151], v[186:189], v[52:55]
	v_mfma_f32_16x16x32_bf16 v[48:51], v[166:169], v[186:189], v[48:51]
	v_mfma_f32_16x16x32_bf16 v[36:39], v[148:151], v[194:197], v[36:39]
	v_mfma_f32_16x16x32_bf16 v[32:35], v[166:169], v[194:197], v[32:35]
	v_mfma_f32_16x16x32_bf16 v[20:23], v[148:151], v[216:219], v[20:23]
	v_mfma_f32_16x16x32_bf16 v[16:19], v[166:169], v[216:219], v[16:19]
	v_mfma_f32_16x16x32_bf16 v[4:7], v[148:151], v[230:233], v[4:7]
	v_mfma_f32_16x16x32_bf16 v[0:3], v[166:169], v[230:233], v[0:3]
	s_barrier
	s_setprio 0
	s_add_i32 s73, s73, 2
	s_add_u32 s8, s8, 0x100
	s_addc_u32 s9, s9, 0
	s_add_u32 s63, s63, 0x100
	s_addc_u32 s68, s68, 0
	s_cmp_gt_u32 s73, 13
.LBB0_899:
	s_add_u32 s60, s8, 0xfffc0080
	s_addc_u32 s61, s9, -1
	s_add_i32 s76, 0, 0x10000
	s_cmp_eq_u32 s73, 12
	s_cselect_b32 vcc_hi, s22, s61
	s_cselect_b32 vcc_lo, s23, s60
	s_cselect_b32 s61, s51, s68
	s_cselect_b32 s60, s53, s63
	s_add_i32 s92, 0, 0x14000
	v_add_u32_e32 v100, s76, v173
	v_add_u32_e32 v166, s92, v173
	ds_read_b128 v[84:87], v100
	ds_read_b128 v[88:91], v100 offset:1024
	ds_read_b128 v[92:95], v100 offset:2048
	ds_read_b128 v[100:103], v100 offset:3072
	ds_read_b128 v[144:147], v166
	ds_read_b128 v[148:151], v166 offset:1024
	ds_read_b128 v[162:165], v166 offset:2048
	ds_read_b128 v[166:169], v166 offset:3072
	v_lshl_add_u64 v[170:171], s[8:9], 0, v[158:159]
	s_add_i32 m0, s38, 0xc000
	ds_read_b128 v[176:179], v175
	ds_read_b128 v[186:189], v175 offset:1024
	ds_read_b128 v[190:193], v175 offset:2048
	ds_read_b128 v[194:197], v175 offset:3072
	ds_read_b128 v[198:201], v175 offset:4096
	ds_read_b128 v[216:219], v175 offset:5120
	ds_read_b128 v[224:227], v175 offset:6144
	ds_read_b128 v[230:233], v175 offset:7168
	global_load_lds_dwordx4 v[170:171], off
	v_lshl_add_u64 v[170:171], s[8:9], 0, v[160:161]
	s_add_i32 m0, s38, 0xe000
	s_nop 0
	global_load_lds_dwordx4 v[170:171], off
	s_waitcnt vmcnt(8)
	s_waitcnt lgkmcnt(0)
	s_setprio 1
	s_barrier
; #define PG8_STAGE(bufoff, gbase, voff) do { _Pragma("unroll") for (int _i = 0; _i < 2; ++_i) \
;         __builtin_amdgcn_global_load_lds((const unsigned*)((const char*)(gbase) + (voff)[_i]), (PG8_LAS unsigned*)(lds + (bufoff) + ldsw + _i * 8192), 16, 0, 0); } while (0)
; #define PG8_LDA(dst, b, h) do { _Pragma("unroll") for (int m = 0; m < 4; ++m) _Pragma("unroll") for (int k = 0; k < 2; ++k) dst[m][k] = *(const PG8_LAS bf16x8*)(lds + PG8_SA(b, h) + aoff + m * 2048 + k * 1024); } while (0)
; #define PG8_LDB(dst, b, h) do { _Pragma("unroll") for (int n = 0; n < 2; ++n) _Pragma("unroll") for (int k = 0; k < 2; ++k) dst[n][k] = *(const PG8_LAS bf16x8*)(lds + PG8_SB(b, h) + boff + n * 2048 + k * 1024); } while (0)
; #define PG8_MMA(ai, bj, At, Bt) do { __builtin_amdgcn_s_setprio(1); _Pragma("unroll") for (int m = 0; m < 4; ++m) _Pragma("unroll") for (int n = 0; n < 2; ++n) _Pragma("unroll") for (int k = 0; k < 2; ++k) \
;         acc[ai][bj][m][n] = __builtin_amdgcn_mfma_f32_16x16x32_bf16(Bt[n][k], At[m][k], acc[ai][bj][m][n], 0, 0, 0); __builtin_amdgcn_s_setprio(0); } while (0)
; #define PG8_WAIT_V(n) asm volatile("s_waitcnt vmcnt(" #n ")" ::: "memory")
; template <class Epi, class Sched, bool ALIGN_EPI = false, bool SP2 = false>
; __device__ __forceinline__ void gemm_phase(PG8_LAS unsigned char* lds, const Gemm g, const Sched& S, const Epi& E) {
;     ...
;             PG8_LDB(B0, 0, 0); PG8_LDB(B1, 0, 1); PG8_SCHED; PG8_LDA(At, 0, 0); PG8_STAGE(PG8_SA(1, 1), a1 + hstep, voffA);
;             PG8_WAIT_V(8); PG8_WAIT_L(0); PG8_BAR; PG8_MMA(0, 0, At, B0); PG8_MMA(0, 1, At, B1); PG8_BAR; PG8_SCHED;
;             PG8_LDA(At, 0, 1); PG8_STAGE(PG8_SB(0, 0), b2, voffB); PG8_STAGE(PG8_SB(0, 1), b2 + hstep, voffB); PG8_STAGE(PG8_SA(0, 0), a2, voffA);
;             PG8_WAIT_V(8); PG8_WAIT_L(0); PG8_BAR; PG8_MMA(1, 0, At, B0); PG8_MMA(1, 1, At, B1); PG8_BAR; PG8_SCHED;
;             PG8_LDB(B0, 1, 0); PG8_LDB(B1, 1, 1); PG8_SCHED; PG8_LDA(At, 1, 0); PG8_STAGE(PG8_SA(0, 1), a2 + hstep, voffA);
;             PG8_WAIT_V(8); PG8_WAIT_L(0); PG8_BAR; PG8_MMA(0, 0, At, B0); PG8_MMA(0, 1, At, B1); PG8_BAR; PG8_SCHED;
;             PG8_LDA(At, 1, 1); PG8_STAGE(PG8_SB(1, 0), b3, voffB); PG8_STAGE(PG8_SB(1, 1), b3 + hstep, voffB); PG8_STAGE(PG8_SA(1, 0), a3, voffA);
;             PG8_WAIT_V(8); PG8_WAIT_L(0); PG8_BAR; PG8_MMA(1, 0, At, B0); PG8_MMA(1, 1, At, B1); PG8_BAR; PG8_SCHED;
	v_mfma_f32_16x16x32_bf16 v[140:143], v[84:87], v[176:179], v[140:143]
	v_mfma_f32_16x16x32_bf16 v[136:139], v[92:95], v[176:179], v[136:139]
	v_mfma_f32_16x16x32_bf16 v[124:127], v[84:87], v[190:193], v[124:127]
	v_mfma_f32_16x16x32_bf16 v[120:123], v[92:95], v[190:193], v[120:123]
	v_mfma_f32_16x16x32_bf16 v[108:111], v[84:87], v[198:201], v[108:111]
	v_mfma_f32_16x16x32_bf16 v[104:107], v[92:95], v[198:201], v[104:107]
	v_mfma_f32_16x16x32_bf16 v[76:79], v[84:87], v[224:227], v[76:79]
	v_mfma_f32_16x16x32_bf16 v[72:75], v[92:95], v[224:227], v[72:75]
	v_mfma_f32_16x16x32_bf16 v[140:143], v[88:91], v[186:189], v[140:143]
	v_mfma_f32_16x16x32_bf16 v[136:139], v[100:103], v[186:189], v[136:139]
	v_mfma_f32_16x16x32_bf16 v[124:127], v[88:91], v[194:197], v[124:127]
	v_mfma_f32_16x16x32_bf16 v[120:123], v[100:103], v[194:197], v[120:123]
	v_mfma_f32_16x16x32_bf16 v[108:111], v[88:91], v[216:219], v[108:111]
	v_mfma_f32_16x16x32_bf16 v[104:107], v[100:103], v[216:219], v[104:107]
	v_mfma_f32_16x16x32_bf16 v[76:79], v[88:91], v[230:233], v[76:79]
	v_mfma_f32_16x16x32_bf16 v[72:75], v[100:103], v[230:233], v[72:75]
	s_setprio 0
	s_setprio 1
	v_mfma_f32_16x16x32_bf16 v[132:135], v[144:147], v[176:179], v[132:135]
	v_mfma_f32_16x16x32_bf16 v[128:131], v[162:165], v[176:179], v[128:131]
	v_mfma_f32_16x16x32_bf16 v[116:119], v[144:147], v[190:193], v[116:119]
	v_mfma_f32_16x16x32_bf16 v[112:115], v[162:165], v[190:193], v[112:115]
	v_mfma_f32_16x16x32_bf16 v[96:99], v[144:147], v[198:201], v[96:99]
	v_mfma_f32_16x16x32_bf16 v[80:83], v[162:165], v[198:201], v[80:83]
	v_mfma_f32_16x16x32_bf16 v[68:71], v[144:147], v[224:227], v[68:71]
	v_mfma_f32_16x16x32_bf16 v[64:67], v[162:165], v[224:227], v[64:67]
	v_mfma_f32_16x16x32_bf16 v[132:135], v[148:151], v[186:189], v[132:135]
	v_mfma_f32_16x16x32_bf16 v[128:131], v[166:169], v[186:189], v[128:131]
	v_mfma_f32_16x16x32_bf16 v[116:119], v[148:151], v[194:197], v[116:119]
	v_mfma_f32_16x16x32_bf16 v[112:115], v[166:169], v[194:197], v[112:115]
	v_mfma_f32_16x16x32_bf16 v[96:99], v[148:151], v[216:219], v[96:99]
	v_mfma_f32_16x16x32_bf16 v[80:83], v[166:169], v[216:219], v[80:83]
	v_mfma_f32_16x16x32_bf16 v[68:71], v[148:151], v[230:233], v[68:71]
	v_mfma_f32_16x16x32_bf16 v[64:67], v[166:169], v[230:233], v[64:67]
	s_barrier
	s_setprio 0
	s_add_i32 s76, s76, s37
	v_lshl_add_u64 v[170:171], s[60:61], 0, v[180:181]
	s_mov_b32 m0, s76
	ds_read_b128 v[176:179], v175 offset:16384
	ds_read_b128 v[186:189], v175 offset:17408
	ds_read_b128 v[190:193], v175 offset:18432
	ds_read_b128 v[194:197], v175 offset:19456
	ds_read_b128 v[198:201], v175 offset:20480
	ds_read_b128 v[216:219], v175 offset:21504
	ds_read_b128 v[224:227], v175 offset:22528
	ds_read_b128 v[230:233], v175 offset:23552
	global_load_lds_dwordx4 v[170:171], off
	s_add_i32 m0, s76, 0x2000
	s_add_u32 s76, s60, 0x40000
	v_lshl_add_u64 v[202:203], s[60:61], 0, v[152:153]
	s_addc_u32 s77, s61, 0
	s_add_i32 s92, s92, s37
	global_load_lds_dwordx4 v[202:203], off
	v_lshl_add_u64 v[208:209], s[76:77], 0, v[180:181]
	s_mov_b32 m0, s92
	v_lshl_add_u64 v[214:215], vcc, 0, v[154:155]
	global_load_lds_dwordx4 v[208:209], off
	v_lshl_add_u64 v[208:209], s[76:77], 0, v[152:153]
	s_add_i32 m0, s92, 0x2000
	s_nop 0
	global_load_lds_dwordx4 v[208:209], off
	v_lshl_add_u64 v[208:209], vcc, 0, v[156:157]
	s_mov_b32 m0, s38
	s_nop 0
	global_load_lds_dwordx4 v[208:209], off
	s_mov_b32 m0, s39
	s_nop 0
	global_load_lds_dwordx4 v[214:215], off
	s_waitcnt vmcnt(8)
	s_waitcnt lgkmcnt(0)
	s_setprio 1
	s_barrier
	v_mfma_f32_16x16x32_bf16 v[60:63], v[84:87], v[176:179], v[60:63]
	v_mfma_f32_16x16x32_bf16 v[56:59], v[92:95], v[176:179], v[56:59]
	v_mfma_f32_16x16x32_bf16 v[44:47], v[84:87], v[190:193], v[44:47]
	v_mfma_f32_16x16x32_bf16 v[40:43], v[92:95], v[190:193], v[40:43]
	v_mfma_f32_16x16x32_bf16 v[28:31], v[84:87], v[198:201], v[28:31]
	v_mfma_f32_16x16x32_bf16 v[24:27], v[92:95], v[198:201], v[24:27]
	v_mfma_f32_16x16x32_bf16 v[12:15], v[84:87], v[224:227], v[12:15]
	v_mfma_f32_16x16x32_bf16 v[8:11], v[92:95], v[224:227], v[8:11]
	v_mfma_f32_16x16x32_bf16 v[60:63], v[88:91], v[186:189], v[60:63]
	v_mfma_f32_16x16x32_bf16 v[56:59], v[100:103], v[186:189], v[56:59]
	v_mfma_f32_16x16x32_bf16 v[44:47], v[88:91], v[194:197], v[44:47]
	v_mfma_f32_16x16x32_bf16 v[40:43], v[100:103], v[194:197], v[40:43]
	v_mfma_f32_16x16x32_bf16 v[28:31], v[88:91], v[216:219], v[28:31]
	v_mfma_f32_16x16x32_bf16 v[24:27], v[100:103], v[216:219], v[24:27]
	v_mfma_f32_16x16x32_bf16 v[12:15], v[88:91], v[230:233], v[12:15]
	v_mfma_f32_16x16x32_bf16 v[8:11], v[100:103], v[230:233], v[8:11]
	s_setprio 0
	s_setprio 1
	v_mfma_f32_16x16x32_bf16 v[52:55], v[144:147], v[176:179], v[52:55]
	v_mfma_f32_16x16x32_bf16 v[48:51], v[162:165], v[176:179], v[48:51]
	v_mfma_f32_16x16x32_bf16 v[36:39], v[144:147], v[190:193], v[36:39]
	v_mfma_f32_16x16x32_bf16 v[32:35], v[162:165], v[190:193], v[32:35]
	v_mfma_f32_16x16x32_bf16 v[20:23], v[144:147], v[198:201], v[20:23]
	v_mfma_f32_16x16x32_bf16 v[16:19], v[162:165], v[198:201], v[16:19]
	v_mfma_f32_16x16x32_bf16 v[4:7], v[144:147], v[224:227], v[4:7]
	v_mfma_f32_16x16x32_bf16 v[0:3], v[162:165], v[224:227], v[0:3]
	v_mfma_f32_16x16x32_bf16 v[52:55], v[148:151], v[186:189], v[52:55]
	v_mfma_f32_16x16x32_bf16 v[48:51], v[166:169], v[186:189], v[48:51]
	v_mfma_f32_16x16x32_bf16 v[36:39], v[148:151], v[194:197], v[36:39]
	v_mfma_f32_16x16x32_bf16 v[32:35], v[166:169], v[194:197], v[32:35]
	v_mfma_f32_16x16x32_bf16 v[20:23], v[148:151], v[216:219], v[20:23]
	v_mfma_f32_16x16x32_bf16 v[16:19], v[166:169], v[216:219], v[16:19]
	v_mfma_f32_16x16x32_bf16 v[4:7], v[148:151], v[230:233], v[4:7]
	v_mfma_f32_16x16x32_bf16 v[0:3], v[166:169], v[230:233], v[0:3]
	s_barrier
; #define PG8_STAGE(bufoff, gbase, voff) do { _Pragma("unroll") for (int _i = 0; _i < 2; ++_i) \
;         __builtin_amdgcn_global_load_lds((const unsigned*)((const char*)(gbase) + (voff)[_i]), (PG8_LAS unsigned*)(lds + (bufoff) + ldsw + _i * 8192), 16, 0, 0); } while (0)
; #define PG8_LDA(dst, b, h) do { _Pragma("unroll") for (int m = 0; m < 4; ++m) _Pragma("unroll") for (int k = 0; k < 2; ++k) dst[m][k] = *(const PG8_LAS bf16x8*)(lds + PG8_SA(b, h) + aoff + m * 2048 + k * 1024); } while (0)
; #define PG8_LDB(dst, b, h) do { _Pragma("unroll") for (int n = 0; n < 2; ++n) _Pragma("unroll") for (int k = 0; k < 2; ++k) dst[n][k] = *(const PG8_LAS bf16x8*)(lds + PG8_SB(b, h) + boff + n * 2048 + k * 1024); } while (0)
; #define PG8_MMA(ai, bj, At, Bt) do { __builtin_amdgcn_s_setprio(1); _Pragma("unroll") for (int m = 0; m < 4; ++m) _Pragma("unroll") for (int n = 0; n < 2; ++n) _Pragma("unroll") for (int k = 0; k < 2; ++k) \
;         acc[ai][bj][m][n] = __builtin_amdgcn_mfma_f32_16x16x32_bf16(Bt[n][k], At[m][k], acc[ai][bj][m][n], 0, 0, 0); __builtin_amdgcn_s_setprio(0); } while (0)
; #define PG8_WAIT_V(n) asm volatile("s_waitcnt vmcnt(" #n ")" ::: "memory")
; template <class Epi, class Sched, bool ALIGN_EPI = false, bool SP2 = false>
; __device__ __forceinline__ void gemm_phase(PG8_LAS unsigned char* lds, const Gemm g, const Sched& S, const Epi& E) {
;     ...
;             PG8_LDB(B0, 0, 0); PG8_LDB(B1, 0, 1); PG8_SCHED; PG8_LDA(At, 0, 0); PG8_STAGE(PG8_SA(1, 1), a1 + hstep, voffA);
;             PG8_WAIT_V(8); PG8_WAIT_L(0); PG8_BAR; PG8_MMA(0, 0, At, B0); PG8_MMA(0, 1, At, B1); PG8_BAR; PG8_SCHED;
;             PG8_LDA(At, 0, 1); PG8_STAGE(PG8_SB(0, 0), b2, voffB); PG8_STAGE(PG8_SB(0, 1), b2 + hstep, voffB); PG8_STAGE(PG8_SA(0, 0), a2, voffA);
;             PG8_WAIT_V(8); PG8_WAIT_L(0); PG8_BAR; PG8_MMA(1, 0, At, B0); PG8_MMA(1, 1, At, B1); PG8_BAR; PG8_SCHED;
;             PG8_LDB(B0, 1, 0); PG8_LDB(B1, 1, 1); PG8_SCHED; PG8_LDA(At, 1, 0); PG8_STAGE(PG8_SA(0, 1), a2 + hstep, voffA);
;             PG8_WAIT_V(8); PG8_WAIT_L(0); PG8_BAR; PG8_MMA(0, 0, At, B0); PG8_MMA(0, 1, At, B1); PG8_BAR; PG8_SCHED;
;             PG8_LDA(At, 1, 1); PG8_STAGE(PG8_SB(1, 0), b3, voffB); PG8_STAGE(PG8_SB(1, 1), b3 + hstep, voffB); PG8_STAGE(PG8_SA(1, 0), a3, voffA);
;             PG8_WAIT_V(8); PG8_WAIT_L(0); PG8_BAR; PG8_MMA(1, 0, At, B0); PG8_MMA(1, 1, At, B1); PG8_BAR; PG8_SCHED;
	s_setprio 0
	s_add_i32 s92, 0, 0x18000
	s_add_i32 s93, 0, 0x1c000
	v_add_u32_e32 v100, s92, v173
	v_add_u32_e32 v166, s93, v173
	ds_read_b128 v[84:87], v100
	ds_read_b128 v[88:91], v100 offset:1024
	ds_read_b128 v[92:95], v100 offset:2048
	ds_read_b128 v[100:103], v100 offset:3072
	ds_read_b128 v[144:147], v166
	ds_read_b128 v[148:151], v166 offset:1024
	ds_read_b128 v[162:165], v166 offset:2048
	ds_read_b128 v[166:169], v166 offset:3072
	s_add_u32 s76, vcc_lo, 0x40000
	s_addc_u32 s77, vcc_hi, 0
	s_mov_b32 m0, s46
	v_lshl_add_u64 v[220:221], s[76:77], 0, v[156:157]
	ds_read_b128 v[176:179], v175 offset:32768
	ds_read_b128 v[186:189], v175 offset:33792
	ds_read_b128 v[190:193], v175 offset:34816
	ds_read_b128 v[194:197], v175 offset:35840
	ds_read_b128 v[198:201], v175 offset:36864
	ds_read_b128 v[216:219], v175 offset:37888
	ds_read_b128 v[224:227], v175 offset:38912
	ds_read_b128 v[230:233], v175 offset:39936
	global_load_lds_dwordx4 v[220:221], off
	v_lshl_add_u64 v[220:221], s[76:77], 0, v[154:155]
	s_mov_b32 m0, s47
	s_nop 0
	global_load_lds_dwordx4 v[220:221], off
	s_waitcnt vmcnt(8)
	s_waitcnt lgkmcnt(0)
	s_setprio 1
	s_barrier
	v_mfma_f32_16x16x32_bf16 v[140:143], v[84:87], v[176:179], v[140:143]
	v_mfma_f32_16x16x32_bf16 v[136:139], v[92:95], v[176:179], v[136:139]
	v_mfma_f32_16x16x32_bf16 v[124:127], v[84:87], v[190:193], v[124:127]
	v_mfma_f32_16x16x32_bf16 v[120:123], v[92:95], v[190:193], v[120:123]
	v_mfma_f32_16x16x32_bf16 v[108:111], v[84:87], v[198:201], v[108:111]
	v_mfma_f32_16x16x32_bf16 v[104:107], v[92:95], v[198:201], v[104:107]
	v_mfma_f32_16x16x32_bf16 v[76:79], v[84:87], v[224:227], v[76:79]
	v_mfma_f32_16x16x32_bf16 v[72:75], v[92:95], v[224:227], v[72:75]
	v_mfma_f32_16x16x32_bf16 v[140:143], v[88:91], v[186:189], v[140:143]
	v_mfma_f32_16x16x32_bf16 v[136:139], v[100:103], v[186:189], v[136:139]
	v_mfma_f32_16x16x32_bf16 v[124:127], v[88:91], v[194:197], v[124:127]
	v_mfma_f32_16x16x32_bf16 v[120:123], v[100:103], v[194:197], v[120:123]
	v_mfma_f32_16x16x32_bf16 v[108:111], v[88:91], v[216:219], v[108:111]
	v_mfma_f32_16x16x32_bf16 v[104:107], v[100:103], v[216:219], v[104:107]
	v_mfma_f32_16x16x32_bf16 v[76:79], v[88:91], v[230:233], v[76:79]
	v_mfma_f32_16x16x32_bf16 v[72:75], v[100:103], v[230:233], v[72:75]
	s_setprio 0
	s_setprio 1
	v_mfma_f32_16x16x32_bf16 v[132:135], v[144:147], v[176:179], v[132:135]
	v_mfma_f32_16x16x32_bf16 v[128:131], v[162:165], v[176:179], v[128:131]
	v_mfma_f32_16x16x32_bf16 v[116:119], v[144:147], v[190:193], v[116:119]
	v_mfma_f32_16x16x32_bf16 v[112:115], v[162:165], v[190:193], v[112:115]
	v_mfma_f32_16x16x32_bf16 v[96:99], v[144:147], v[198:201], v[96:99]
	v_mfma_f32_16x16x32_bf16 v[80:83], v[162:165], v[198:201], v[80:83]
	v_mfma_f32_16x16x32_bf16 v[68:71], v[144:147], v[224:227], v[68:71]
	v_mfma_f32_16x16x32_bf16 v[64:67], v[162:165], v[224:227], v[64:67]
	v_mfma_f32_16x16x32_bf16 v[132:135], v[148:151], v[186:189], v[132:135]
	v_mfma_f32_16x16x32_bf16 v[128:131], v[166:169], v[186:189], v[128:131]
	v_mfma_f32_16x16x32_bf16 v[116:119], v[148:151], v[194:197], v[116:119]
	v_mfma_f32_16x16x32_bf16 v[112:115], v[166:169], v[194:197], v[112:115]
	v_mfma_f32_16x16x32_bf16 v[96:99], v[148:151], v[216:219], v[96:99]
	v_mfma_f32_16x16x32_bf16 v[80:83], v[166:169], v[216:219], v[80:83]
	v_mfma_f32_16x16x32_bf16 v[68:71], v[148:151], v[230:233], v[68:71]
	v_mfma_f32_16x16x32_bf16 v[64:67], v[166:169], v[230:233], v[64:67]
	s_barrier
; #define PG8_STAGE(bufoff, gbase, voff) do { _Pragma("unroll") for (int _i = 0; _i < 2; ++_i) \
;         __builtin_amdgcn_global_load_lds((const unsigned*)((const char*)(gbase) + (voff)[_i]), (PG8_LAS unsigned*)(lds + (bufoff) + ldsw + _i * 8192), 16, 0, 0); } while (0)
; #define PG8_LDA(dst, b, h) do { _Pragma("unroll") for (int m = 0; m < 4; ++m) _Pragma("unroll") for (int k = 0; k < 2; ++k) dst[m][k] = *(const PG8_LAS bf16x8*)(lds + PG8_SA(b, h) + aoff + m * 2048 + k * 1024); } while (0)
; #define PG8_LDB(dst, b, h) do { _Pragma("unroll") for (int n = 0; n < 2; ++n) _Pragma("unroll") for (int k = 0; k < 2; ++k) dst[n][k] = *(const PG8_LAS bf16x8*)(lds + PG8_SB(b, h) + boff + n * 2048 + k * 1024); } while (0)
; #define PG8_MMA(ai, bj, At, Bt) do { __builtin_amdgcn_s_setprio(1); _Pragma("unroll") for (int m = 0; m < 4; ++m) _Pragma("unroll") for (int n = 0; n < 2; ++n) _Pragma("unroll") for (int k = 0; k < 2; ++k) \
;         acc[ai][bj][m][n] = __builtin_amdgcn_mfma_f32_16x16x32_bf16(Bt[n][k], At[m][k], acc[ai][bj][m][n], 0, 0, 0); __builtin_amdgcn_s_setprio(0); } while (0)
; template <class Epi, class Sched, bool ALIGN_EPI = false, bool SP2 = false>
; __device__ __forceinline__ void gemm_phase(PG8_LAS unsigned char* lds, const Gemm g, const Sched& S, const Epi& E) {
;     ...
;             PG8_LDB(B0, 0, 0); PG8_LDB(B1, 0, 1); PG8_SCHED; PG8_LDA(At, 0, 0); PG8_STAGE(PG8_SA(1, 1), a1 + hstep, voffA);
;             PG8_WAIT_V(8); PG8_WAIT_L(0); PG8_BAR; PG8_MMA(0, 0, At, B0); PG8_MMA(0, 1, At, B1); PG8_BAR; PG8_SCHED;
;             PG8_LDA(At, 0, 1); PG8_STAGE(PG8_SB(0, 0), b2, voffB); PG8_STAGE(PG8_SB(0, 1), b2 + hstep, voffB); PG8_STAGE(PG8_SA(0, 0), a2, voffA);
;             PG8_WAIT_V(8); PG8_WAIT_L(0); PG8_BAR; PG8_MMA(1, 0, At, B0); PG8_MMA(1, 1, At, B1); PG8_BAR; PG8_SCHED;
;             PG8_LDB(B0, 1, 0); PG8_LDB(B1, 1, 1); PG8_SCHED; PG8_LDA(At, 1, 0); PG8_STAGE(PG8_SA(0, 1), a2 + hstep, voffA);
;             PG8_WAIT_V(8); PG8_WAIT_L(0); PG8_BAR; PG8_MMA(0, 0, At, B0); PG8_MMA(0, 1, At, B1); PG8_BAR; PG8_SCHED;
;             PG8_LDA(At, 1, 1); PG8_STAGE(PG8_SB(1, 0), b3, voffB); PG8_STAGE(PG8_SB(1, 1), b3 + hstep, voffB); PG8_STAGE(PG8_SA(1, 0), a3, voffA);
;             PG8_WAIT_V(8); PG8_WAIT_L(0); PG8_BAR; PG8_MMA(1, 0, At, B0); PG8_MMA(1, 1, At, B1); PG8_BAR; PG8_SCHED;
;     ...
;         if constexpr (ALIGN_EPI) { if (wr == 0) PG8_BAR; }
	s_setprio 0
	s_add_i32 s76, s92, s37
	v_lshl_add_u64 v[170:171], v[170:171], 0, s[70:71]
	s_mov_b32 m0, s76
	ds_read_b128 v[176:179], v175 offset:49152
	ds_read_b128 v[186:189], v175 offset:50176
	ds_read_b128 v[190:193], v175 offset:51200
	ds_read_b128 v[194:197], v175 offset:52224
	ds_read_b128 v[198:201], v175 offset:53248
	ds_read_b128 v[216:219], v175 offset:54272
	ds_read_b128 v[224:227], v175 offset:55296
	ds_read_b128 v[230:233], v175 offset:56320
	global_load_lds_dwordx4 v[170:171], off
	s_add_i32 m0, s76, 0x2000
	s_add_u32 s60, s60, 0x40080
	v_lshl_add_u64 v[170:171], v[202:203], 0, s[70:71]
	s_addc_u32 s61, s61, 0
	s_add_i32 s76, s93, s37
	global_load_lds_dwordx4 v[170:171], off
	v_lshl_add_u64 v[170:171], s[60:61], 0, v[180:181]
	s_mov_b32 m0, s76
	s_nop 0
	global_load_lds_dwordx4 v[170:171], off
	v_lshl_add_u64 v[170:171], s[60:61], 0, v[152:153]
	s_add_i32 m0, s76, 0x2000
	s_nop 0
	global_load_lds_dwordx4 v[170:171], off
	v_lshl_add_u64 v[170:171], v[208:209], 0, s[70:71]
	s_mov_b32 m0, s57
	s_nop 0
	global_load_lds_dwordx4 v[170:171], off
	v_lshl_add_u64 v[170:171], v[214:215], 0, s[70:71]
	s_mov_b32 m0, s58
	s_nop 0
	global_load_lds_dwordx4 v[170:171], off
	s_waitcnt vmcnt(8)
	s_waitcnt lgkmcnt(0)
	s_setprio 1
	s_barrier
	v_mfma_f32_16x16x32_bf16 v[60:63], v[84:87], v[176:179], v[60:63]
	v_mfma_f32_16x16x32_bf16 v[56:59], v[92:95], v[176:179], v[56:59]
	v_mfma_f32_16x16x32_bf16 v[44:47], v[84:87], v[190:193], v[44:47]
	v_mfma_f32_16x16x32_bf16 v[40:43], v[92:95], v[190:193], v[40:43]
	v_mfma_f32_16x16x32_bf16 v[28:31], v[84:87], v[198:201], v[28:31]
	v_mfma_f32_16x16x32_bf16 v[24:27], v[92:95], v[198:201], v[24:27]
	v_mfma_f32_16x16x32_bf16 v[12:15], v[84:87], v[224:227], v[12:15]
	v_mfma_f32_16x16x32_bf16 v[8:11], v[92:95], v[224:227], v[8:11]
	v_mfma_f32_16x16x32_bf16 v[60:63], v[88:91], v[186:189], v[60:63]
	v_mfma_f32_16x16x32_bf16 v[56:59], v[100:103], v[186:189], v[56:59]
	v_mfma_f32_16x16x32_bf16 v[44:47], v[88:91], v[194:197], v[44:47]
	v_mfma_f32_16x16x32_bf16 v[40:43], v[100:103], v[194:197], v[40:43]
	v_mfma_f32_16x16x32_bf16 v[28:31], v[88:91], v[216:219], v[28:31]
	v_mfma_f32_16x16x32_bf16 v[24:27], v[100:103], v[216:219], v[24:27]
	v_mfma_f32_16x16x32_bf16 v[12:15], v[88:91], v[230:233], v[12:15]
	v_mfma_f32_16x16x32_bf16 v[8:11], v[100:103], v[230:233], v[8:11]
	s_setprio 0
	s_setprio 1
	v_mfma_f32_16x16x32_bf16 v[52:55], v[144:147], v[176:179], v[52:55]
	v_mfma_f32_16x16x32_bf16 v[48:51], v[162:165], v[176:179], v[48:51]
	v_mfma_f32_16x16x32_bf16 v[36:39], v[144:147], v[190:193], v[36:39]
	v_mfma_f32_16x16x32_bf16 v[32:35], v[162:165], v[190:193], v[32:35]
	v_mfma_f32_16x16x32_bf16 v[20:23], v[144:147], v[198:201], v[20:23]
	v_mfma_f32_16x16x32_bf16 v[16:19], v[162:165], v[198:201], v[16:19]
	v_mfma_f32_16x16x32_bf16 v[4:7], v[144:147], v[224:227], v[4:7]
	v_mfma_f32_16x16x32_bf16 v[0:3], v[162:165], v[224:227], v[0:3]
	v_mfma_f32_16x16x32_bf16 v[52:55], v[148:151], v[186:189], v[52:55]
	v_mfma_f32_16x16x32_bf16 v[48:51], v[166:169], v[186:189], v[48:51]
	v_mfma_f32_16x16x32_bf16 v[36:39], v[148:151], v[194:197], v[36:39]
	v_mfma_f32_16x16x32_bf16 v[32:35], v[166:169], v[194:197], v[32:35]
	v_mfma_f32_16x16x32_bf16 v[20:23], v[148:151], v[216:219], v[20:23]
	v_mfma_f32_16x16x32_bf16 v[16:19], v[166:169], v[216:219], v[16:19]
	v_mfma_f32_16x16x32_bf16 v[4:7], v[148:151], v[230:233], v[4:7]
	v_mfma_f32_16x16x32_bf16 v[0:3], v[166:169], v[230:233], v[0:3]
	s_barrier
	s_setprio 0
	s_add_i32 s73, s73, 2
	s_add_u32 s8, s8, 0x100
	s_addc_u32 s9, s9, 0
	s_add_u32 s63, s63, 0x100
	s_addc_u32 s68, s68, 0
	s_cmp_gt_u32 s73, 13
	s_cbranch_scc0 .LBB0_899
	s_and_b64 vcc, exec, s[42:43]
	s_cbranch_vccz .LBB0_902
	s_barrier
